# v12 + GEMM MFMA segments: the two k-steps of each accumulator issued back to back (SrcC forwarding order)
# speedup vs baseline: 1.0083x; 1.0083x over previous
; #define PG8_STAGE(bufoff, gbase, voff) do { _Pragma("unroll") for (int _i = 0; _i < 2; ++_i) \
;         __builtin_amdgcn_global_load_lds((const unsigned*)((const char*)(gbase) + (voff)[_i]), (LAS unsigned*)(lds + (bufoff) + ldsw + _i * 8192), 16, 0, 0); } while (0)
; #define PG8_LDA(dst, b, h) do { _Pragma("unroll") for (int m = 0; m < 4; ++m) _Pragma("unroll") for (int k = 0; k < 2; ++k) dst[m][k] = *(const LAS bf16x8*)(lds + PG8_SA(b, h) + aoff + m * 2048 + k * 1024); } while (0)
; #define PG8_LDB(dst, b, h) do { _Pragma("unroll") for (int n = 0; n < 2; ++n) _Pragma("unroll") for (int k = 0; k < 2; ++k) dst[n][k] = *(const LAS bf16x8*)(lds + PG8_SB(b, h) + boff + n * 2048 + k * 1024); } while (0)
; #define PG8_MMA(ai, bj, At, Bt) do { __builtin_amdgcn_s_setprio(1); _Pragma("unroll") for (int m = 0; m < 4; ++m) _Pragma("unroll") for (int n = 0; n < 2; ++n) _Pragma("unroll") for (int k = 0; k < 2; ++k) \
;         acc[ai][bj][m][n] = __builtin_amdgcn_mfma_f32_16x16x32_bf16(Bt[n][k], At[m][k], acc[ai][bj][m][n], 0, 0, 0); __builtin_amdgcn_s_setprio(0); } while (0)
; #define PG8_WAIT_V(n) asm volatile("s_waitcnt vmcnt(" #n ")" ::: "memory")
; #define PG8_WAIT_L(n) asm volatile("s_waitcnt lgkmcnt(" #n ")" ::: "memory")
; #define PG8_BAR __builtin_amdgcn_s_barrier()
; #define PG8_SCHED __builtin_amdgcn_sched_barrier(0)
; template <class Epi, class Sched, int LDA, int LDB, bool ALIGN_EPI = true>
; __device__ __forceinline__ void gemm_phase(LAS unsigned char* lds, const Gemm g, const Sched& S, const Epi& E, int wave) {
;     ...
;             PG8_LDB(B0, 0, 0); PG8_LDB(B1, 0, 1); PG8_SCHED; PG8_LDA(At, 0, 0); PG8_STAGE(PG8_SA(1, 1), a1 + hstepA, voffA);
;             PG8_WAIT_V(8); PG8_WAIT_L(0); PG8_BAR; PG8_MMA(0, 0, At, B0); PG8_MMA(0, 1, At, B1); PG8_BAR; PG8_SCHED;
;             PG8_LDA(At, 0, 1); PG8_STAGE(PG8_SB(0, 0), b2, voffB); PG8_STAGE(PG8_SB(0, 1), b2 + hstepB, voffB); PG8_STAGE(PG8_SA(0, 0), a2, voffA);
;             PG8_WAIT_V(8); PG8_WAIT_L(0); PG8_BAR; PG8_MMA(1, 0, At, B0); PG8_MMA(1, 1, At, B1); PG8_BAR; PG8_SCHED;
.LBB0_485:
	s_add_u32 s24, s18, 0x100
	s_addc_u32 s25, s19, 0
	s_add_i32 s54, 0, 0x10000
	s_cmp_eq_u32 s53, 28
	s_cselect_b32 s35, s3, s25
	s_cselect_b32 s34, s2, s24
	v_add_u32_e32 v140, s54, v143
	s_cselect_b32 s29, s1, s45
	s_cselect_b32 s28, s17, s44
	s_add_i32 s55, 0, 0x14000
	ds_read_b128 v[146:149], v140
	ds_read_b128 v[150:153], v140 offset:1024
	ds_read_b128 v[154:157], v140 offset:2048
	ds_read_b128 v[158:161], v140 offset:3072
	v_add_u32_e32 v140, s55, v143
	ds_read_b128 v[162:165], v140
	ds_read_b128 v[166:169], v140 offset:1024
	ds_read_b128 v[170:173], v140 offset:2048
	ds_read_b128 v[180:183], v140 offset:3072
	v_lshl_add_u64 v[140:141], s[18:19], 0, v[136:137]
	s_add_i32 m0, s38, 0xc000
	ds_read_b128 v[184:187], v145
	ds_read_b128 v[188:191], v145 offset:1024
	ds_read_b128 v[192:195], v145 offset:2048
	ds_read_b128 v[196:199], v145 offset:3072
	ds_read_b128 v[200:203], v145 offset:4096
	ds_read_b128 v[204:207], v145 offset:5120
	ds_read_b128 v[208:211], v145 offset:6144
	ds_read_b128 v[212:215], v145 offset:7168
	global_load_lds_dwordx4 v[140:141], off
	v_lshl_add_u64 v[140:141], s[18:19], 0, v[138:139]
	s_add_i32 m0, s38, 0xe000
	s_nop 0
	global_load_lds_dwordx4 v[140:141], off
	s_waitcnt vmcnt(8)
	s_waitcnt lgkmcnt(0)
	s_setprio 1
	s_barrier
	v_mfma_f32_16x16x32_bf16 v[126:129], v[146:149], v[184:187], v[126:129]
	v_mfma_f32_16x16x32_bf16 v[126:129], v[150:153], v[188:191], v[126:129]
	v_mfma_f32_16x16x32_bf16 v[118:121], v[154:157], v[184:187], v[118:121]
	v_mfma_f32_16x16x32_bf16 v[118:121], v[158:161], v[188:191], v[118:121]
	v_mfma_f32_16x16x32_bf16 v[110:113], v[146:149], v[192:195], v[110:113]
	v_mfma_f32_16x16x32_bf16 v[110:113], v[150:153], v[196:199], v[110:113]
	v_mfma_f32_16x16x32_bf16 v[102:105], v[154:157], v[192:195], v[102:105]
	v_mfma_f32_16x16x32_bf16 v[102:105], v[158:161], v[196:199], v[102:105]
	v_mfma_f32_16x16x32_bf16 v[94:97], v[146:149], v[200:203], v[94:97]
	v_mfma_f32_16x16x32_bf16 v[94:97], v[150:153], v[204:207], v[94:97]
	v_mfma_f32_16x16x32_bf16 v[86:89], v[154:157], v[200:203], v[86:89]
	v_mfma_f32_16x16x32_bf16 v[86:89], v[158:161], v[204:207], v[86:89]
	v_mfma_f32_16x16x32_bf16 v[78:81], v[146:149], v[208:211], v[78:81]
	v_mfma_f32_16x16x32_bf16 v[78:81], v[150:153], v[212:215], v[78:81]
	v_mfma_f32_16x16x32_bf16 v[70:73], v[154:157], v[208:211], v[70:73]
	v_mfma_f32_16x16x32_bf16 v[70:73], v[158:161], v[212:215], v[70:73]
	v_mfma_f32_16x16x32_bf16 v[122:125], v[162:165], v[184:187], v[122:125]
	v_mfma_f32_16x16x32_bf16 v[122:125], v[166:169], v[188:191], v[122:125]
	v_mfma_f32_16x16x32_bf16 v[114:117], v[170:173], v[184:187], v[114:117]
	v_mfma_f32_16x16x32_bf16 v[114:117], v[180:183], v[188:191], v[114:117]
	v_mfma_f32_16x16x32_bf16 v[106:109], v[162:165], v[192:195], v[106:109]
	v_mfma_f32_16x16x32_bf16 v[106:109], v[166:169], v[196:199], v[106:109]
	v_mfma_f32_16x16x32_bf16 v[98:101], v[170:173], v[192:195], v[98:101]
	v_mfma_f32_16x16x32_bf16 v[98:101], v[180:183], v[196:199], v[98:101]
	v_mfma_f32_16x16x32_bf16 v[90:93], v[162:165], v[200:203], v[90:93]
	v_mfma_f32_16x16x32_bf16 v[90:93], v[166:169], v[204:207], v[90:93]
	v_mfma_f32_16x16x32_bf16 v[82:85], v[170:173], v[200:203], v[82:85]
	v_mfma_f32_16x16x32_bf16 v[82:85], v[180:183], v[204:207], v[82:85]
	v_mfma_f32_16x16x32_bf16 v[74:77], v[162:165], v[208:211], v[74:77]
	v_mfma_f32_16x16x32_bf16 v[74:77], v[166:169], v[212:215], v[74:77]
	v_mfma_f32_16x16x32_bf16 v[66:69], v[170:173], v[208:211], v[66:69]
	v_mfma_f32_16x16x32_bf16 v[66:69], v[180:183], v[212:215], v[66:69]
	s_barrier
	s_setprio 0
	s_add_i32 s18, s54, s5
	v_lshl_add_u64 v[140:141], s[28:29], 0, v[0:1]
	s_mov_b32 m0, s18
	ds_read_b128 v[184:187], v145 offset:16384
	ds_read_b128 v[188:191], v145 offset:17408
	ds_read_b128 v[192:195], v145 offset:18432
	ds_read_b128 v[196:199], v145 offset:19456
	ds_read_b128 v[200:203], v145 offset:20480
	ds_read_b128 v[204:207], v145 offset:21504
	ds_read_b128 v[208:211], v145 offset:22528
	ds_read_b128 v[212:215], v145 offset:23552
	global_load_lds_dwordx4 v[140:141], off
	s_add_i32 m0, s18, 0x2000
	s_add_u32 s18, s28, 0x80000
	v_lshl_add_u64 v[174:175], s[28:29], 0, v[130:131]
	s_addc_u32 s19, s29, 0
	s_add_i32 s54, s55, s5
	global_load_lds_dwordx4 v[174:175], off
	v_lshl_add_u64 v[216:217], s[18:19], 0, v[0:1]
	s_mov_b32 m0, s54
	v_lshl_add_u64 v[218:219], s[34:35], 0, v[132:133]
	global_load_lds_dwordx4 v[216:217], off
	v_lshl_add_u64 v[216:217], s[18:19], 0, v[130:131]
	s_add_i32 m0, s54, 0x2000
	s_nop 0
	global_load_lds_dwordx4 v[216:217], off
	v_lshl_add_u64 v[216:217], s[34:35], 0, v[134:135]
	s_mov_b32 m0, s38
	s_nop 0
	global_load_lds_dwordx4 v[216:217], off
	s_mov_b32 m0, s39
	s_nop 0
	global_load_lds_dwordx4 v[218:219], off
	s_waitcnt vmcnt(8)
	s_waitcnt lgkmcnt(0)
	s_setprio 1
	s_barrier
; #define PG8_STAGE(bufoff, gbase, voff) do { _Pragma("unroll") for (int _i = 0; _i < 2; ++_i) \
;         __builtin_amdgcn_global_load_lds((const unsigned*)((const char*)(gbase) + (voff)[_i]), (LAS unsigned*)(lds + (bufoff) + ldsw + _i * 8192), 16, 0, 0); } while (0)
; #define PG8_LDA(dst, b, h) do { _Pragma("unroll") for (int m = 0; m < 4; ++m) _Pragma("unroll") for (int k = 0; k < 2; ++k) dst[m][k] = *(const LAS bf16x8*)(lds + PG8_SA(b, h) + aoff + m * 2048 + k * 1024); } while (0)
; #define PG8_LDB(dst, b, h) do { _Pragma("unroll") for (int n = 0; n < 2; ++n) _Pragma("unroll") for (int k = 0; k < 2; ++k) dst[n][k] = *(const LAS bf16x8*)(lds + PG8_SB(b, h) + boff + n * 2048 + k * 1024); } while (0)
; #define PG8_MMA(ai, bj, At, Bt) do { __builtin_amdgcn_s_setprio(1); _Pragma("unroll") for (int m = 0; m < 4; ++m) _Pragma("unroll") for (int n = 0; n < 2; ++n) _Pragma("unroll") for (int k = 0; k < 2; ++k) \
;         acc[ai][bj][m][n] = __builtin_amdgcn_mfma_f32_16x16x32_bf16(Bt[n][k], At[m][k], acc[ai][bj][m][n], 0, 0, 0); __builtin_amdgcn_s_setprio(0); } while (0)
; #define PG8_WAIT_V(n) asm volatile("s_waitcnt vmcnt(" #n ")" ::: "memory")
; #define PG8_WAIT_L(n) asm volatile("s_waitcnt lgkmcnt(" #n ")" ::: "memory")
; #define PG8_BAR __builtin_amdgcn_s_barrier()
; #define PG8_SCHED __builtin_amdgcn_sched_barrier(0)
; template <class Epi, class Sched, int LDA, int LDB, bool ALIGN_EPI = true>
; __device__ __forceinline__ void gemm_phase(LAS unsigned char* lds, const Gemm g, const Sched& S, const Epi& E, int wave) {
;     ...
;             PG8_WAIT_V(8); PG8_WAIT_L(0); PG8_BAR; PG8_MMA(1, 0, At, B0); PG8_MMA(1, 1, At, B1); PG8_BAR; PG8_SCHED;
;             PG8_LDB(B0, 1, 0); PG8_LDB(B1, 1, 1); PG8_SCHED; PG8_LDA(At, 1, 0); PG8_STAGE(PG8_SA(0, 1), a2 + hstepA, voffA);
;             PG8_WAIT_V(8); PG8_WAIT_L(0); PG8_BAR; PG8_MMA(0, 0, At, B0); PG8_MMA(0, 1, At, B1); PG8_BAR; PG8_SCHED;
	v_mfma_f32_16x16x32_bf16 v[62:65], v[146:149], v[184:187], v[62:65]
	v_mfma_f32_16x16x32_bf16 v[62:65], v[150:153], v[188:191], v[62:65]
	v_mfma_f32_16x16x32_bf16 v[54:57], v[154:157], v[184:187], v[54:57]
	v_mfma_f32_16x16x32_bf16 v[54:57], v[158:161], v[188:191], v[54:57]
	v_mfma_f32_16x16x32_bf16 v[46:49], v[146:149], v[192:195], v[46:49]
	v_mfma_f32_16x16x32_bf16 v[46:49], v[150:153], v[196:199], v[46:49]
	v_mfma_f32_16x16x32_bf16 v[38:41], v[154:157], v[192:195], v[38:41]
	v_mfma_f32_16x16x32_bf16 v[38:41], v[158:161], v[196:199], v[38:41]
	v_mfma_f32_16x16x32_bf16 v[30:33], v[146:149], v[200:203], v[30:33]
	v_mfma_f32_16x16x32_bf16 v[30:33], v[150:153], v[204:207], v[30:33]
	v_mfma_f32_16x16x32_bf16 v[22:25], v[154:157], v[200:203], v[22:25]
	v_mfma_f32_16x16x32_bf16 v[22:25], v[158:161], v[204:207], v[22:25]
	v_mfma_f32_16x16x32_bf16 v[14:17], v[146:149], v[208:211], v[14:17]
	v_mfma_f32_16x16x32_bf16 v[14:17], v[150:153], v[212:215], v[14:17]
	v_mfma_f32_16x16x32_bf16 v[6:9], v[154:157], v[208:211], v[6:9]
	v_mfma_f32_16x16x32_bf16 v[6:9], v[158:161], v[212:215], v[6:9]
	v_mfma_f32_16x16x32_bf16 v[58:61], v[162:165], v[184:187], v[58:61]
	v_mfma_f32_16x16x32_bf16 v[58:61], v[166:169], v[188:191], v[58:61]
	v_mfma_f32_16x16x32_bf16 v[50:53], v[170:173], v[184:187], v[50:53]
	v_mfma_f32_16x16x32_bf16 v[50:53], v[180:183], v[188:191], v[50:53]
	v_mfma_f32_16x16x32_bf16 v[42:45], v[162:165], v[192:195], v[42:45]
	v_mfma_f32_16x16x32_bf16 v[42:45], v[166:169], v[196:199], v[42:45]
	v_mfma_f32_16x16x32_bf16 v[34:37], v[170:173], v[192:195], v[34:37]
	v_mfma_f32_16x16x32_bf16 v[34:37], v[180:183], v[196:199], v[34:37]
	v_mfma_f32_16x16x32_bf16 v[26:29], v[162:165], v[200:203], v[26:29]
	v_mfma_f32_16x16x32_bf16 v[26:29], v[166:169], v[204:207], v[26:29]
	v_mfma_f32_16x16x32_bf16 v[18:21], v[170:173], v[200:203], v[18:21]
	v_mfma_f32_16x16x32_bf16 v[18:21], v[180:183], v[204:207], v[18:21]
	v_mfma_f32_16x16x32_bf16 v[10:13], v[162:165], v[208:211], v[10:13]
	v_mfma_f32_16x16x32_bf16 v[10:13], v[166:169], v[212:215], v[10:13]
	v_mfma_f32_16x16x32_bf16 v[2:5], v[170:173], v[208:211], v[2:5]
	v_mfma_f32_16x16x32_bf16 v[2:5], v[180:183], v[212:215], v[2:5]
	s_barrier
	s_setprio 0
	s_add_i32 s54, 0, 0x18000
	s_add_i32 s55, 0, 0x1c000
	v_add_u32_e32 v158, s54, v143
	v_add_u32_e32 v180, s55, v143
	ds_read_b128 v[146:149], v158
	ds_read_b128 v[150:153], v158 offset:1024
	ds_read_b128 v[154:157], v158 offset:2048
	ds_read_b128 v[158:161], v158 offset:3072
	ds_read_b128 v[162:165], v180
	ds_read_b128 v[166:169], v180 offset:1024
	ds_read_b128 v[170:173], v180 offset:2048
	ds_read_b128 v[180:183], v180 offset:3072
	s_add_u32 s18, s34, 0x84000
	s_addc_u32 s19, s35, 0
	s_mov_b32 m0, s46
	v_lshl_add_u64 v[220:221], s[18:19], 0, v[134:135]
	ds_read_b128 v[184:187], v145 offset:32768
	ds_read_b128 v[188:191], v145 offset:33792
	ds_read_b128 v[192:195], v145 offset:34816
	ds_read_b128 v[196:199], v145 offset:35840
	ds_read_b128 v[200:203], v145 offset:36864
	ds_read_b128 v[204:207], v145 offset:37888
	ds_read_b128 v[208:211], v145 offset:38912
	ds_read_b128 v[212:215], v145 offset:39936
	global_load_lds_dwordx4 v[220:221], off
	v_lshl_add_u64 v[220:221], s[18:19], 0, v[132:133]
	s_mov_b32 m0, s47
	s_nop 0
	global_load_lds_dwordx4 v[220:221], off
	s_waitcnt vmcnt(8)
	s_waitcnt lgkmcnt(0)
	s_setprio 1
	s_barrier
	v_mfma_f32_16x16x32_bf16 v[126:129], v[146:149], v[184:187], v[126:129]
	v_mfma_f32_16x16x32_bf16 v[126:129], v[150:153], v[188:191], v[126:129]
	v_mfma_f32_16x16x32_bf16 v[118:121], v[154:157], v[184:187], v[118:121]
	v_mfma_f32_16x16x32_bf16 v[118:121], v[158:161], v[188:191], v[118:121]
	v_mfma_f32_16x16x32_bf16 v[110:113], v[146:149], v[192:195], v[110:113]
	v_mfma_f32_16x16x32_bf16 v[110:113], v[150:153], v[196:199], v[110:113]
	v_mfma_f32_16x16x32_bf16 v[102:105], v[154:157], v[192:195], v[102:105]
	v_mfma_f32_16x16x32_bf16 v[102:105], v[158:161], v[196:199], v[102:105]
	v_mfma_f32_16x16x32_bf16 v[94:97], v[146:149], v[200:203], v[94:97]
	v_mfma_f32_16x16x32_bf16 v[94:97], v[150:153], v[204:207], v[94:97]
	v_mfma_f32_16x16x32_bf16 v[86:89], v[154:157], v[200:203], v[86:89]
	v_mfma_f32_16x16x32_bf16 v[86:89], v[158:161], v[204:207], v[86:89]
	v_mfma_f32_16x16x32_bf16 v[78:81], v[146:149], v[208:211], v[78:81]
	v_mfma_f32_16x16x32_bf16 v[78:81], v[150:153], v[212:215], v[78:81]
	v_mfma_f32_16x16x32_bf16 v[70:73], v[154:157], v[208:211], v[70:73]
	v_mfma_f32_16x16x32_bf16 v[70:73], v[158:161], v[212:215], v[70:73]
	v_mfma_f32_16x16x32_bf16 v[122:125], v[162:165], v[184:187], v[122:125]
	v_mfma_f32_16x16x32_bf16 v[122:125], v[166:169], v[188:191], v[122:125]
	v_mfma_f32_16x16x32_bf16 v[114:117], v[170:173], v[184:187], v[114:117]
	v_mfma_f32_16x16x32_bf16 v[114:117], v[180:183], v[188:191], v[114:117]
	v_mfma_f32_16x16x32_bf16 v[106:109], v[162:165], v[192:195], v[106:109]
	v_mfma_f32_16x16x32_bf16 v[106:109], v[166:169], v[196:199], v[106:109]
	v_mfma_f32_16x16x32_bf16 v[98:101], v[170:173], v[192:195], v[98:101]
	v_mfma_f32_16x16x32_bf16 v[98:101], v[180:183], v[196:199], v[98:101]
	v_mfma_f32_16x16x32_bf16 v[90:93], v[162:165], v[200:203], v[90:93]
	v_mfma_f32_16x16x32_bf16 v[90:93], v[166:169], v[204:207], v[90:93]
	v_mfma_f32_16x16x32_bf16 v[82:85], v[170:173], v[200:203], v[82:85]
	v_mfma_f32_16x16x32_bf16 v[82:85], v[180:183], v[204:207], v[82:85]
	v_mfma_f32_16x16x32_bf16 v[74:77], v[162:165], v[208:211], v[74:77]
	v_mfma_f32_16x16x32_bf16 v[74:77], v[166:169], v[212:215], v[74:77]
	v_mfma_f32_16x16x32_bf16 v[66:69], v[170:173], v[208:211], v[66:69]
	v_mfma_f32_16x16x32_bf16 v[66:69], v[180:183], v[212:215], v[66:69]
	s_barrier
; #define PG8_STAGE(bufoff, gbase, voff) do { _Pragma("unroll") for (int _i = 0; _i < 2; ++_i) \
;         __builtin_amdgcn_global_load_lds((const unsigned*)((const char*)(gbase) + (voff)[_i]), (LAS unsigned*)(lds + (bufoff) + ldsw + _i * 8192), 16, 0, 0); } while (0)
; #define PG8_LDA(dst, b, h) do { _Pragma("unroll") for (int m = 0; m < 4; ++m) _Pragma("unroll") for (int k = 0; k < 2; ++k) dst[m][k] = *(const LAS bf16x8*)(lds + PG8_SA(b, h) + aoff + m * 2048 + k * 1024); } while (0)
; #define PG8_MMA(ai, bj, At, Bt) do { __builtin_amdgcn_s_setprio(1); _Pragma("unroll") for (int m = 0; m < 4; ++m) _Pragma("unroll") for (int n = 0; n < 2; ++n) _Pragma("unroll") for (int k = 0; k < 2; ++k) \
;         acc[ai][bj][m][n] = __builtin_amdgcn_mfma_f32_16x16x32_bf16(Bt[n][k], At[m][k], acc[ai][bj][m][n], 0, 0, 0); __builtin_amdgcn_s_setprio(0); } while (0)
; #define PG8_WAIT_V(n) asm volatile("s_waitcnt vmcnt(" #n ")" ::: "memory")
; #define PG8_WAIT_L(n) asm volatile("s_waitcnt lgkmcnt(" #n ")" ::: "memory")
; #define PG8_BAR __builtin_amdgcn_s_barrier()
; #define PG8_SCHED __builtin_amdgcn_sched_barrier(0)
; template <class Epi, class Sched, int LDA, int LDB, bool ALIGN_EPI = true>
; __device__ __forceinline__ void gemm_phase(LAS unsigned char* lds, const Gemm g, const Sched& S, const Epi& E, int wave) {
;     ...
;             PG8_LDA(At, 1, 1); PG8_STAGE(PG8_SB(1, 0), b3, voffB); PG8_STAGE(PG8_SB(1, 1), b3 + hstepB, voffB); PG8_STAGE(PG8_SA(1, 0), a3, voffA);
;             PG8_WAIT_V(8); PG8_WAIT_L(0); PG8_BAR; PG8_MMA(1, 0, At, B0); PG8_MMA(1, 1, At, B1); PG8_BAR; PG8_SCHED;
;         }
;         if constexpr (ALIGN_EPI) { if (wr == 0) PG8_BAR; }
	s_setprio 0
	s_add_i32 s18, s54, s5
	v_lshl_add_u64 v[140:141], v[140:141], 0, s[6:7]
	s_mov_b32 m0, s18
	ds_read_b128 v[184:187], v145 offset:49152
	ds_read_b128 v[188:191], v145 offset:50176
	ds_read_b128 v[192:195], v145 offset:51200
	ds_read_b128 v[196:199], v145 offset:52224
	ds_read_b128 v[200:203], v145 offset:53248
	ds_read_b128 v[204:207], v145 offset:54272
	ds_read_b128 v[208:211], v145 offset:55296
	ds_read_b128 v[212:215], v145 offset:56320
	global_load_lds_dwordx4 v[140:141], off
	s_add_i32 m0, s18, 0x2000
	s_add_u32 s18, s28, 0x80080
	v_lshl_add_u64 v[140:141], v[174:175], 0, s[6:7]
	s_addc_u32 s19, s29, 0
	s_add_i32 s28, s55, s5
	global_load_lds_dwordx4 v[140:141], off
	v_lshl_add_u64 v[140:141], s[18:19], 0, v[0:1]
	s_mov_b32 m0, s28
	s_nop 0
	global_load_lds_dwordx4 v[140:141], off
	v_lshl_add_u64 v[140:141], s[18:19], 0, v[130:131]
	s_add_i32 m0, s28, 0x2000
	s_nop 0
	global_load_lds_dwordx4 v[140:141], off
	v_lshl_add_u64 v[140:141], v[216:217], 0, s[6:7]
	s_mov_b32 m0, s48
	s_nop 0
	global_load_lds_dwordx4 v[140:141], off
	v_lshl_add_u64 v[140:141], v[218:219], 0, s[6:7]
	s_mov_b32 m0, s49
	s_nop 0
	global_load_lds_dwordx4 v[140:141], off
	s_waitcnt vmcnt(8)
	s_waitcnt lgkmcnt(0)
	s_setprio 1
	s_barrier
	v_mfma_f32_16x16x32_bf16 v[62:65], v[146:149], v[184:187], v[62:65]
	v_mfma_f32_16x16x32_bf16 v[62:65], v[150:153], v[188:191], v[62:65]
	v_mfma_f32_16x16x32_bf16 v[54:57], v[154:157], v[184:187], v[54:57]
	v_mfma_f32_16x16x32_bf16 v[54:57], v[158:161], v[188:191], v[54:57]
	v_mfma_f32_16x16x32_bf16 v[46:49], v[146:149], v[192:195], v[46:49]
	v_mfma_f32_16x16x32_bf16 v[46:49], v[150:153], v[196:199], v[46:49]
	v_mfma_f32_16x16x32_bf16 v[38:41], v[154:157], v[192:195], v[38:41]
	v_mfma_f32_16x16x32_bf16 v[38:41], v[158:161], v[196:199], v[38:41]
	v_mfma_f32_16x16x32_bf16 v[30:33], v[146:149], v[200:203], v[30:33]
	v_mfma_f32_16x16x32_bf16 v[30:33], v[150:153], v[204:207], v[30:33]
	v_mfma_f32_16x16x32_bf16 v[22:25], v[154:157], v[200:203], v[22:25]
	v_mfma_f32_16x16x32_bf16 v[22:25], v[158:161], v[204:207], v[22:25]
	v_mfma_f32_16x16x32_bf16 v[14:17], v[146:149], v[208:211], v[14:17]
	v_mfma_f32_16x16x32_bf16 v[14:17], v[150:153], v[212:215], v[14:17]
	v_mfma_f32_16x16x32_bf16 v[6:9], v[154:157], v[208:211], v[6:9]
	v_mfma_f32_16x16x32_bf16 v[6:9], v[158:161], v[212:215], v[6:9]
	v_mfma_f32_16x16x32_bf16 v[58:61], v[162:165], v[184:187], v[58:61]
	v_mfma_f32_16x16x32_bf16 v[58:61], v[166:169], v[188:191], v[58:61]
	v_mfma_f32_16x16x32_bf16 v[50:53], v[170:173], v[184:187], v[50:53]
	v_mfma_f32_16x16x32_bf16 v[50:53], v[180:183], v[188:191], v[50:53]
	v_mfma_f32_16x16x32_bf16 v[42:45], v[162:165], v[192:195], v[42:45]
	v_mfma_f32_16x16x32_bf16 v[42:45], v[166:169], v[196:199], v[42:45]
	v_mfma_f32_16x16x32_bf16 v[34:37], v[170:173], v[192:195], v[34:37]
	v_mfma_f32_16x16x32_bf16 v[34:37], v[180:183], v[196:199], v[34:37]
	v_mfma_f32_16x16x32_bf16 v[26:29], v[162:165], v[200:203], v[26:29]
	v_mfma_f32_16x16x32_bf16 v[26:29], v[166:169], v[204:207], v[26:29]
	v_mfma_f32_16x16x32_bf16 v[18:21], v[170:173], v[200:203], v[18:21]
	v_mfma_f32_16x16x32_bf16 v[18:21], v[180:183], v[204:207], v[18:21]
	v_mfma_f32_16x16x32_bf16 v[10:13], v[162:165], v[208:211], v[10:13]
	v_mfma_f32_16x16x32_bf16 v[10:13], v[166:169], v[212:215], v[10:13]
	v_mfma_f32_16x16x32_bf16 v[2:5], v[170:173], v[208:211], v[2:5]
	v_mfma_f32_16x16x32_bf16 v[2:5], v[180:183], v[212:215], v[2:5]
	s_barrier
	s_setprio 0
	s_add_i32 s53, s53, 2
	s_add_u32 s44, s44, 0x100
	s_addc_u32 s45, s45, 0
	s_cmp_gt_u32 s53, 29
	s_mov_b64 s[18:19], s[24:25]
	s_cbranch_scc0 .LBB0_485
	v_readlane_b32 s6, v252, 14
	v_readlane_b32 s7, v252, 15
	s_and_b64 vcc, exec, s[6:7]
	s_cbranch_vccz .LBB0_488
	s_barrier

; #define PG8_STAGE(bufoff, gbase, voff) do { _Pragma("unroll") for (int _i = 0; _i < 2; ++_i) \
;         __builtin_amdgcn_global_load_lds((const unsigned*)((const char*)(gbase) + (voff)[_i]), (LAS unsigned*)(lds + (bufoff) + ldsw + _i * 8192), 16, 0, 0); } while (0)
; #define PG8_LDA(dst, b, h) do { _Pragma("unroll") for (int m = 0; m < 4; ++m) _Pragma("unroll") for (int k = 0; k < 2; ++k) dst[m][k] = *(const LAS bf16x8*)(lds + PG8_SA(b, h) + aoff + m * 2048 + k * 1024); } while (0)
; #define PG8_LDB(dst, b, h) do { _Pragma("unroll") for (int n = 0; n < 2; ++n) _Pragma("unroll") for (int k = 0; k < 2; ++k) dst[n][k] = *(const LAS bf16x8*)(lds + PG8_SB(b, h) + boff + n * 2048 + k * 1024); } while (0)
; #define PG8_MMA(ai, bj, At, Bt) do { __builtin_amdgcn_s_setprio(1); _Pragma("unroll") for (int m = 0; m < 4; ++m) _Pragma("unroll") for (int n = 0; n < 2; ++n) _Pragma("unroll") for (int k = 0; k < 2; ++k) \
;         acc[ai][bj][m][n] = __builtin_amdgcn_mfma_f32_16x16x32_bf16(Bt[n][k], At[m][k], acc[ai][bj][m][n], 0, 0, 0); __builtin_amdgcn_s_setprio(0); } while (0)
; #define PG8_WAIT_V(n) asm volatile("s_waitcnt vmcnt(" #n ")" ::: "memory")
; #define PG8_WAIT_L(n) asm volatile("s_waitcnt lgkmcnt(" #n ")" ::: "memory")
; #define PG8_BAR __builtin_amdgcn_s_barrier()
; #define PG8_SCHED __builtin_amdgcn_sched_barrier(0)
; template <class Epi, class Sched, int LDA, int LDB, bool ALIGN_EPI = true>
; __device__ __forceinline__ void gemm_phase(LAS unsigned char* lds, const Gemm g, const Sched& S, const Epi& E, int wave) {
;     ...
;             PG8_LDB(B0, 0, 0); PG8_LDB(B1, 0, 1); PG8_SCHED; PG8_LDA(At, 0, 0); PG8_STAGE(PG8_SA(1, 1), a1 + hstepA, voffA);
;             PG8_WAIT_V(8); PG8_WAIT_L(0); PG8_BAR; PG8_MMA(0, 0, At, B0); PG8_MMA(0, 1, At, B1); PG8_BAR; PG8_SCHED;
;             PG8_LDA(At, 0, 1); PG8_STAGE(PG8_SB(0, 0), b2, voffB); PG8_STAGE(PG8_SB(0, 1), b2 + hstepB, voffB); PG8_STAGE(PG8_SA(0, 0), a2, voffA);
;             PG8_WAIT_V(8); PG8_WAIT_L(0); PG8_BAR; PG8_MMA(1, 0, At, B0); PG8_MMA(1, 1, At, B1); PG8_BAR; PG8_SCHED;
.LBB0_1893:
	s_add_i32 s79, s46, 2
	s_add_u32 s38, s36, 0x100
	s_addc_u32 s39, s37, 0
	s_add_i32 s82, 0, 0x10000
	s_cmp_eq_u32 s25, s46
	s_cselect_b32 s49, s29, s39
	s_cselect_b32 s48, s28, s38
	s_cselect_b32 s47, s35, s78
	s_cselect_b32 s46, s34, s77
	s_add_i32 s85, 0, 0x14000
	v_add_u32_e32 v152, s82, v249
	v_add_u32_e32 v168, s85, v249
	ds_read_b128 v[130:133], v152
	ds_read_b128 v[134:137], v152 offset:1024
	ds_read_b128 v[148:151], v152 offset:2048
	ds_read_b128 v[152:155], v152 offset:3072
	ds_read_b128 v[156:159], v168
	ds_read_b128 v[160:163], v168 offset:1024
	ds_read_b128 v[164:167], v168 offset:2048
	ds_read_b128 v[168:171], v168 offset:3072
	v_lshl_add_u64 v[208:209], s[36:37], 0, v[144:145]
	s_add_i32 m0, s50, 0xc000
	ds_read_b128 v[172:175], v236
	ds_read_b128 v[180:183], v236 offset:1024
	ds_read_b128 v[184:187], v236 offset:2048
	ds_read_b128 v[188:191], v236 offset:3072
	ds_read_b128 v[192:195], v236 offset:4096
	ds_read_b128 v[196:199], v236 offset:5120
	ds_read_b128 v[200:203], v236 offset:6144
	ds_read_b128 v[204:207], v236 offset:7168
	global_load_lds_dwordx4 v[208:209], off
	v_lshl_add_u64 v[208:209], s[36:37], 0, v[146:147]
	s_add_i32 m0, s50, 0xe000
	s_nop 0
	global_load_lds_dwordx4 v[208:209], off
	s_waitcnt vmcnt(8)
	s_waitcnt lgkmcnt(0)
	s_setprio 1
	s_barrier
	v_mfma_f32_16x16x32_bf16 v[126:129], v[130:133], v[172:175], v[126:129]
	v_mfma_f32_16x16x32_bf16 v[126:129], v[134:137], v[180:183], v[126:129]
	v_mfma_f32_16x16x32_bf16 v[122:125], v[148:151], v[172:175], v[122:125]
	v_mfma_f32_16x16x32_bf16 v[122:125], v[152:155], v[180:183], v[122:125]
	v_mfma_f32_16x16x32_bf16 v[110:113], v[130:133], v[184:187], v[110:113]
	v_mfma_f32_16x16x32_bf16 v[110:113], v[134:137], v[188:191], v[110:113]
	v_mfma_f32_16x16x32_bf16 v[106:109], v[148:151], v[184:187], v[106:109]
	v_mfma_f32_16x16x32_bf16 v[106:109], v[152:155], v[188:191], v[106:109]
	v_mfma_f32_16x16x32_bf16 v[94:97], v[130:133], v[192:195], v[94:97]
	v_mfma_f32_16x16x32_bf16 v[94:97], v[134:137], v[196:199], v[94:97]
	v_mfma_f32_16x16x32_bf16 v[90:93], v[148:151], v[192:195], v[90:93]
	v_mfma_f32_16x16x32_bf16 v[90:93], v[152:155], v[196:199], v[90:93]
	v_mfma_f32_16x16x32_bf16 v[78:81], v[130:133], v[200:203], v[78:81]
	v_mfma_f32_16x16x32_bf16 v[78:81], v[134:137], v[204:207], v[78:81]
	v_mfma_f32_16x16x32_bf16 v[74:77], v[148:151], v[200:203], v[74:77]
	v_mfma_f32_16x16x32_bf16 v[74:77], v[152:155], v[204:207], v[74:77]
	v_mfma_f32_16x16x32_bf16 v[118:121], v[156:159], v[172:175], v[118:121]
	v_mfma_f32_16x16x32_bf16 v[118:121], v[160:163], v[180:183], v[118:121]
	v_mfma_f32_16x16x32_bf16 v[114:117], v[164:167], v[172:175], v[114:117]
	v_mfma_f32_16x16x32_bf16 v[114:117], v[168:171], v[180:183], v[114:117]
	v_mfma_f32_16x16x32_bf16 v[102:105], v[156:159], v[184:187], v[102:105]
	v_mfma_f32_16x16x32_bf16 v[102:105], v[160:163], v[188:191], v[102:105]
	v_mfma_f32_16x16x32_bf16 v[98:101], v[164:167], v[184:187], v[98:101]
	v_mfma_f32_16x16x32_bf16 v[98:101], v[168:171], v[188:191], v[98:101]
	v_mfma_f32_16x16x32_bf16 v[86:89], v[156:159], v[192:195], v[86:89]
	v_mfma_f32_16x16x32_bf16 v[86:89], v[160:163], v[196:199], v[86:89]
	v_mfma_f32_16x16x32_bf16 v[82:85], v[164:167], v[192:195], v[82:85]
	v_mfma_f32_16x16x32_bf16 v[82:85], v[168:171], v[196:199], v[82:85]
	v_mfma_f32_16x16x32_bf16 v[70:73], v[156:159], v[200:203], v[70:73]
	v_mfma_f32_16x16x32_bf16 v[70:73], v[160:163], v[204:207], v[70:73]
	v_mfma_f32_16x16x32_bf16 v[66:69], v[164:167], v[200:203], v[66:69]
	v_mfma_f32_16x16x32_bf16 v[66:69], v[168:171], v[204:207], v[66:69]
	s_barrier
	s_setprio 0
	s_add_i32 s36, s82, s2
	v_lshl_add_u64 v[208:209], s[46:47], 0, v[0:1]
	s_mov_b32 m0, s36
	ds_read_b128 v[172:175], v236 offset:16384
	ds_read_b128 v[180:183], v236 offset:17408
	ds_read_b128 v[184:187], v236 offset:18432
	ds_read_b128 v[188:191], v236 offset:19456
	ds_read_b128 v[192:195], v236 offset:20480
	ds_read_b128 v[196:199], v236 offset:21504
	ds_read_b128 v[200:203], v236 offset:22528
	ds_read_b128 v[204:207], v236 offset:23552
	global_load_lds_dwordx4 v[208:209], off
	s_add_i32 m0, s36, 0x2000
	s_add_u32 s36, s46, 0x160000
	v_lshl_add_u64 v[210:211], s[46:47], 0, v[142:143]
	s_addc_u32 s37, s47, 0
	s_add_i32 s82, s85, s2
	global_load_lds_dwordx4 v[210:211], off
	v_lshl_add_u64 v[212:213], s[36:37], 0, v[0:1]
	s_mov_b32 m0, s82
	v_lshl_add_u64 v[214:215], s[48:49], 0, v[140:141]
	global_load_lds_dwordx4 v[212:213], off
	v_lshl_add_u64 v[212:213], s[36:37], 0, v[142:143]
	s_add_i32 m0, s82, 0x2000
	s_nop 0
	global_load_lds_dwordx4 v[212:213], off
	v_lshl_add_u64 v[212:213], s[48:49], 0, v[138:139]
	s_mov_b32 m0, s50
	s_nop 0
	global_load_lds_dwordx4 v[212:213], off
	s_mov_b32 m0, s51
	s_nop 0
	global_load_lds_dwordx4 v[214:215], off
	s_waitcnt vmcnt(8)
	s_waitcnt lgkmcnt(0)
	s_setprio 1
	s_barrier
; #define PG8_STAGE(bufoff, gbase, voff) do { _Pragma("unroll") for (int _i = 0; _i < 2; ++_i) \
;         __builtin_amdgcn_global_load_lds((const unsigned*)((const char*)(gbase) + (voff)[_i]), (LAS unsigned*)(lds + (bufoff) + ldsw + _i * 8192), 16, 0, 0); } while (0)
; #define PG8_LDA(dst, b, h) do { _Pragma("unroll") for (int m = 0; m < 4; ++m) _Pragma("unroll") for (int k = 0; k < 2; ++k) dst[m][k] = *(const LAS bf16x8*)(lds + PG8_SA(b, h) + aoff + m * 2048 + k * 1024); } while (0)
; #define PG8_LDB(dst, b, h) do { _Pragma("unroll") for (int n = 0; n < 2; ++n) _Pragma("unroll") for (int k = 0; k < 2; ++k) dst[n][k] = *(const LAS bf16x8*)(lds + PG8_SB(b, h) + boff + n * 2048 + k * 1024); } while (0)
; #define PG8_MMA(ai, bj, At, Bt) do { __builtin_amdgcn_s_setprio(1); _Pragma("unroll") for (int m = 0; m < 4; ++m) _Pragma("unroll") for (int n = 0; n < 2; ++n) _Pragma("unroll") for (int k = 0; k < 2; ++k) \
;         acc[ai][bj][m][n] = __builtin_amdgcn_mfma_f32_16x16x32_bf16(Bt[n][k], At[m][k], acc[ai][bj][m][n], 0, 0, 0); __builtin_amdgcn_s_setprio(0); } while (0)
; #define PG8_WAIT_V(n) asm volatile("s_waitcnt vmcnt(" #n ")" ::: "memory")
; #define PG8_WAIT_L(n) asm volatile("s_waitcnt lgkmcnt(" #n ")" ::: "memory")
; #define PG8_BAR __builtin_amdgcn_s_barrier()
; #define PG8_SCHED __builtin_amdgcn_sched_barrier(0)
; template <class Epi, class Sched, int LDA, int LDB, bool ALIGN_EPI = true>
; __device__ __forceinline__ void gemm_phase(LAS unsigned char* lds, const Gemm g, const Sched& S, const Epi& E, int wave) {
;     ...
;             PG8_WAIT_V(8); PG8_WAIT_L(0); PG8_BAR; PG8_MMA(1, 0, At, B0); PG8_MMA(1, 1, At, B1); PG8_BAR; PG8_SCHED;
;             PG8_LDB(B0, 1, 0); PG8_LDB(B1, 1, 1); PG8_SCHED; PG8_LDA(At, 1, 0); PG8_STAGE(PG8_SA(0, 1), a2 + hstepA, voffA);
;             PG8_WAIT_V(8); PG8_WAIT_L(0); PG8_BAR; PG8_MMA(0, 0, At, B0); PG8_MMA(0, 1, At, B1); PG8_BAR; PG8_SCHED;
	v_mfma_f32_16x16x32_bf16 v[62:65], v[130:133], v[172:175], v[62:65]
	v_mfma_f32_16x16x32_bf16 v[62:65], v[134:137], v[180:183], v[62:65]
	v_mfma_f32_16x16x32_bf16 v[58:61], v[148:151], v[172:175], v[58:61]
	v_mfma_f32_16x16x32_bf16 v[58:61], v[152:155], v[180:183], v[58:61]
	v_mfma_f32_16x16x32_bf16 v[46:49], v[130:133], v[184:187], v[46:49]
	v_mfma_f32_16x16x32_bf16 v[46:49], v[134:137], v[188:191], v[46:49]
	v_mfma_f32_16x16x32_bf16 v[42:45], v[148:151], v[184:187], v[42:45]
	v_mfma_f32_16x16x32_bf16 v[42:45], v[152:155], v[188:191], v[42:45]
	v_mfma_f32_16x16x32_bf16 v[30:33], v[130:133], v[192:195], v[30:33]
	v_mfma_f32_16x16x32_bf16 v[30:33], v[134:137], v[196:199], v[30:33]
	v_mfma_f32_16x16x32_bf16 v[26:29], v[148:151], v[192:195], v[26:29]
	v_mfma_f32_16x16x32_bf16 v[26:29], v[152:155], v[196:199], v[26:29]
	v_mfma_f32_16x16x32_bf16 v[14:17], v[130:133], v[200:203], v[14:17]
	v_mfma_f32_16x16x32_bf16 v[14:17], v[134:137], v[204:207], v[14:17]
	v_mfma_f32_16x16x32_bf16 v[10:13], v[148:151], v[200:203], v[10:13]
	v_mfma_f32_16x16x32_bf16 v[10:13], v[152:155], v[204:207], v[10:13]
	v_mfma_f32_16x16x32_bf16 v[54:57], v[156:159], v[172:175], v[54:57]
	v_mfma_f32_16x16x32_bf16 v[54:57], v[160:163], v[180:183], v[54:57]
	v_mfma_f32_16x16x32_bf16 v[50:53], v[164:167], v[172:175], v[50:53]
	v_mfma_f32_16x16x32_bf16 v[50:53], v[168:171], v[180:183], v[50:53]
	v_mfma_f32_16x16x32_bf16 v[38:41], v[156:159], v[184:187], v[38:41]
	v_mfma_f32_16x16x32_bf16 v[38:41], v[160:163], v[188:191], v[38:41]
	v_mfma_f32_16x16x32_bf16 v[34:37], v[164:167], v[184:187], v[34:37]
	v_mfma_f32_16x16x32_bf16 v[34:37], v[168:171], v[188:191], v[34:37]
	v_mfma_f32_16x16x32_bf16 v[22:25], v[156:159], v[192:195], v[22:25]
	v_mfma_f32_16x16x32_bf16 v[22:25], v[160:163], v[196:199], v[22:25]
	v_mfma_f32_16x16x32_bf16 v[18:21], v[164:167], v[192:195], v[18:21]
	v_mfma_f32_16x16x32_bf16 v[18:21], v[168:171], v[196:199], v[18:21]
	v_mfma_f32_16x16x32_bf16 v[6:9], v[156:159], v[200:203], v[6:9]
	v_mfma_f32_16x16x32_bf16 v[6:9], v[160:163], v[204:207], v[6:9]
	v_mfma_f32_16x16x32_bf16 v[2:5], v[164:167], v[200:203], v[2:5]
	v_mfma_f32_16x16x32_bf16 v[2:5], v[168:171], v[204:207], v[2:5]
	s_barrier
	s_setprio 0
	s_add_i32 s82, 0, 0x18000
	s_add_i32 s85, 0, 0x1c000
	v_add_u32_e32 v152, s82, v249
	v_add_u32_e32 v168, s85, v249
	ds_read_b128 v[130:133], v152
	ds_read_b128 v[134:137], v152 offset:1024
	ds_read_b128 v[148:151], v152 offset:2048
	ds_read_b128 v[152:155], v152 offset:3072
	ds_read_b128 v[156:159], v168
	ds_read_b128 v[160:163], v168 offset:1024
	ds_read_b128 v[164:167], v168 offset:2048
	ds_read_b128 v[168:171], v168 offset:3072
	s_add_u32 s36, s48, 0x160000
	s_addc_u32 s37, s49, 0
	s_mov_b32 m0, s52
	v_lshl_add_u64 v[216:217], s[36:37], 0, v[138:139]
	ds_read_b128 v[172:175], v236 offset:32768
	ds_read_b128 v[180:183], v236 offset:33792
	ds_read_b128 v[184:187], v236 offset:34816
	ds_read_b128 v[188:191], v236 offset:35840
	ds_read_b128 v[192:195], v236 offset:36864
	ds_read_b128 v[196:199], v236 offset:37888
	ds_read_b128 v[200:203], v236 offset:38912
	ds_read_b128 v[204:207], v236 offset:39936
	global_load_lds_dwordx4 v[216:217], off
	v_lshl_add_u64 v[216:217], s[36:37], 0, v[140:141]
	s_mov_b32 m0, s53
	s_nop 0
	global_load_lds_dwordx4 v[216:217], off
	s_waitcnt vmcnt(8)
	s_waitcnt lgkmcnt(0)
	s_setprio 1
	s_barrier
	v_mfma_f32_16x16x32_bf16 v[126:129], v[130:133], v[172:175], v[126:129]
	v_mfma_f32_16x16x32_bf16 v[126:129], v[134:137], v[180:183], v[126:129]
	v_mfma_f32_16x16x32_bf16 v[122:125], v[148:151], v[172:175], v[122:125]
	v_mfma_f32_16x16x32_bf16 v[122:125], v[152:155], v[180:183], v[122:125]
	v_mfma_f32_16x16x32_bf16 v[110:113], v[130:133], v[184:187], v[110:113]
	v_mfma_f32_16x16x32_bf16 v[110:113], v[134:137], v[188:191], v[110:113]
	v_mfma_f32_16x16x32_bf16 v[106:109], v[148:151], v[184:187], v[106:109]
	v_mfma_f32_16x16x32_bf16 v[106:109], v[152:155], v[188:191], v[106:109]
	v_mfma_f32_16x16x32_bf16 v[94:97], v[130:133], v[192:195], v[94:97]
	v_mfma_f32_16x16x32_bf16 v[94:97], v[134:137], v[196:199], v[94:97]
	v_mfma_f32_16x16x32_bf16 v[90:93], v[148:151], v[192:195], v[90:93]
	v_mfma_f32_16x16x32_bf16 v[90:93], v[152:155], v[196:199], v[90:93]
	v_mfma_f32_16x16x32_bf16 v[78:81], v[130:133], v[200:203], v[78:81]
	v_mfma_f32_16x16x32_bf16 v[78:81], v[134:137], v[204:207], v[78:81]
	v_mfma_f32_16x16x32_bf16 v[74:77], v[148:151], v[200:203], v[74:77]
	v_mfma_f32_16x16x32_bf16 v[74:77], v[152:155], v[204:207], v[74:77]
	v_mfma_f32_16x16x32_bf16 v[118:121], v[156:159], v[172:175], v[118:121]
	v_mfma_f32_16x16x32_bf16 v[118:121], v[160:163], v[180:183], v[118:121]
	v_mfma_f32_16x16x32_bf16 v[114:117], v[164:167], v[172:175], v[114:117]
	v_mfma_f32_16x16x32_bf16 v[114:117], v[168:171], v[180:183], v[114:117]
	v_mfma_f32_16x16x32_bf16 v[102:105], v[156:159], v[184:187], v[102:105]
	v_mfma_f32_16x16x32_bf16 v[102:105], v[160:163], v[188:191], v[102:105]
	v_mfma_f32_16x16x32_bf16 v[98:101], v[164:167], v[184:187], v[98:101]
	v_mfma_f32_16x16x32_bf16 v[98:101], v[168:171], v[188:191], v[98:101]
	v_mfma_f32_16x16x32_bf16 v[86:89], v[156:159], v[192:195], v[86:89]
	v_mfma_f32_16x16x32_bf16 v[86:89], v[160:163], v[196:199], v[86:89]
	v_mfma_f32_16x16x32_bf16 v[82:85], v[164:167], v[192:195], v[82:85]
	v_mfma_f32_16x16x32_bf16 v[82:85], v[168:171], v[196:199], v[82:85]
	v_mfma_f32_16x16x32_bf16 v[70:73], v[156:159], v[200:203], v[70:73]
	v_mfma_f32_16x16x32_bf16 v[70:73], v[160:163], v[204:207], v[70:73]
	v_mfma_f32_16x16x32_bf16 v[66:69], v[164:167], v[200:203], v[66:69]
	v_mfma_f32_16x16x32_bf16 v[66:69], v[168:171], v[204:207], v[66:69]
	s_barrier
; #define PG8_STAGE(bufoff, gbase, voff) do { _Pragma("unroll") for (int _i = 0; _i < 2; ++_i) \
;         __builtin_amdgcn_global_load_lds((const unsigned*)((const char*)(gbase) + (voff)[_i]), (LAS unsigned*)(lds + (bufoff) + ldsw + _i * 8192), 16, 0, 0); } while (0)
; #define PG8_LDA(dst, b, h) do { _Pragma("unroll") for (int m = 0; m < 4; ++m) _Pragma("unroll") for (int k = 0; k < 2; ++k) dst[m][k] = *(const LAS bf16x8*)(lds + PG8_SA(b, h) + aoff + m * 2048 + k * 1024); } while (0)
; #define PG8_MMA(ai, bj, At, Bt) do { __builtin_amdgcn_s_setprio(1); _Pragma("unroll") for (int m = 0; m < 4; ++m) _Pragma("unroll") for (int n = 0; n < 2; ++n) _Pragma("unroll") for (int k = 0; k < 2; ++k) \
;         acc[ai][bj][m][n] = __builtin_amdgcn_mfma_f32_16x16x32_bf16(Bt[n][k], At[m][k], acc[ai][bj][m][n], 0, 0, 0); __builtin_amdgcn_s_setprio(0); } while (0)
; #define PG8_WAIT_V(n) asm volatile("s_waitcnt vmcnt(" #n ")" ::: "memory")
; #define PG8_WAIT_L(n) asm volatile("s_waitcnt lgkmcnt(" #n ")" ::: "memory")
; #define PG8_BAR __builtin_amdgcn_s_barrier()
; #define PG8_SCHED __builtin_amdgcn_sched_barrier(0)
; template <class Epi, class Sched, int LDA, int LDB, bool ALIGN_EPI = true>
; __device__ __forceinline__ void gemm_phase(LAS unsigned char* lds, const Gemm g, const Sched& S, const Epi& E, int wave) {
;     ...
;             PG8_LDA(At, 1, 1); PG8_STAGE(PG8_SB(1, 0), b3, voffB); PG8_STAGE(PG8_SB(1, 1), b3 + hstepB, voffB); PG8_STAGE(PG8_SA(1, 0), a3, voffA);
;             PG8_WAIT_V(8); PG8_WAIT_L(0); PG8_BAR; PG8_MMA(1, 0, At, B0); PG8_MMA(1, 1, At, B1); PG8_BAR; PG8_SCHED;
;         }
;         if constexpr (ALIGN_EPI) { if (wr == 0) PG8_BAR; }
	s_setprio 0
	s_add_i32 s36, s82, s2
	v_lshl_add_u64 v[208:209], v[208:209], 0, s[8:9]
	s_mov_b32 m0, s36
	ds_read_b128 v[172:175], v236 offset:49152
	ds_read_b128 v[180:183], v236 offset:50176
	ds_read_b128 v[184:187], v236 offset:51200
	ds_read_b128 v[188:191], v236 offset:52224
	ds_read_b128 v[192:195], v236 offset:53248
	ds_read_b128 v[196:199], v236 offset:54272
	ds_read_b128 v[200:203], v236 offset:55296
	ds_read_b128 v[204:207], v236 offset:56320
	global_load_lds_dwordx4 v[208:209], off
	s_add_i32 m0, s36, 0x2000
	s_add_u32 s36, s46, 0x160080
	v_lshl_add_u64 v[208:209], v[210:211], 0, s[8:9]
	s_addc_u32 s37, s47, 0
	s_add_i32 s46, s85, s2
	global_load_lds_dwordx4 v[208:209], off
	v_lshl_add_u64 v[208:209], s[36:37], 0, v[0:1]
	s_mov_b32 m0, s46
	s_nop 0
	global_load_lds_dwordx4 v[208:209], off
	v_lshl_add_u64 v[208:209], s[36:37], 0, v[142:143]
	s_add_i32 m0, s46, 0x2000
	s_nop 0
	global_load_lds_dwordx4 v[208:209], off
	v_lshl_add_u64 v[208:209], v[212:213], 0, s[8:9]
	s_mov_b32 m0, s5
	s_nop 0
	global_load_lds_dwordx4 v[208:209], off
	v_lshl_add_u64 v[208:209], v[214:215], 0, s[8:9]
	s_mov_b32 m0, s59
	s_nop 0
	global_load_lds_dwordx4 v[208:209], off
	s_waitcnt vmcnt(8)
	s_waitcnt lgkmcnt(0)
	s_setprio 1
	s_barrier
	v_mfma_f32_16x16x32_bf16 v[62:65], v[130:133], v[172:175], v[62:65]
	v_mfma_f32_16x16x32_bf16 v[62:65], v[134:137], v[180:183], v[62:65]
	v_mfma_f32_16x16x32_bf16 v[58:61], v[148:151], v[172:175], v[58:61]
	v_mfma_f32_16x16x32_bf16 v[58:61], v[152:155], v[180:183], v[58:61]
	v_mfma_f32_16x16x32_bf16 v[46:49], v[130:133], v[184:187], v[46:49]
	v_mfma_f32_16x16x32_bf16 v[46:49], v[134:137], v[188:191], v[46:49]
	v_mfma_f32_16x16x32_bf16 v[42:45], v[148:151], v[184:187], v[42:45]
	v_mfma_f32_16x16x32_bf16 v[42:45], v[152:155], v[188:191], v[42:45]
	v_mfma_f32_16x16x32_bf16 v[30:33], v[130:133], v[192:195], v[30:33]
	v_mfma_f32_16x16x32_bf16 v[30:33], v[134:137], v[196:199], v[30:33]
	v_mfma_f32_16x16x32_bf16 v[26:29], v[148:151], v[192:195], v[26:29]
	v_mfma_f32_16x16x32_bf16 v[26:29], v[152:155], v[196:199], v[26:29]
	v_mfma_f32_16x16x32_bf16 v[14:17], v[130:133], v[200:203], v[14:17]
	v_mfma_f32_16x16x32_bf16 v[14:17], v[134:137], v[204:207], v[14:17]
	v_mfma_f32_16x16x32_bf16 v[10:13], v[148:151], v[200:203], v[10:13]
	v_mfma_f32_16x16x32_bf16 v[10:13], v[152:155], v[204:207], v[10:13]
	v_mfma_f32_16x16x32_bf16 v[54:57], v[156:159], v[172:175], v[54:57]
	v_mfma_f32_16x16x32_bf16 v[54:57], v[160:163], v[180:183], v[54:57]
	v_mfma_f32_16x16x32_bf16 v[50:53], v[164:167], v[172:175], v[50:53]
	v_mfma_f32_16x16x32_bf16 v[50:53], v[168:171], v[180:183], v[50:53]
	v_mfma_f32_16x16x32_bf16 v[38:41], v[156:159], v[184:187], v[38:41]
	v_mfma_f32_16x16x32_bf16 v[38:41], v[160:163], v[188:191], v[38:41]
	v_mfma_f32_16x16x32_bf16 v[34:37], v[164:167], v[184:187], v[34:37]
	v_mfma_f32_16x16x32_bf16 v[34:37], v[168:171], v[188:191], v[34:37]
	v_mfma_f32_16x16x32_bf16 v[22:25], v[156:159], v[192:195], v[22:25]
	v_mfma_f32_16x16x32_bf16 v[22:25], v[160:163], v[196:199], v[22:25]
	v_mfma_f32_16x16x32_bf16 v[18:21], v[164:167], v[192:195], v[18:21]
	v_mfma_f32_16x16x32_bf16 v[18:21], v[168:171], v[196:199], v[18:21]
	v_mfma_f32_16x16x32_bf16 v[6:9], v[156:159], v[200:203], v[6:9]
	v_mfma_f32_16x16x32_bf16 v[6:9], v[160:163], v[204:207], v[6:9]
	v_mfma_f32_16x16x32_bf16 v[2:5], v[164:167], v[200:203], v[2:5]
	v_mfma_f32_16x16x32_bf16 v[2:5], v[168:171], v[204:207], v[2:5]
	s_barrier
	s_setprio 0
	s_add_u32 s77, s77, 0x100
	s_addc_u32 s78, s78, 0
	s_cmp_ge_i32 s79, s75
	s_mov_b64 s[36:37], s[38:39]
	s_mov_b32 s46, s79
	s_cbranch_scc0 .LBB0_1893
	v_readlane_b32 s2, v252, 14
	v_readlane_b32 s3, v252, 15
	s_and_b64 vcc, exec, s[2:3]
	s_cbranch_vccz .LBB0_1896
	s_barrier

; #define PG8_STAGE(bufoff, gbase, voff) do { _Pragma("unroll") for (int _i = 0; _i < 2; ++_i) \
;         __builtin_amdgcn_global_load_lds((const unsigned*)((const char*)(gbase) + (voff)[_i]), (LAS unsigned*)(lds + (bufoff) + ldsw + _i * 8192), 16, 0, 0); } while (0)
; #define PG8_LDA(dst, b, h) do { _Pragma("unroll") for (int m = 0; m < 4; ++m) _Pragma("unroll") for (int k = 0; k < 2; ++k) dst[m][k] = *(const LAS bf16x8*)(lds + PG8_SA(b, h) + aoff + m * 2048 + k * 1024); } while (0)
; #define PG8_LDB(dst, b, h) do { _Pragma("unroll") for (int n = 0; n < 2; ++n) _Pragma("unroll") for (int k = 0; k < 2; ++k) dst[n][k] = *(const LAS bf16x8*)(lds + PG8_SB(b, h) + boff + n * 2048 + k * 1024); } while (0)
; #define PG8_MMA(ai, bj, At, Bt) do { __builtin_amdgcn_s_setprio(1); _Pragma("unroll") for (int m = 0; m < 4; ++m) _Pragma("unroll") for (int n = 0; n < 2; ++n) _Pragma("unroll") for (int k = 0; k < 2; ++k) \
;         acc[ai][bj][m][n] = __builtin_amdgcn_mfma_f32_16x16x32_bf16(Bt[n][k], At[m][k], acc[ai][bj][m][n], 0, 0, 0); __builtin_amdgcn_s_setprio(0); } while (0)
; #define PG8_WAIT_V(n) asm volatile("s_waitcnt vmcnt(" #n ")" ::: "memory")
; #define PG8_WAIT_L(n) asm volatile("s_waitcnt lgkmcnt(" #n ")" ::: "memory")
; #define PG8_BAR __builtin_amdgcn_s_barrier()
; #define PG8_SCHED __builtin_amdgcn_sched_barrier(0)
; template <class Epi, class Sched, int LDA, int LDB, bool ALIGN_EPI = true>
; __device__ __forceinline__ void gemm_phase(LAS unsigned char* lds, const Gemm g, const Sched& S, const Epi& E, int wave) {
;     ...
;             PG8_LDB(B0, 0, 0); PG8_LDB(B1, 0, 1); PG8_SCHED; PG8_LDA(At, 0, 0); PG8_STAGE(PG8_SA(1, 1), a1 + hstepA, voffA);
;             PG8_WAIT_V(8); PG8_WAIT_L(0); PG8_BAR; PG8_MMA(0, 0, At, B0); PG8_MMA(0, 1, At, B1); PG8_BAR; PG8_SCHED;
;             PG8_LDA(At, 0, 1); PG8_STAGE(PG8_SB(0, 0), b2, voffB); PG8_STAGE(PG8_SB(0, 1), b2 + hstepB, voffB); PG8_STAGE(PG8_SA(0, 0), a2, voffA);
;             PG8_WAIT_V(8); PG8_WAIT_L(0); PG8_BAR; PG8_MMA(1, 0, At, B0); PG8_MMA(1, 1, At, B1); PG8_BAR; PG8_SCHED;
.LBB0_2254:
	s_add_u32 s2, s0, 0x100
	s_addc_u32 s3, s1, 0
	s_add_i32 s64, 0, 0x10000
	s_cmp_eq_u32 s59, 28
	s_cselect_b32 s29, s15, s3
	s_cselect_b32 s28, s14, s2
	v_add_u32_e32 v0, s64, v161
	s_cselect_b32 s25, s13, s58
	s_cselect_b32 s24, s48, s49
	s_add_i32 s65, 0, 0x14000
	ds_read_b128 v[144:147], v0
	ds_read_b128 v[148:151], v0 offset:1024
	ds_read_b128 v[152:155], v0 offset:2048
	ds_read_b128 v[156:159], v0 offset:3072
	v_add_u32_e32 v0, s65, v161
	ds_read_b128 v[164:167], v0
	ds_read_b128 v[168:171], v0 offset:1024
	ds_read_b128 v[172:175], v0 offset:2048
	ds_read_b128 v[180:183], v0 offset:3072
	v_lshl_add_u64 v[216:217], s[0:1], 0, v[140:141]
	s_add_i32 m0, s19, 0xc000
	ds_read_b128 v[184:187], v163
	ds_read_b128 v[188:191], v163 offset:1024
	ds_read_b128 v[192:195], v163 offset:2048
	ds_read_b128 v[196:199], v163 offset:3072
	ds_read_b128 v[200:203], v163 offset:4096
	ds_read_b128 v[204:207], v163 offset:5120
	ds_read_b128 v[208:211], v163 offset:6144
	ds_read_b128 v[212:215], v163 offset:7168
	global_load_lds_dwordx4 v[216:217], off
	v_lshl_add_u64 v[216:217], s[0:1], 0, v[142:143]
	s_add_i32 m0, s19, 0xe000
	s_nop 0
	global_load_lds_dwordx4 v[216:217], off
	s_waitcnt vmcnt(8)
	s_waitcnt lgkmcnt(0)
	s_setprio 1
	s_barrier
	v_mfma_f32_16x16x32_bf16 v[126:129], v[144:147], v[184:187], v[126:129]
	v_mfma_f32_16x16x32_bf16 v[126:129], v[148:151], v[188:191], v[126:129]
	v_mfma_f32_16x16x32_bf16 v[122:125], v[152:155], v[184:187], v[122:125]
	v_mfma_f32_16x16x32_bf16 v[122:125], v[156:159], v[188:191], v[122:125]
	v_mfma_f32_16x16x32_bf16 v[118:121], v[144:147], v[192:195], v[118:121]
	v_mfma_f32_16x16x32_bf16 v[118:121], v[148:151], v[196:199], v[118:121]
	v_mfma_f32_16x16x32_bf16 v[114:117], v[152:155], v[192:195], v[114:117]
	v_mfma_f32_16x16x32_bf16 v[114:117], v[156:159], v[196:199], v[114:117]
	v_mfma_f32_16x16x32_bf16 v[110:113], v[144:147], v[200:203], v[110:113]
	v_mfma_f32_16x16x32_bf16 v[110:113], v[148:151], v[204:207], v[110:113]
	v_mfma_f32_16x16x32_bf16 v[106:109], v[152:155], v[200:203], v[106:109]
	v_mfma_f32_16x16x32_bf16 v[106:109], v[156:159], v[204:207], v[106:109]
	v_mfma_f32_16x16x32_bf16 v[102:105], v[144:147], v[208:211], v[102:105]
	v_mfma_f32_16x16x32_bf16 v[102:105], v[148:151], v[212:215], v[102:105]
	v_mfma_f32_16x16x32_bf16 v[98:101], v[152:155], v[208:211], v[98:101]
	v_mfma_f32_16x16x32_bf16 v[98:101], v[156:159], v[212:215], v[98:101]
	v_mfma_f32_16x16x32_bf16 v[62:65], v[164:167], v[184:187], v[62:65]
	v_mfma_f32_16x16x32_bf16 v[62:65], v[168:171], v[188:191], v[62:65]
	v_mfma_f32_16x16x32_bf16 v[58:61], v[172:175], v[184:187], v[58:61]
	v_mfma_f32_16x16x32_bf16 v[58:61], v[180:183], v[188:191], v[58:61]
	v_mfma_f32_16x16x32_bf16 v[54:57], v[164:167], v[192:195], v[54:57]
	v_mfma_f32_16x16x32_bf16 v[54:57], v[168:171], v[196:199], v[54:57]
	v_mfma_f32_16x16x32_bf16 v[50:53], v[172:175], v[192:195], v[50:53]
	v_mfma_f32_16x16x32_bf16 v[50:53], v[180:183], v[196:199], v[50:53]
	v_mfma_f32_16x16x32_bf16 v[46:49], v[164:167], v[200:203], v[46:49]
	v_mfma_f32_16x16x32_bf16 v[46:49], v[168:171], v[204:207], v[46:49]
	v_mfma_f32_16x16x32_bf16 v[42:45], v[172:175], v[200:203], v[42:45]
	v_mfma_f32_16x16x32_bf16 v[42:45], v[180:183], v[204:207], v[42:45]
	v_mfma_f32_16x16x32_bf16 v[38:41], v[164:167], v[208:211], v[38:41]
	v_mfma_f32_16x16x32_bf16 v[38:41], v[168:171], v[212:215], v[38:41]
	v_mfma_f32_16x16x32_bf16 v[34:37], v[172:175], v[208:211], v[34:37]
	v_mfma_f32_16x16x32_bf16 v[34:37], v[180:183], v[212:215], v[34:37]
	s_barrier
	s_setprio 0
	s_add_i32 s0, s64, s61
	v_lshl_add_u64 v[216:217], s[24:25], 0, v[132:133]
	s_mov_b32 m0, s0
	ds_read_b128 v[184:187], v163 offset:16384
	ds_read_b128 v[188:191], v163 offset:17408
	ds_read_b128 v[192:195], v163 offset:18432
	ds_read_b128 v[196:199], v163 offset:19456
	ds_read_b128 v[200:203], v163 offset:20480
	ds_read_b128 v[204:207], v163 offset:21504
	ds_read_b128 v[208:211], v163 offset:22528
	ds_read_b128 v[212:215], v163 offset:23552
	global_load_lds_dwordx4 v[216:217], off
	s_add_i32 m0, s0, 0x2000
	s_add_u32 s0, s24, 0x80000
	v_lshl_add_u64 v[218:219], s[24:25], 0, v[136:137]
	s_addc_u32 s1, s25, 0
	s_add_i32 s64, s65, s61
	global_load_lds_dwordx4 v[218:219], off
	v_lshl_add_u64 v[220:221], s[0:1], 0, v[132:133]
	s_mov_b32 m0, s64
	v_lshl_add_u64 v[222:223], s[28:29], 0, v[134:135]
	global_load_lds_dwordx4 v[220:221], off
	v_lshl_add_u64 v[220:221], s[0:1], 0, v[136:137]
	s_add_i32 m0, s64, 0x2000
	s_nop 0
	global_load_lds_dwordx4 v[220:221], off
	v_lshl_add_u64 v[220:221], s[28:29], 0, v[130:131]
	s_mov_b32 m0, s19
	s_nop 0
	global_load_lds_dwordx4 v[220:221], off
	s_mov_b32 m0, s35
	s_nop 0
	global_load_lds_dwordx4 v[222:223], off
	s_waitcnt vmcnt(8)
	s_waitcnt lgkmcnt(0)
	s_setprio 1
	s_barrier
; #define PG8_STAGE(bufoff, gbase, voff) do { _Pragma("unroll") for (int _i = 0; _i < 2; ++_i) \
;         __builtin_amdgcn_global_load_lds((const unsigned*)((const char*)(gbase) + (voff)[_i]), (LAS unsigned*)(lds + (bufoff) + ldsw + _i * 8192), 16, 0, 0); } while (0)
; #define PG8_LDA(dst, b, h) do { _Pragma("unroll") for (int m = 0; m < 4; ++m) _Pragma("unroll") for (int k = 0; k < 2; ++k) dst[m][k] = *(const LAS bf16x8*)(lds + PG8_SA(b, h) + aoff + m * 2048 + k * 1024); } while (0)
; #define PG8_LDB(dst, b, h) do { _Pragma("unroll") for (int n = 0; n < 2; ++n) _Pragma("unroll") for (int k = 0; k < 2; ++k) dst[n][k] = *(const LAS bf16x8*)(lds + PG8_SB(b, h) + boff + n * 2048 + k * 1024); } while (0)
; #define PG8_MMA(ai, bj, At, Bt) do { __builtin_amdgcn_s_setprio(1); _Pragma("unroll") for (int m = 0; m < 4; ++m) _Pragma("unroll") for (int n = 0; n < 2; ++n) _Pragma("unroll") for (int k = 0; k < 2; ++k) \
;         acc[ai][bj][m][n] = __builtin_amdgcn_mfma_f32_16x16x32_bf16(Bt[n][k], At[m][k], acc[ai][bj][m][n], 0, 0, 0); __builtin_amdgcn_s_setprio(0); } while (0)
; #define PG8_WAIT_V(n) asm volatile("s_waitcnt vmcnt(" #n ")" ::: "memory")
; #define PG8_WAIT_L(n) asm volatile("s_waitcnt lgkmcnt(" #n ")" ::: "memory")
; #define PG8_BAR __builtin_amdgcn_s_barrier()
; #define PG8_SCHED __builtin_amdgcn_sched_barrier(0)
; template <class Epi, class Sched, int LDA, int LDB, bool ALIGN_EPI = true>
; __device__ __forceinline__ void gemm_phase(LAS unsigned char* lds, const Gemm g, const Sched& S, const Epi& E, int wave) {
;     ...
;             PG8_WAIT_V(8); PG8_WAIT_L(0); PG8_BAR; PG8_MMA(1, 0, At, B0); PG8_MMA(1, 1, At, B1); PG8_BAR; PG8_SCHED;
;             PG8_LDB(B0, 1, 0); PG8_LDB(B1, 1, 1); PG8_SCHED; PG8_LDA(At, 1, 0); PG8_STAGE(PG8_SA(0, 1), a2 + hstepA, voffA);
;             PG8_WAIT_V(8); PG8_WAIT_L(0); PG8_BAR; PG8_MMA(0, 0, At, B0); PG8_MMA(0, 1, At, B1); PG8_BAR; PG8_SCHED;
	v_mfma_f32_16x16x32_bf16 v[94:97], v[144:147], v[184:187], v[94:97]
	v_mfma_f32_16x16x32_bf16 v[94:97], v[148:151], v[188:191], v[94:97]
	v_mfma_f32_16x16x32_bf16 v[90:93], v[152:155], v[184:187], v[90:93]
	v_mfma_f32_16x16x32_bf16 v[90:93], v[156:159], v[188:191], v[90:93]
	v_mfma_f32_16x16x32_bf16 v[86:89], v[144:147], v[192:195], v[86:89]
	v_mfma_f32_16x16x32_bf16 v[86:89], v[148:151], v[196:199], v[86:89]
	v_mfma_f32_16x16x32_bf16 v[82:85], v[152:155], v[192:195], v[82:85]
	v_mfma_f32_16x16x32_bf16 v[82:85], v[156:159], v[196:199], v[82:85]
	v_mfma_f32_16x16x32_bf16 v[78:81], v[144:147], v[200:203], v[78:81]
	v_mfma_f32_16x16x32_bf16 v[78:81], v[148:151], v[204:207], v[78:81]
	v_mfma_f32_16x16x32_bf16 v[74:77], v[152:155], v[200:203], v[74:77]
	v_mfma_f32_16x16x32_bf16 v[74:77], v[156:159], v[204:207], v[74:77]
	v_mfma_f32_16x16x32_bf16 v[70:73], v[144:147], v[208:211], v[70:73]
	v_mfma_f32_16x16x32_bf16 v[70:73], v[148:151], v[212:215], v[70:73]
	v_mfma_f32_16x16x32_bf16 v[66:69], v[152:155], v[208:211], v[66:69]
	v_mfma_f32_16x16x32_bf16 v[66:69], v[156:159], v[212:215], v[66:69]
	v_mfma_f32_16x16x32_bf16 v[30:33], v[164:167], v[184:187], v[30:33]
	v_mfma_f32_16x16x32_bf16 v[30:33], v[168:171], v[188:191], v[30:33]
	v_mfma_f32_16x16x32_bf16 v[26:29], v[172:175], v[184:187], v[26:29]
	v_mfma_f32_16x16x32_bf16 v[26:29], v[180:183], v[188:191], v[26:29]
	v_mfma_f32_16x16x32_bf16 v[22:25], v[164:167], v[192:195], v[22:25]
	v_mfma_f32_16x16x32_bf16 v[22:25], v[168:171], v[196:199], v[22:25]
	v_mfma_f32_16x16x32_bf16 v[18:21], v[172:175], v[192:195], v[18:21]
	v_mfma_f32_16x16x32_bf16 v[18:21], v[180:183], v[196:199], v[18:21]
	v_mfma_f32_16x16x32_bf16 v[14:17], v[164:167], v[200:203], v[14:17]
	v_mfma_f32_16x16x32_bf16 v[14:17], v[168:171], v[204:207], v[14:17]
	v_mfma_f32_16x16x32_bf16 v[10:13], v[172:175], v[200:203], v[10:13]
	v_mfma_f32_16x16x32_bf16 v[10:13], v[180:183], v[204:207], v[10:13]
	v_mfma_f32_16x16x32_bf16 v[6:9], v[164:167], v[208:211], v[6:9]
	v_mfma_f32_16x16x32_bf16 v[6:9], v[168:171], v[212:215], v[6:9]
	v_mfma_f32_16x16x32_bf16 v[2:5], v[172:175], v[208:211], v[2:5]
	v_mfma_f32_16x16x32_bf16 v[2:5], v[180:183], v[212:215], v[2:5]
	s_barrier
	s_setprio 0
	s_add_i32 s64, 0, 0x18000
	v_add_u32_e32 v0, s64, v161
	s_add_i32 s65, 0, 0x1c000
	ds_read_b128 v[144:147], v0
	ds_read_b128 v[148:151], v0 offset:1024
	ds_read_b128 v[152:155], v0 offset:2048
	ds_read_b128 v[156:159], v0 offset:3072
	v_add_u32_e32 v0, s65, v161
	ds_read_b128 v[164:167], v0
	ds_read_b128 v[168:171], v0 offset:1024
	ds_read_b128 v[172:175], v0 offset:2048
	ds_read_b128 v[180:183], v0 offset:3072
	s_add_u32 s0, s28, 0x84000
	s_addc_u32 s1, s29, 0
	s_mov_b32 m0, s36
	v_lshl_add_u64 v[224:225], s[0:1], 0, v[130:131]
	ds_read_b128 v[184:187], v163 offset:32768
	ds_read_b128 v[188:191], v163 offset:33792
	ds_read_b128 v[192:195], v163 offset:34816
	ds_read_b128 v[196:199], v163 offset:35840
	ds_read_b128 v[200:203], v163 offset:36864
	ds_read_b128 v[204:207], v163 offset:37888
	ds_read_b128 v[208:211], v163 offset:38912
	ds_read_b128 v[212:215], v163 offset:39936
	global_load_lds_dwordx4 v[224:225], off
	v_lshl_add_u64 v[224:225], s[0:1], 0, v[134:135]
	s_mov_b32 m0, s37
	s_nop 0
	global_load_lds_dwordx4 v[224:225], off
	s_waitcnt vmcnt(8)
	s_waitcnt lgkmcnt(0)
	s_setprio 1
	s_barrier
	v_mfma_f32_16x16x32_bf16 v[126:129], v[144:147], v[184:187], v[126:129]
	v_mfma_f32_16x16x32_bf16 v[126:129], v[148:151], v[188:191], v[126:129]
	v_mfma_f32_16x16x32_bf16 v[122:125], v[152:155], v[184:187], v[122:125]
	v_mfma_f32_16x16x32_bf16 v[122:125], v[156:159], v[188:191], v[122:125]
	v_mfma_f32_16x16x32_bf16 v[118:121], v[144:147], v[192:195], v[118:121]
	v_mfma_f32_16x16x32_bf16 v[118:121], v[148:151], v[196:199], v[118:121]
	v_mfma_f32_16x16x32_bf16 v[114:117], v[152:155], v[192:195], v[114:117]
	v_mfma_f32_16x16x32_bf16 v[114:117], v[156:159], v[196:199], v[114:117]
	v_mfma_f32_16x16x32_bf16 v[110:113], v[144:147], v[200:203], v[110:113]
	v_mfma_f32_16x16x32_bf16 v[110:113], v[148:151], v[204:207], v[110:113]
	v_mfma_f32_16x16x32_bf16 v[106:109], v[152:155], v[200:203], v[106:109]
	v_mfma_f32_16x16x32_bf16 v[106:109], v[156:159], v[204:207], v[106:109]
	v_mfma_f32_16x16x32_bf16 v[102:105], v[144:147], v[208:211], v[102:105]
	v_mfma_f32_16x16x32_bf16 v[102:105], v[148:151], v[212:215], v[102:105]
	v_mfma_f32_16x16x32_bf16 v[98:101], v[152:155], v[208:211], v[98:101]
	v_mfma_f32_16x16x32_bf16 v[98:101], v[156:159], v[212:215], v[98:101]
	v_mfma_f32_16x16x32_bf16 v[62:65], v[164:167], v[184:187], v[62:65]
	v_mfma_f32_16x16x32_bf16 v[62:65], v[168:171], v[188:191], v[62:65]
	v_mfma_f32_16x16x32_bf16 v[58:61], v[172:175], v[184:187], v[58:61]
	v_mfma_f32_16x16x32_bf16 v[58:61], v[180:183], v[188:191], v[58:61]
	v_mfma_f32_16x16x32_bf16 v[54:57], v[164:167], v[192:195], v[54:57]
	v_mfma_f32_16x16x32_bf16 v[54:57], v[168:171], v[196:199], v[54:57]
	v_mfma_f32_16x16x32_bf16 v[50:53], v[172:175], v[192:195], v[50:53]
	v_mfma_f32_16x16x32_bf16 v[50:53], v[180:183], v[196:199], v[50:53]
	v_mfma_f32_16x16x32_bf16 v[46:49], v[164:167], v[200:203], v[46:49]
	v_mfma_f32_16x16x32_bf16 v[46:49], v[168:171], v[204:207], v[46:49]
	v_mfma_f32_16x16x32_bf16 v[42:45], v[172:175], v[200:203], v[42:45]
	v_mfma_f32_16x16x32_bf16 v[42:45], v[180:183], v[204:207], v[42:45]
	v_mfma_f32_16x16x32_bf16 v[38:41], v[164:167], v[208:211], v[38:41]
	v_mfma_f32_16x16x32_bf16 v[38:41], v[168:171], v[212:215], v[38:41]
	v_mfma_f32_16x16x32_bf16 v[34:37], v[172:175], v[208:211], v[34:37]
	v_mfma_f32_16x16x32_bf16 v[34:37], v[180:183], v[212:215], v[34:37]
	s_barrier
; #define PG8_STAGE(bufoff, gbase, voff) do { _Pragma("unroll") for (int _i = 0; _i < 2; ++_i) \
;         __builtin_amdgcn_global_load_lds((const unsigned*)((const char*)(gbase) + (voff)[_i]), (LAS unsigned*)(lds + (bufoff) + ldsw + _i * 8192), 16, 0, 0); } while (0)
; #define PG8_LDA(dst, b, h) do { _Pragma("unroll") for (int m = 0; m < 4; ++m) _Pragma("unroll") for (int k = 0; k < 2; ++k) dst[m][k] = *(const LAS bf16x8*)(lds + PG8_SA(b, h) + aoff + m * 2048 + k * 1024); } while (0)
; #define PG8_MMA(ai, bj, At, Bt) do { __builtin_amdgcn_s_setprio(1); _Pragma("unroll") for (int m = 0; m < 4; ++m) _Pragma("unroll") for (int n = 0; n < 2; ++n) _Pragma("unroll") for (int k = 0; k < 2; ++k) \
;         acc[ai][bj][m][n] = __builtin_amdgcn_mfma_f32_16x16x32_bf16(Bt[n][k], At[m][k], acc[ai][bj][m][n], 0, 0, 0); __builtin_amdgcn_s_setprio(0); } while (0)
; #define PG8_WAIT_V(n) asm volatile("s_waitcnt vmcnt(" #n ")" ::: "memory")
; #define PG8_WAIT_L(n) asm volatile("s_waitcnt lgkmcnt(" #n ")" ::: "memory")
; #define PG8_BAR __builtin_amdgcn_s_barrier()
; #define PG8_SCHED __builtin_amdgcn_sched_barrier(0)
; template <class Epi, class Sched, int LDA, int LDB, bool ALIGN_EPI = true>
; __device__ __forceinline__ void gemm_phase(LAS unsigned char* lds, const Gemm g, const Sched& S, const Epi& E, int wave) {
;     ...
;             PG8_LDA(At, 1, 1); PG8_STAGE(PG8_SB(1, 0), b3, voffB); PG8_STAGE(PG8_SB(1, 1), b3 + hstepB, voffB); PG8_STAGE(PG8_SA(1, 0), a3, voffA);
;             PG8_WAIT_V(8); PG8_WAIT_L(0); PG8_BAR; PG8_MMA(1, 0, At, B0); PG8_MMA(1, 1, At, B1); PG8_BAR; PG8_SCHED;
;         }
	s_setprio 0
	s_add_i32 s0, s64, s61
	v_lshl_add_u64 v[216:217], v[216:217], 0, s[70:71]
	s_mov_b32 m0, s0
	ds_read_b128 v[184:187], v163 offset:49152
	ds_read_b128 v[188:191], v163 offset:50176
	ds_read_b128 v[192:195], v163 offset:51200
	ds_read_b128 v[196:199], v163 offset:52224
	ds_read_b128 v[200:203], v163 offset:53248
	ds_read_b128 v[204:207], v163 offset:54272
	ds_read_b128 v[208:211], v163 offset:55296
	ds_read_b128 v[212:215], v163 offset:56320
	global_load_lds_dwordx4 v[216:217], off
	s_add_i32 m0, s0, 0x2000
	s_add_u32 s0, s24, 0x80080
	v_lshl_add_u64 v[216:217], v[218:219], 0, s[70:71]
	s_addc_u32 s1, s25, 0
	s_add_i32 s24, s65, s61
	global_load_lds_dwordx4 v[216:217], off
	v_lshl_add_u64 v[216:217], s[0:1], 0, v[132:133]
	s_mov_b32 m0, s24
	s_nop 0
	global_load_lds_dwordx4 v[216:217], off
	v_lshl_add_u64 v[216:217], s[0:1], 0, v[136:137]
	s_add_i32 m0, s24, 0x2000
	s_nop 0
	global_load_lds_dwordx4 v[216:217], off
	v_lshl_add_u64 v[216:217], v[220:221], 0, s[70:71]
	s_mov_b32 m0, s38
	s_nop 0
	global_load_lds_dwordx4 v[216:217], off
	v_lshl_add_u64 v[216:217], v[222:223], 0, s[70:71]
	s_mov_b32 m0, s39
	s_nop 0
	global_load_lds_dwordx4 v[216:217], off
	s_waitcnt vmcnt(8)
	s_waitcnt lgkmcnt(0)
	s_setprio 1
	s_barrier
	v_mfma_f32_16x16x32_bf16 v[94:97], v[144:147], v[184:187], v[94:97]
	v_mfma_f32_16x16x32_bf16 v[94:97], v[148:151], v[188:191], v[94:97]
	v_mfma_f32_16x16x32_bf16 v[90:93], v[152:155], v[184:187], v[90:93]
	v_mfma_f32_16x16x32_bf16 v[90:93], v[156:159], v[188:191], v[90:93]
	v_mfma_f32_16x16x32_bf16 v[86:89], v[144:147], v[192:195], v[86:89]
	v_mfma_f32_16x16x32_bf16 v[86:89], v[148:151], v[196:199], v[86:89]
	v_mfma_f32_16x16x32_bf16 v[82:85], v[152:155], v[192:195], v[82:85]
	v_mfma_f32_16x16x32_bf16 v[82:85], v[156:159], v[196:199], v[82:85]
	v_mfma_f32_16x16x32_bf16 v[78:81], v[144:147], v[200:203], v[78:81]
	v_mfma_f32_16x16x32_bf16 v[78:81], v[148:151], v[204:207], v[78:81]
	v_mfma_f32_16x16x32_bf16 v[74:77], v[152:155], v[200:203], v[74:77]
	v_mfma_f32_16x16x32_bf16 v[74:77], v[156:159], v[204:207], v[74:77]
	v_mfma_f32_16x16x32_bf16 v[70:73], v[144:147], v[208:211], v[70:73]
	v_mfma_f32_16x16x32_bf16 v[70:73], v[148:151], v[212:215], v[70:73]
	v_mfma_f32_16x16x32_bf16 v[66:69], v[152:155], v[208:211], v[66:69]
	v_mfma_f32_16x16x32_bf16 v[66:69], v[156:159], v[212:215], v[66:69]
	v_mfma_f32_16x16x32_bf16 v[30:33], v[164:167], v[184:187], v[30:33]
	v_mfma_f32_16x16x32_bf16 v[30:33], v[168:171], v[188:191], v[30:33]
	v_mfma_f32_16x16x32_bf16 v[26:29], v[172:175], v[184:187], v[26:29]
	v_mfma_f32_16x16x32_bf16 v[26:29], v[180:183], v[188:191], v[26:29]
	v_mfma_f32_16x16x32_bf16 v[22:25], v[164:167], v[192:195], v[22:25]
	v_mfma_f32_16x16x32_bf16 v[22:25], v[168:171], v[196:199], v[22:25]
	v_mfma_f32_16x16x32_bf16 v[18:21], v[172:175], v[192:195], v[18:21]
	v_mfma_f32_16x16x32_bf16 v[18:21], v[180:183], v[196:199], v[18:21]
	v_mfma_f32_16x16x32_bf16 v[14:17], v[164:167], v[200:203], v[14:17]
	v_mfma_f32_16x16x32_bf16 v[14:17], v[168:171], v[204:207], v[14:17]
	v_mfma_f32_16x16x32_bf16 v[10:13], v[172:175], v[200:203], v[10:13]
	v_mfma_f32_16x16x32_bf16 v[10:13], v[180:183], v[204:207], v[10:13]
	v_mfma_f32_16x16x32_bf16 v[6:9], v[164:167], v[208:211], v[6:9]
	v_mfma_f32_16x16x32_bf16 v[6:9], v[168:171], v[212:215], v[6:9]
	v_mfma_f32_16x16x32_bf16 v[2:5], v[172:175], v[208:211], v[2:5]
	v_mfma_f32_16x16x32_bf16 v[2:5], v[180:183], v[212:215], v[2:5]
	s_barrier
	s_setprio 0
	s_add_i32 s59, s59, 2
	s_add_u32 s49, s49, 0x100
	s_addc_u32 s58, s58, 0
	s_cmp_gt_u32 s59, 29
	s_mov_b64 s[0:1], s[2:3]
	s_cbranch_scc0 .LBB0_2254
	v_readlane_b32 s0, v252, 14
	v_readlane_b32 s1, v252, 15
	s_and_b64 vcc, exec, s[0:1]
	s_cbranch_vccz .LBB0_2257
	s_barrier

; #define PG8_STAGE(bufoff, gbase, voff) do { _Pragma("unroll") for (int _i = 0; _i < 2; ++_i) \
;         __builtin_amdgcn_global_load_lds((const unsigned*)((const char*)(gbase) + (voff)[_i]), (LAS unsigned*)(lds + (bufoff) + ldsw + _i * 8192), 16, 0, 0); } while (0)
; #define PG8_LDA(dst, b, h) do { _Pragma("unroll") for (int m = 0; m < 4; ++m) _Pragma("unroll") for (int k = 0; k < 2; ++k) dst[m][k] = *(const LAS bf16x8*)(lds + PG8_SA(b, h) + aoff + m * 2048 + k * 1024); } while (0)
; #define PG8_LDB(dst, b, h) do { _Pragma("unroll") for (int n = 0; n < 2; ++n) _Pragma("unroll") for (int k = 0; k < 2; ++k) dst[n][k] = *(const LAS bf16x8*)(lds + PG8_SB(b, h) + boff + n * 2048 + k * 1024); } while (0)
; #define PG8_MMA(ai, bj, At, Bt) do { __builtin_amdgcn_s_setprio(1); _Pragma("unroll") for (int m = 0; m < 4; ++m) _Pragma("unroll") for (int n = 0; n < 2; ++n) _Pragma("unroll") for (int k = 0; k < 2; ++k) \
;         acc[ai][bj][m][n] = __builtin_amdgcn_mfma_f32_16x16x32_bf16(Bt[n][k], At[m][k], acc[ai][bj][m][n], 0, 0, 0); __builtin_amdgcn_s_setprio(0); } while (0)
; #define PG8_WAIT_V(n) asm volatile("s_waitcnt vmcnt(" #n ")" ::: "memory")
; template <class Epi, class Sched, int LDA, int LDB, bool ALIGN_EPI = true>
; __device__ __forceinline__ void gemm_phase(LAS unsigned char* lds, const Gemm g, const Sched& S, const Epi& E, int wave) {
;     ...
;         for (int t = 0; t < nt; t += 2) {
;             const bool last = (t == nt - 2);
;             const char* a1 = cA + (size_t)(t + 1) * kstep;
;             const char* a2 = last ? nA : cA + (size_t)(t + 2) * kstep; const char* b2 = last ? nB : cB + (size_t)(t + 2) * kstep;
;             const char* a3 = a2 + kstep; const char* b3 = b2 + kstep;
;             PG8_LDB(B0, 0, 0); PG8_LDB(B1, 0, 1); PG8_SCHED; PG8_LDA(At, 0, 0); PG8_STAGE(PG8_SA(1, 1), a1 + hstepA, voffA);
;             PG8_WAIT_V(8); PG8_WAIT_L(0); PG8_BAR; PG8_MMA(0, 0, At, B0); PG8_MMA(0, 1, At, B1); PG8_BAR; PG8_SCHED;
;             PG8_LDA(At, 0, 1); PG8_STAGE(PG8_SB(0, 0), b2, voffB); PG8_STAGE(PG8_SB(0, 1), b2 + hstepB, voffB); PG8_STAGE(PG8_SA(0, 0), a2, voffA);
;             PG8_WAIT_V(8); PG8_WAIT_L(0); PG8_BAR; PG8_MMA(1, 0, At, B0); PG8_MMA(1, 1, At, B1); PG8_BAR; PG8_SCHED;
;             PG8_LDB(B0, 1, 0); PG8_LDB(B1, 1, 1); PG8_SCHED; PG8_LDA(At, 1, 0); PG8_STAGE(PG8_SA(0, 1), a2 + hstepA, voffA);
.LBB0_2415:
	s_add_u32 s12, s10, 0xfff80080
	s_addc_u32 s13, s11, -1
	s_add_i32 s39, 0, 0x10000
	s_cmp_eq_u32 s38, 28
	s_cselect_b32 s15, s1, s13
	s_cselect_b32 s14, s3, s12
	v_add_u32_e32 v140, s39, v143
	s_cselect_b32 s13, s7, s37
	s_cselect_b32 s12, s6, s36
	s_add_i32 s46, 0, 0x14000
	ds_read_b128 v[146:149], v140
	ds_read_b128 v[150:153], v140 offset:1024
	ds_read_b128 v[154:157], v140 offset:2048
	ds_read_b128 v[158:161], v140 offset:3072
	v_add_u32_e32 v140, s46, v143
	ds_read_b128 v[162:165], v140
	ds_read_b128 v[166:169], v140 offset:1024
	ds_read_b128 v[170:173], v140 offset:2048
	ds_read_b128 v[180:183], v140 offset:3072
	v_lshl_add_u64 v[140:141], s[10:11], 0, v[136:137]
	s_add_i32 m0, s18, 0xc000
	ds_read_b128 v[184:187], v145
	ds_read_b128 v[188:191], v145 offset:1024
	ds_read_b128 v[192:195], v145 offset:2048
	ds_read_b128 v[196:199], v145 offset:3072
	ds_read_b128 v[200:203], v145 offset:4096
	ds_read_b128 v[204:207], v145 offset:5120
	ds_read_b128 v[208:211], v145 offset:6144
	ds_read_b128 v[212:215], v145 offset:7168
	global_load_lds_dwordx4 v[140:141], off
	v_lshl_add_u64 v[140:141], s[10:11], 0, v[138:139]
	s_add_i32 m0, s18, 0xe000
	s_nop 0
	global_load_lds_dwordx4 v[140:141], off
	s_waitcnt vmcnt(8)
	s_waitcnt lgkmcnt(0)
	s_setprio 1
	s_barrier
	v_mfma_f32_16x16x32_bf16 v[126:129], v[146:149], v[184:187], v[126:129]
	v_mfma_f32_16x16x32_bf16 v[126:129], v[150:153], v[188:191], v[126:129]
	v_mfma_f32_16x16x32_bf16 v[122:125], v[154:157], v[184:187], v[122:125]
	v_mfma_f32_16x16x32_bf16 v[122:125], v[158:161], v[188:191], v[122:125]
	v_mfma_f32_16x16x32_bf16 v[114:117], v[146:149], v[192:195], v[114:117]
	v_mfma_f32_16x16x32_bf16 v[114:117], v[150:153], v[196:199], v[114:117]
	v_mfma_f32_16x16x32_bf16 v[106:109], v[154:157], v[192:195], v[106:109]
	v_mfma_f32_16x16x32_bf16 v[106:109], v[158:161], v[196:199], v[106:109]
	v_mfma_f32_16x16x32_bf16 v[98:101], v[146:149], v[200:203], v[98:101]
	v_mfma_f32_16x16x32_bf16 v[98:101], v[150:153], v[204:207], v[98:101]
	v_mfma_f32_16x16x32_bf16 v[90:93], v[154:157], v[200:203], v[90:93]
	v_mfma_f32_16x16x32_bf16 v[90:93], v[158:161], v[204:207], v[90:93]
	v_mfma_f32_16x16x32_bf16 v[82:85], v[146:149], v[208:211], v[82:85]
	v_mfma_f32_16x16x32_bf16 v[82:85], v[150:153], v[212:215], v[82:85]
	v_mfma_f32_16x16x32_bf16 v[74:77], v[154:157], v[208:211], v[74:77]
	v_mfma_f32_16x16x32_bf16 v[74:77], v[158:161], v[212:215], v[74:77]
	v_mfma_f32_16x16x32_bf16 v[118:121], v[162:165], v[184:187], v[118:121]
	v_mfma_f32_16x16x32_bf16 v[118:121], v[166:169], v[188:191], v[118:121]
	v_mfma_f32_16x16x32_bf16 v[110:113], v[170:173], v[184:187], v[110:113]
	v_mfma_f32_16x16x32_bf16 v[110:113], v[180:183], v[188:191], v[110:113]
	v_mfma_f32_16x16x32_bf16 v[102:105], v[162:165], v[192:195], v[102:105]
	v_mfma_f32_16x16x32_bf16 v[102:105], v[166:169], v[196:199], v[102:105]
	v_mfma_f32_16x16x32_bf16 v[94:97], v[170:173], v[192:195], v[94:97]
	v_mfma_f32_16x16x32_bf16 v[94:97], v[180:183], v[196:199], v[94:97]
	v_mfma_f32_16x16x32_bf16 v[86:89], v[162:165], v[200:203], v[86:89]
	v_mfma_f32_16x16x32_bf16 v[86:89], v[166:169], v[204:207], v[86:89]
	v_mfma_f32_16x16x32_bf16 v[78:81], v[170:173], v[200:203], v[78:81]
	v_mfma_f32_16x16x32_bf16 v[78:81], v[180:183], v[204:207], v[78:81]
	v_mfma_f32_16x16x32_bf16 v[70:73], v[162:165], v[208:211], v[70:73]
	v_mfma_f32_16x16x32_bf16 v[70:73], v[166:169], v[212:215], v[70:73]
	v_mfma_f32_16x16x32_bf16 v[66:69], v[170:173], v[208:211], v[66:69]
	v_mfma_f32_16x16x32_bf16 v[66:69], v[180:183], v[212:215], v[66:69]
	s_barrier
	s_setprio 0
	s_add_i32 s39, s39, s47
	v_lshl_add_u64 v[140:141], s[12:13], 0, v[0:1]
	s_mov_b32 m0, s39
	ds_read_b128 v[184:187], v145 offset:16384
	ds_read_b128 v[188:191], v145 offset:17408
	ds_read_b128 v[192:195], v145 offset:18432
	ds_read_b128 v[196:199], v145 offset:19456
	ds_read_b128 v[200:203], v145 offset:20480
	ds_read_b128 v[204:207], v145 offset:21504
	ds_read_b128 v[208:211], v145 offset:22528
	ds_read_b128 v[212:215], v145 offset:23552
	global_load_lds_dwordx4 v[140:141], off
	s_add_i32 m0, s39, 0x2000
	s_add_u32 s44, s12, 0x84000
	v_lshl_add_u64 v[174:175], s[12:13], 0, v[134:135]
	s_addc_u32 s45, s13, 0
	s_add_i32 s39, s46, s47
	global_load_lds_dwordx4 v[174:175], off
	v_lshl_add_u64 v[216:217], s[44:45], 0, v[0:1]
	s_mov_b32 m0, s39
	v_lshl_add_u64 v[218:219], s[14:15], 0, v[132:133]
	global_load_lds_dwordx4 v[216:217], off
	v_lshl_add_u64 v[216:217], s[44:45], 0, v[134:135]
	s_add_i32 m0, s39, 0x2000
	s_nop 0
	global_load_lds_dwordx4 v[216:217], off
	v_lshl_add_u64 v[216:217], s[14:15], 0, v[130:131]
	s_mov_b32 m0, s18
	s_nop 0
	global_load_lds_dwordx4 v[216:217], off
	s_mov_b32 m0, s19
	s_nop 0
	global_load_lds_dwordx4 v[218:219], off
	s_waitcnt vmcnt(8)
	s_waitcnt lgkmcnt(0)
	s_setprio 1
	s_barrier
; #define PG8_STAGE(bufoff, gbase, voff) do { _Pragma("unroll") for (int _i = 0; _i < 2; ++_i) \
;         __builtin_amdgcn_global_load_lds((const unsigned*)((const char*)(gbase) + (voff)[_i]), (LAS unsigned*)(lds + (bufoff) + ldsw + _i * 8192), 16, 0, 0); } while (0)
; #define PG8_LDA(dst, b, h) do { _Pragma("unroll") for (int m = 0; m < 4; ++m) _Pragma("unroll") for (int k = 0; k < 2; ++k) dst[m][k] = *(const LAS bf16x8*)(lds + PG8_SA(b, h) + aoff + m * 2048 + k * 1024); } while (0)
; #define PG8_LDB(dst, b, h) do { _Pragma("unroll") for (int n = 0; n < 2; ++n) _Pragma("unroll") for (int k = 0; k < 2; ++k) dst[n][k] = *(const LAS bf16x8*)(lds + PG8_SB(b, h) + boff + n * 2048 + k * 1024); } while (0)
; #define PG8_MMA(ai, bj, At, Bt) do { __builtin_amdgcn_s_setprio(1); _Pragma("unroll") for (int m = 0; m < 4; ++m) _Pragma("unroll") for (int n = 0; n < 2; ++n) _Pragma("unroll") for (int k = 0; k < 2; ++k) \
;         acc[ai][bj][m][n] = __builtin_amdgcn_mfma_f32_16x16x32_bf16(Bt[n][k], At[m][k], acc[ai][bj][m][n], 0, 0, 0); __builtin_amdgcn_s_setprio(0); } while (0)
; #define PG8_WAIT_V(n) asm volatile("s_waitcnt vmcnt(" #n ")" ::: "memory")
; #define PG8_WAIT_L(n) asm volatile("s_waitcnt lgkmcnt(" #n ")" ::: "memory")
; #define PG8_BAR __builtin_amdgcn_s_barrier()
; #define PG8_SCHED __builtin_amdgcn_sched_barrier(0)
; template <class Epi, class Sched, int LDA, int LDB, bool ALIGN_EPI = true>
; __device__ __forceinline__ void gemm_phase(LAS unsigned char* lds, const Gemm g, const Sched& S, const Epi& E, int wave) {
;     ...
;             PG8_WAIT_V(8); PG8_WAIT_L(0); PG8_BAR; PG8_MMA(1, 0, At, B0); PG8_MMA(1, 1, At, B1); PG8_BAR; PG8_SCHED;
;             PG8_LDB(B0, 1, 0); PG8_LDB(B1, 1, 1); PG8_SCHED; PG8_LDA(At, 1, 0); PG8_STAGE(PG8_SA(0, 1), a2 + hstepA, voffA);
;             PG8_WAIT_V(8); PG8_WAIT_L(0); PG8_BAR; PG8_MMA(0, 0, At, B0); PG8_MMA(0, 1, At, B1); PG8_BAR; PG8_SCHED;
	v_mfma_f32_16x16x32_bf16 v[62:65], v[146:149], v[184:187], v[62:65]
	v_mfma_f32_16x16x32_bf16 v[62:65], v[150:153], v[188:191], v[62:65]
	v_mfma_f32_16x16x32_bf16 v[58:61], v[154:157], v[184:187], v[58:61]
	v_mfma_f32_16x16x32_bf16 v[58:61], v[158:161], v[188:191], v[58:61]
	v_mfma_f32_16x16x32_bf16 v[50:53], v[146:149], v[192:195], v[50:53]
	v_mfma_f32_16x16x32_bf16 v[50:53], v[150:153], v[196:199], v[50:53]
	v_mfma_f32_16x16x32_bf16 v[42:45], v[154:157], v[192:195], v[42:45]
	v_mfma_f32_16x16x32_bf16 v[42:45], v[158:161], v[196:199], v[42:45]
	v_mfma_f32_16x16x32_bf16 v[34:37], v[146:149], v[200:203], v[34:37]
	v_mfma_f32_16x16x32_bf16 v[34:37], v[150:153], v[204:207], v[34:37]
	v_mfma_f32_16x16x32_bf16 v[26:29], v[154:157], v[200:203], v[26:29]
	v_mfma_f32_16x16x32_bf16 v[26:29], v[158:161], v[204:207], v[26:29]
	v_mfma_f32_16x16x32_bf16 v[18:21], v[146:149], v[208:211], v[18:21]
	v_mfma_f32_16x16x32_bf16 v[18:21], v[150:153], v[212:215], v[18:21]
	v_mfma_f32_16x16x32_bf16 v[10:13], v[154:157], v[208:211], v[10:13]
	v_mfma_f32_16x16x32_bf16 v[10:13], v[158:161], v[212:215], v[10:13]
	v_mfma_f32_16x16x32_bf16 v[54:57], v[162:165], v[184:187], v[54:57]
	v_mfma_f32_16x16x32_bf16 v[54:57], v[166:169], v[188:191], v[54:57]
	v_mfma_f32_16x16x32_bf16 v[46:49], v[170:173], v[184:187], v[46:49]
	v_mfma_f32_16x16x32_bf16 v[46:49], v[180:183], v[188:191], v[46:49]
	v_mfma_f32_16x16x32_bf16 v[38:41], v[162:165], v[192:195], v[38:41]
	v_mfma_f32_16x16x32_bf16 v[38:41], v[166:169], v[196:199], v[38:41]
	v_mfma_f32_16x16x32_bf16 v[30:33], v[170:173], v[192:195], v[30:33]
	v_mfma_f32_16x16x32_bf16 v[30:33], v[180:183], v[196:199], v[30:33]
	v_mfma_f32_16x16x32_bf16 v[22:25], v[162:165], v[200:203], v[22:25]
	v_mfma_f32_16x16x32_bf16 v[22:25], v[166:169], v[204:207], v[22:25]
	v_mfma_f32_16x16x32_bf16 v[14:17], v[170:173], v[200:203], v[14:17]
	v_mfma_f32_16x16x32_bf16 v[14:17], v[180:183], v[204:207], v[14:17]
	v_mfma_f32_16x16x32_bf16 v[6:9], v[162:165], v[208:211], v[6:9]
	v_mfma_f32_16x16x32_bf16 v[6:9], v[166:169], v[212:215], v[6:9]
	v_mfma_f32_16x16x32_bf16 v[2:5], v[170:173], v[208:211], v[2:5]
	v_mfma_f32_16x16x32_bf16 v[2:5], v[180:183], v[212:215], v[2:5]
	s_barrier
	s_setprio 0
	s_add_i32 s39, 0, 0x18000
	s_add_i32 s44, 0, 0x1c000
	v_add_u32_e32 v158, s39, v143
	v_add_u32_e32 v180, s44, v143
	ds_read_b128 v[146:149], v158
	ds_read_b128 v[150:153], v158 offset:1024
	ds_read_b128 v[154:157], v158 offset:2048
	ds_read_b128 v[158:161], v158 offset:3072
	ds_read_b128 v[162:165], v180
	ds_read_b128 v[166:169], v180 offset:1024
	ds_read_b128 v[170:173], v180 offset:2048
	ds_read_b128 v[180:183], v180 offset:3072
	s_add_u32 s14, s14, 0x80000
	s_addc_u32 s15, s15, 0
	s_mov_b32 m0, s24
	v_lshl_add_u64 v[220:221], s[14:15], 0, v[130:131]
	ds_read_b128 v[184:187], v145 offset:32768
	ds_read_b128 v[188:191], v145 offset:33792
	ds_read_b128 v[192:195], v145 offset:34816
	ds_read_b128 v[196:199], v145 offset:35840
	ds_read_b128 v[200:203], v145 offset:36864
	ds_read_b128 v[204:207], v145 offset:37888
	ds_read_b128 v[208:211], v145 offset:38912
	ds_read_b128 v[212:215], v145 offset:39936
	global_load_lds_dwordx4 v[220:221], off
	v_lshl_add_u64 v[220:221], s[14:15], 0, v[132:133]
	s_mov_b32 m0, s25
	s_nop 0
	global_load_lds_dwordx4 v[220:221], off
	s_waitcnt vmcnt(8)
	s_waitcnt lgkmcnt(0)
	s_setprio 1
	s_barrier
	v_mfma_f32_16x16x32_bf16 v[126:129], v[146:149], v[184:187], v[126:129]
	v_mfma_f32_16x16x32_bf16 v[126:129], v[150:153], v[188:191], v[126:129]
	v_mfma_f32_16x16x32_bf16 v[122:125], v[154:157], v[184:187], v[122:125]
	v_mfma_f32_16x16x32_bf16 v[122:125], v[158:161], v[188:191], v[122:125]
	v_mfma_f32_16x16x32_bf16 v[114:117], v[146:149], v[192:195], v[114:117]
	v_mfma_f32_16x16x32_bf16 v[114:117], v[150:153], v[196:199], v[114:117]
	v_mfma_f32_16x16x32_bf16 v[106:109], v[154:157], v[192:195], v[106:109]
	v_mfma_f32_16x16x32_bf16 v[106:109], v[158:161], v[196:199], v[106:109]
	v_mfma_f32_16x16x32_bf16 v[98:101], v[146:149], v[200:203], v[98:101]
	v_mfma_f32_16x16x32_bf16 v[98:101], v[150:153], v[204:207], v[98:101]
	v_mfma_f32_16x16x32_bf16 v[90:93], v[154:157], v[200:203], v[90:93]
	v_mfma_f32_16x16x32_bf16 v[90:93], v[158:161], v[204:207], v[90:93]
	v_mfma_f32_16x16x32_bf16 v[82:85], v[146:149], v[208:211], v[82:85]
	v_mfma_f32_16x16x32_bf16 v[82:85], v[150:153], v[212:215], v[82:85]
	v_mfma_f32_16x16x32_bf16 v[74:77], v[154:157], v[208:211], v[74:77]
	v_mfma_f32_16x16x32_bf16 v[74:77], v[158:161], v[212:215], v[74:77]
	v_mfma_f32_16x16x32_bf16 v[118:121], v[162:165], v[184:187], v[118:121]
	v_mfma_f32_16x16x32_bf16 v[118:121], v[166:169], v[188:191], v[118:121]
	v_mfma_f32_16x16x32_bf16 v[110:113], v[170:173], v[184:187], v[110:113]
	v_mfma_f32_16x16x32_bf16 v[110:113], v[180:183], v[188:191], v[110:113]
	v_mfma_f32_16x16x32_bf16 v[102:105], v[162:165], v[192:195], v[102:105]
	v_mfma_f32_16x16x32_bf16 v[102:105], v[166:169], v[196:199], v[102:105]
	v_mfma_f32_16x16x32_bf16 v[94:97], v[170:173], v[192:195], v[94:97]
	v_mfma_f32_16x16x32_bf16 v[94:97], v[180:183], v[196:199], v[94:97]
	v_mfma_f32_16x16x32_bf16 v[86:89], v[162:165], v[200:203], v[86:89]
	v_mfma_f32_16x16x32_bf16 v[86:89], v[166:169], v[204:207], v[86:89]
	v_mfma_f32_16x16x32_bf16 v[78:81], v[170:173], v[200:203], v[78:81]
	v_mfma_f32_16x16x32_bf16 v[78:81], v[180:183], v[204:207], v[78:81]
	v_mfma_f32_16x16x32_bf16 v[70:73], v[162:165], v[208:211], v[70:73]
	v_mfma_f32_16x16x32_bf16 v[70:73], v[166:169], v[212:215], v[70:73]
	v_mfma_f32_16x16x32_bf16 v[66:69], v[170:173], v[208:211], v[66:69]
	v_mfma_f32_16x16x32_bf16 v[66:69], v[180:183], v[212:215], v[66:69]
	s_barrier
; #define PG8_STAGE(bufoff, gbase, voff) do { _Pragma("unroll") for (int _i = 0; _i < 2; ++_i) \
;         __builtin_amdgcn_global_load_lds((const unsigned*)((const char*)(gbase) + (voff)[_i]), (LAS unsigned*)(lds + (bufoff) + ldsw + _i * 8192), 16, 0, 0); } while (0)
; #define PG8_LDA(dst, b, h) do { _Pragma("unroll") for (int m = 0; m < 4; ++m) _Pragma("unroll") for (int k = 0; k < 2; ++k) dst[m][k] = *(const LAS bf16x8*)(lds + PG8_SA(b, h) + aoff + m * 2048 + k * 1024); } while (0)
; #define PG8_MMA(ai, bj, At, Bt) do { __builtin_amdgcn_s_setprio(1); _Pragma("unroll") for (int m = 0; m < 4; ++m) _Pragma("unroll") for (int n = 0; n < 2; ++n) _Pragma("unroll") for (int k = 0; k < 2; ++k) \
;         acc[ai][bj][m][n] = __builtin_amdgcn_mfma_f32_16x16x32_bf16(Bt[n][k], At[m][k], acc[ai][bj][m][n], 0, 0, 0); __builtin_amdgcn_s_setprio(0); } while (0)
; #define PG8_WAIT_V(n) asm volatile("s_waitcnt vmcnt(" #n ")" ::: "memory")
; #define PG8_WAIT_L(n) asm volatile("s_waitcnt lgkmcnt(" #n ")" ::: "memory")
; #define PG8_BAR __builtin_amdgcn_s_barrier()
; #define PG8_SCHED __builtin_amdgcn_sched_barrier(0)
; template <class Epi, class Sched, int LDA, int LDB, bool ALIGN_EPI = true>
; __device__ __forceinline__ void gemm_phase(LAS unsigned char* lds, const Gemm g, const Sched& S, const Epi& E, int wave) {
;     ...
;             PG8_LDA(At, 1, 1); PG8_STAGE(PG8_SB(1, 0), b3, voffB); PG8_STAGE(PG8_SB(1, 1), b3 + hstepB, voffB); PG8_STAGE(PG8_SA(1, 0), a3, voffA);
;             PG8_WAIT_V(8); PG8_WAIT_L(0); PG8_BAR; PG8_MMA(1, 0, At, B0); PG8_MMA(1, 1, At, B1); PG8_BAR; PG8_SCHED;
;         }
	s_setprio 0
	s_add_i32 s14, s39, s47
	v_lshl_add_u64 v[140:141], v[140:141], 0, s[48:49]
	s_mov_b32 m0, s14
	ds_read_b128 v[184:187], v145 offset:49152
	ds_read_b128 v[188:191], v145 offset:50176
	ds_read_b128 v[192:195], v145 offset:51200
	ds_read_b128 v[196:199], v145 offset:52224
	ds_read_b128 v[200:203], v145 offset:53248
	ds_read_b128 v[204:207], v145 offset:54272
	ds_read_b128 v[208:211], v145 offset:55296
	ds_read_b128 v[212:215], v145 offset:56320
	global_load_lds_dwordx4 v[140:141], off
	s_add_i32 m0, s14, 0x2000
	s_add_u32 s12, s12, 0x84080
	v_lshl_add_u64 v[140:141], v[174:175], 0, s[48:49]
	s_addc_u32 s13, s13, 0
	s_add_i32 s14, s44, s47
	global_load_lds_dwordx4 v[140:141], off
	v_lshl_add_u64 v[140:141], s[12:13], 0, v[0:1]
	s_mov_b32 m0, s14
	s_nop 0
	global_load_lds_dwordx4 v[140:141], off
	v_lshl_add_u64 v[140:141], s[12:13], 0, v[134:135]
	s_add_i32 m0, s14, 0x2000
	s_nop 0
	global_load_lds_dwordx4 v[140:141], off
	v_lshl_add_u64 v[140:141], v[216:217], 0, s[48:49]
	s_mov_b32 m0, s26
	s_nop 0
	global_load_lds_dwordx4 v[140:141], off
	v_lshl_add_u64 v[140:141], v[218:219], 0, s[48:49]
	s_mov_b32 m0, s27
	s_nop 0
	global_load_lds_dwordx4 v[140:141], off
	s_waitcnt vmcnt(8)
	s_waitcnt lgkmcnt(0)
	s_setprio 1
	s_barrier
	v_mfma_f32_16x16x32_bf16 v[62:65], v[146:149], v[184:187], v[62:65]
	v_mfma_f32_16x16x32_bf16 v[62:65], v[150:153], v[188:191], v[62:65]
	v_mfma_f32_16x16x32_bf16 v[58:61], v[154:157], v[184:187], v[58:61]
	v_mfma_f32_16x16x32_bf16 v[58:61], v[158:161], v[188:191], v[58:61]
	v_mfma_f32_16x16x32_bf16 v[50:53], v[146:149], v[192:195], v[50:53]
	v_mfma_f32_16x16x32_bf16 v[50:53], v[150:153], v[196:199], v[50:53]
	v_mfma_f32_16x16x32_bf16 v[42:45], v[154:157], v[192:195], v[42:45]
	v_mfma_f32_16x16x32_bf16 v[42:45], v[158:161], v[196:199], v[42:45]
	v_mfma_f32_16x16x32_bf16 v[34:37], v[146:149], v[200:203], v[34:37]
	v_mfma_f32_16x16x32_bf16 v[34:37], v[150:153], v[204:207], v[34:37]
	v_mfma_f32_16x16x32_bf16 v[26:29], v[154:157], v[200:203], v[26:29]
	v_mfma_f32_16x16x32_bf16 v[26:29], v[158:161], v[204:207], v[26:29]
	v_mfma_f32_16x16x32_bf16 v[18:21], v[146:149], v[208:211], v[18:21]
	v_mfma_f32_16x16x32_bf16 v[18:21], v[150:153], v[212:215], v[18:21]
	v_mfma_f32_16x16x32_bf16 v[10:13], v[154:157], v[208:211], v[10:13]
	v_mfma_f32_16x16x32_bf16 v[10:13], v[158:161], v[212:215], v[10:13]
	v_mfma_f32_16x16x32_bf16 v[54:57], v[162:165], v[184:187], v[54:57]
	v_mfma_f32_16x16x32_bf16 v[54:57], v[166:169], v[188:191], v[54:57]
	v_mfma_f32_16x16x32_bf16 v[46:49], v[170:173], v[184:187], v[46:49]
	v_mfma_f32_16x16x32_bf16 v[46:49], v[180:183], v[188:191], v[46:49]
	v_mfma_f32_16x16x32_bf16 v[38:41], v[162:165], v[192:195], v[38:41]
	v_mfma_f32_16x16x32_bf16 v[38:41], v[166:169], v[196:199], v[38:41]
	v_mfma_f32_16x16x32_bf16 v[30:33], v[170:173], v[192:195], v[30:33]
	v_mfma_f32_16x16x32_bf16 v[30:33], v[180:183], v[196:199], v[30:33]
	v_mfma_f32_16x16x32_bf16 v[22:25], v[162:165], v[200:203], v[22:25]
	v_mfma_f32_16x16x32_bf16 v[22:25], v[166:169], v[204:207], v[22:25]
	v_mfma_f32_16x16x32_bf16 v[14:17], v[170:173], v[200:203], v[14:17]
	v_mfma_f32_16x16x32_bf16 v[14:17], v[180:183], v[204:207], v[14:17]
	v_mfma_f32_16x16x32_bf16 v[6:9], v[162:165], v[208:211], v[6:9]
	v_mfma_f32_16x16x32_bf16 v[6:9], v[166:169], v[212:215], v[6:9]
	v_mfma_f32_16x16x32_bf16 v[2:5], v[170:173], v[208:211], v[2:5]
	v_mfma_f32_16x16x32_bf16 v[2:5], v[180:183], v[212:215], v[2:5]
	s_barrier
	s_setprio 0
	s_add_i32 s38, s38, 2
	s_add_u32 s10, s10, 0x100
	s_addc_u32 s11, s11, 0
	s_add_u32 s36, s36, 0x100
	s_addc_u32 s37, s37, 0
	s_cmp_gt_u32 s38, 29
	s_cbranch_scc0 .LBB0_2415
	v_readlane_b32 s10, v252, 14
	v_readlane_b32 s11, v252, 15
	s_and_b64 vcc, exec, s[10:11]
	s_cbranch_vccz .LBB0_2418
	s_barrier

; #define PG8_STAGE(bufoff, gbase, voff) do { _Pragma("unroll") for (int _i = 0; _i < 2; ++_i) \
;         __builtin_amdgcn_global_load_lds((const unsigned*)((const char*)(gbase) + (voff)[_i]), (LAS unsigned*)(lds + (bufoff) + ldsw + _i * 8192), 16, 0, 0); } while (0)
; #define PG8_LDA(dst, b, h) do { _Pragma("unroll") for (int m = 0; m < 4; ++m) _Pragma("unroll") for (int k = 0; k < 2; ++k) dst[m][k] = *(const LAS bf16x8*)(lds + PG8_SA(b, h) + aoff + m * 2048 + k * 1024); } while (0)
; #define PG8_LDB(dst, b, h) do { _Pragma("unroll") for (int n = 0; n < 2; ++n) _Pragma("unroll") for (int k = 0; k < 2; ++k) dst[n][k] = *(const LAS bf16x8*)(lds + PG8_SB(b, h) + boff + n * 2048 + k * 1024); } while (0)
; #define PG8_MMA(ai, bj, At, Bt) do { __builtin_amdgcn_s_setprio(1); _Pragma("unroll") for (int m = 0; m < 4; ++m) _Pragma("unroll") for (int n = 0; n < 2; ++n) _Pragma("unroll") for (int k = 0; k < 2; ++k) \
;         acc[ai][bj][m][n] = __builtin_amdgcn_mfma_f32_16x16x32_bf16(Bt[n][k], At[m][k], acc[ai][bj][m][n], 0, 0, 0); __builtin_amdgcn_s_setprio(0); } while (0)
; #define PG8_WAIT_V(n) asm volatile("s_waitcnt vmcnt(" #n ")" ::: "memory")
; template <class Epi, class Sched, int LDA, int LDB, bool ALIGN_EPI = true>
; __device__ __forceinline__ void gemm_phase(LAS unsigned char* lds, const Gemm g, const Sched& S, const Epi& E, int wave) {
;     ...
;         for (int t = 0; t < nt; t += 2) {
;             const bool last = (t == nt - 2);
;             const char* a1 = cA + (size_t)(t + 1) * kstep;
;             const char* a2 = last ? nA : cA + (size_t)(t + 2) * kstep; const char* b2 = last ? nB : cB + (size_t)(t + 2) * kstep;
;             const char* a3 = a2 + kstep; const char* b3 = b2 + kstep;
;             PG8_LDB(B0, 0, 0); PG8_LDB(B1, 0, 1); PG8_SCHED; PG8_LDA(At, 0, 0); PG8_STAGE(PG8_SA(1, 1), a1 + hstepA, voffA);
;             PG8_WAIT_V(8); PG8_WAIT_L(0); PG8_BAR; PG8_MMA(0, 0, At, B0); PG8_MMA(0, 1, At, B1); PG8_BAR; PG8_SCHED;
;             PG8_LDA(At, 0, 1); PG8_STAGE(PG8_SB(0, 0), b2, voffB); PG8_STAGE(PG8_SB(0, 1), b2 + hstepB, voffB); PG8_STAGE(PG8_SA(0, 0), a2, voffA);
;             PG8_WAIT_V(8); PG8_WAIT_L(0); PG8_BAR; PG8_MMA(1, 0, At, B0); PG8_MMA(1, 1, At, B1); PG8_BAR; PG8_SCHED;
;             PG8_LDB(B0, 1, 0); PG8_LDB(B1, 1, 1); PG8_SCHED; PG8_LDA(At, 1, 0); PG8_STAGE(PG8_SA(0, 1), a2 + hstepA, voffA);
.LBB0_2513:
	s_add_u32 s14, s12, 0xfff80080
	s_addc_u32 s15, s13, -1
	s_add_i32 s44, 0, 0x10000
	s_cmp_eq_u32 s39, 28
	s_cselect_b32 s17, s1, s15
	s_cselect_b32 s16, s3, s14
	v_add_u32_e32 v140, s44, v143
	s_cselect_b32 s15, s9, s38
	s_cselect_b32 s14, s8, s37
	s_add_i32 s46, 0, 0x14000
	ds_read_b128 v[146:149], v140
	ds_read_b128 v[150:153], v140 offset:1024
	ds_read_b128 v[154:157], v140 offset:2048
	ds_read_b128 v[158:161], v140 offset:3072
	v_add_u32_e32 v140, s46, v143
	ds_read_b128 v[162:165], v140
	ds_read_b128 v[166:169], v140 offset:1024
	ds_read_b128 v[170:173], v140 offset:2048
	ds_read_b128 v[180:183], v140 offset:3072
	v_lshl_add_u64 v[140:141], s[12:13], 0, v[136:137]
	s_add_i32 m0, s24, 0xc000
	ds_read_b128 v[184:187], v145
	ds_read_b128 v[188:191], v145 offset:1024
	ds_read_b128 v[192:195], v145 offset:2048
	ds_read_b128 v[196:199], v145 offset:3072
	ds_read_b128 v[200:203], v145 offset:4096
	ds_read_b128 v[204:207], v145 offset:5120
	ds_read_b128 v[208:211], v145 offset:6144
	ds_read_b128 v[212:215], v145 offset:7168
	global_load_lds_dwordx4 v[140:141], off
	v_lshl_add_u64 v[140:141], s[12:13], 0, v[138:139]
	s_add_i32 m0, s24, 0xe000
	s_nop 0
	global_load_lds_dwordx4 v[140:141], off
	s_waitcnt vmcnt(8)
	s_waitcnt lgkmcnt(0)
	s_setprio 1
	s_barrier
	v_mfma_f32_16x16x32_bf16 v[126:129], v[146:149], v[184:187], v[126:129]
	v_mfma_f32_16x16x32_bf16 v[126:129], v[150:153], v[188:191], v[126:129]
	v_mfma_f32_16x16x32_bf16 v[122:125], v[154:157], v[184:187], v[122:125]
	v_mfma_f32_16x16x32_bf16 v[122:125], v[158:161], v[188:191], v[122:125]
	v_mfma_f32_16x16x32_bf16 v[114:117], v[146:149], v[192:195], v[114:117]
	v_mfma_f32_16x16x32_bf16 v[114:117], v[150:153], v[196:199], v[114:117]
	v_mfma_f32_16x16x32_bf16 v[106:109], v[154:157], v[192:195], v[106:109]
	v_mfma_f32_16x16x32_bf16 v[106:109], v[158:161], v[196:199], v[106:109]
	v_mfma_f32_16x16x32_bf16 v[98:101], v[146:149], v[200:203], v[98:101]
	v_mfma_f32_16x16x32_bf16 v[98:101], v[150:153], v[204:207], v[98:101]
	v_mfma_f32_16x16x32_bf16 v[90:93], v[154:157], v[200:203], v[90:93]
	v_mfma_f32_16x16x32_bf16 v[90:93], v[158:161], v[204:207], v[90:93]
	v_mfma_f32_16x16x32_bf16 v[82:85], v[146:149], v[208:211], v[82:85]
	v_mfma_f32_16x16x32_bf16 v[82:85], v[150:153], v[212:215], v[82:85]
	v_mfma_f32_16x16x32_bf16 v[74:77], v[154:157], v[208:211], v[74:77]
	v_mfma_f32_16x16x32_bf16 v[74:77], v[158:161], v[212:215], v[74:77]
	v_mfma_f32_16x16x32_bf16 v[118:121], v[162:165], v[184:187], v[118:121]
	v_mfma_f32_16x16x32_bf16 v[118:121], v[166:169], v[188:191], v[118:121]
	v_mfma_f32_16x16x32_bf16 v[110:113], v[170:173], v[184:187], v[110:113]
	v_mfma_f32_16x16x32_bf16 v[110:113], v[180:183], v[188:191], v[110:113]
	v_mfma_f32_16x16x32_bf16 v[102:105], v[162:165], v[192:195], v[102:105]
	v_mfma_f32_16x16x32_bf16 v[102:105], v[166:169], v[196:199], v[102:105]
	v_mfma_f32_16x16x32_bf16 v[94:97], v[170:173], v[192:195], v[94:97]
	v_mfma_f32_16x16x32_bf16 v[94:97], v[180:183], v[196:199], v[94:97]
	v_mfma_f32_16x16x32_bf16 v[86:89], v[162:165], v[200:203], v[86:89]
	v_mfma_f32_16x16x32_bf16 v[86:89], v[166:169], v[204:207], v[86:89]
	v_mfma_f32_16x16x32_bf16 v[78:81], v[170:173], v[200:203], v[78:81]
	v_mfma_f32_16x16x32_bf16 v[78:81], v[180:183], v[204:207], v[78:81]
	v_mfma_f32_16x16x32_bf16 v[70:73], v[162:165], v[208:211], v[70:73]
	v_mfma_f32_16x16x32_bf16 v[70:73], v[166:169], v[212:215], v[70:73]
	v_mfma_f32_16x16x32_bf16 v[66:69], v[170:173], v[208:211], v[66:69]
	v_mfma_f32_16x16x32_bf16 v[66:69], v[180:183], v[212:215], v[66:69]
	s_barrier
	s_setprio 0
	s_add_i32 s44, s44, s47
	v_lshl_add_u64 v[140:141], s[14:15], 0, v[0:1]
	s_mov_b32 m0, s44
	ds_read_b128 v[184:187], v145 offset:16384
	ds_read_b128 v[188:191], v145 offset:17408
	ds_read_b128 v[192:195], v145 offset:18432
	ds_read_b128 v[196:199], v145 offset:19456
	ds_read_b128 v[200:203], v145 offset:20480
	ds_read_b128 v[204:207], v145 offset:21504
	ds_read_b128 v[208:211], v145 offset:22528
	ds_read_b128 v[212:215], v145 offset:23552
	global_load_lds_dwordx4 v[140:141], off
	s_add_i32 m0, s44, 0x2000
	s_add_u32 s44, s14, 0x84000
	v_lshl_add_u64 v[174:175], s[14:15], 0, v[134:135]
	s_addc_u32 s45, s15, 0
	s_add_i32 s46, s46, s47
	global_load_lds_dwordx4 v[174:175], off
	v_lshl_add_u64 v[216:217], s[44:45], 0, v[0:1]
	s_mov_b32 m0, s46
	v_lshl_add_u64 v[218:219], s[16:17], 0, v[132:133]
	global_load_lds_dwordx4 v[216:217], off
	v_lshl_add_u64 v[216:217], s[44:45], 0, v[134:135]
	s_add_i32 m0, s46, 0x2000
	s_nop 0
	global_load_lds_dwordx4 v[216:217], off
	v_lshl_add_u64 v[216:217], s[16:17], 0, v[130:131]
	s_mov_b32 m0, s24
	s_nop 0
	global_load_lds_dwordx4 v[216:217], off
	s_mov_b32 m0, s25
	s_nop 0
	global_load_lds_dwordx4 v[218:219], off
	s_waitcnt vmcnt(8)
	s_waitcnt lgkmcnt(0)
	s_setprio 1
	s_barrier
; #define PG8_STAGE(bufoff, gbase, voff) do { _Pragma("unroll") for (int _i = 0; _i < 2; ++_i) \
;         __builtin_amdgcn_global_load_lds((const unsigned*)((const char*)(gbase) + (voff)[_i]), (LAS unsigned*)(lds + (bufoff) + ldsw + _i * 8192), 16, 0, 0); } while (0)
; #define PG8_LDA(dst, b, h) do { _Pragma("unroll") for (int m = 0; m < 4; ++m) _Pragma("unroll") for (int k = 0; k < 2; ++k) dst[m][k] = *(const LAS bf16x8*)(lds + PG8_SA(b, h) + aoff + m * 2048 + k * 1024); } while (0)
; #define PG8_LDB(dst, b, h) do { _Pragma("unroll") for (int n = 0; n < 2; ++n) _Pragma("unroll") for (int k = 0; k < 2; ++k) dst[n][k] = *(const LAS bf16x8*)(lds + PG8_SB(b, h) + boff + n * 2048 + k * 1024); } while (0)
; #define PG8_MMA(ai, bj, At, Bt) do { __builtin_amdgcn_s_setprio(1); _Pragma("unroll") for (int m = 0; m < 4; ++m) _Pragma("unroll") for (int n = 0; n < 2; ++n) _Pragma("unroll") for (int k = 0; k < 2; ++k) \
;         acc[ai][bj][m][n] = __builtin_amdgcn_mfma_f32_16x16x32_bf16(Bt[n][k], At[m][k], acc[ai][bj][m][n], 0, 0, 0); __builtin_amdgcn_s_setprio(0); } while (0)
; #define PG8_WAIT_V(n) asm volatile("s_waitcnt vmcnt(" #n ")" ::: "memory")
; #define PG8_WAIT_L(n) asm volatile("s_waitcnt lgkmcnt(" #n ")" ::: "memory")
; #define PG8_BAR __builtin_amdgcn_s_barrier()
; #define PG8_SCHED __builtin_amdgcn_sched_barrier(0)
; template <class Epi, class Sched, int LDA, int LDB, bool ALIGN_EPI = true>
; __device__ __forceinline__ void gemm_phase(LAS unsigned char* lds, const Gemm g, const Sched& S, const Epi& E, int wave) {
;     ...
;             PG8_WAIT_V(8); PG8_WAIT_L(0); PG8_BAR; PG8_MMA(1, 0, At, B0); PG8_MMA(1, 1, At, B1); PG8_BAR; PG8_SCHED;
;             PG8_LDB(B0, 1, 0); PG8_LDB(B1, 1, 1); PG8_SCHED; PG8_LDA(At, 1, 0); PG8_STAGE(PG8_SA(0, 1), a2 + hstepA, voffA);
;             PG8_WAIT_V(8); PG8_WAIT_L(0); PG8_BAR; PG8_MMA(0, 0, At, B0); PG8_MMA(0, 1, At, B1); PG8_BAR; PG8_SCHED;
	v_mfma_f32_16x16x32_bf16 v[62:65], v[146:149], v[184:187], v[62:65]
	v_mfma_f32_16x16x32_bf16 v[62:65], v[150:153], v[188:191], v[62:65]
	v_mfma_f32_16x16x32_bf16 v[58:61], v[154:157], v[184:187], v[58:61]
	v_mfma_f32_16x16x32_bf16 v[58:61], v[158:161], v[188:191], v[58:61]
	v_mfma_f32_16x16x32_bf16 v[50:53], v[146:149], v[192:195], v[50:53]
	v_mfma_f32_16x16x32_bf16 v[50:53], v[150:153], v[196:199], v[50:53]
	v_mfma_f32_16x16x32_bf16 v[42:45], v[154:157], v[192:195], v[42:45]
	v_mfma_f32_16x16x32_bf16 v[42:45], v[158:161], v[196:199], v[42:45]
	v_mfma_f32_16x16x32_bf16 v[34:37], v[146:149], v[200:203], v[34:37]
	v_mfma_f32_16x16x32_bf16 v[34:37], v[150:153], v[204:207], v[34:37]
	v_mfma_f32_16x16x32_bf16 v[26:29], v[154:157], v[200:203], v[26:29]
	v_mfma_f32_16x16x32_bf16 v[26:29], v[158:161], v[204:207], v[26:29]
	v_mfma_f32_16x16x32_bf16 v[18:21], v[146:149], v[208:211], v[18:21]
	v_mfma_f32_16x16x32_bf16 v[18:21], v[150:153], v[212:215], v[18:21]
	v_mfma_f32_16x16x32_bf16 v[10:13], v[154:157], v[208:211], v[10:13]
	v_mfma_f32_16x16x32_bf16 v[10:13], v[158:161], v[212:215], v[10:13]
	v_mfma_f32_16x16x32_bf16 v[54:57], v[162:165], v[184:187], v[54:57]
	v_mfma_f32_16x16x32_bf16 v[54:57], v[166:169], v[188:191], v[54:57]
	v_mfma_f32_16x16x32_bf16 v[46:49], v[170:173], v[184:187], v[46:49]
	v_mfma_f32_16x16x32_bf16 v[46:49], v[180:183], v[188:191], v[46:49]
	v_mfma_f32_16x16x32_bf16 v[38:41], v[162:165], v[192:195], v[38:41]
	v_mfma_f32_16x16x32_bf16 v[38:41], v[166:169], v[196:199], v[38:41]
	v_mfma_f32_16x16x32_bf16 v[30:33], v[170:173], v[192:195], v[30:33]
	v_mfma_f32_16x16x32_bf16 v[30:33], v[180:183], v[196:199], v[30:33]
	v_mfma_f32_16x16x32_bf16 v[22:25], v[162:165], v[200:203], v[22:25]
	v_mfma_f32_16x16x32_bf16 v[22:25], v[166:169], v[204:207], v[22:25]
	v_mfma_f32_16x16x32_bf16 v[14:17], v[170:173], v[200:203], v[14:17]
	v_mfma_f32_16x16x32_bf16 v[14:17], v[180:183], v[204:207], v[14:17]
	v_mfma_f32_16x16x32_bf16 v[6:9], v[162:165], v[208:211], v[6:9]
	v_mfma_f32_16x16x32_bf16 v[6:9], v[166:169], v[212:215], v[6:9]
	v_mfma_f32_16x16x32_bf16 v[2:5], v[170:173], v[208:211], v[2:5]
	v_mfma_f32_16x16x32_bf16 v[2:5], v[180:183], v[212:215], v[2:5]
	s_barrier
	s_setprio 0
	s_add_i32 s44, 0, 0x18000
	s_add_i32 s45, 0, 0x1c000
	v_add_u32_e32 v158, s44, v143
	v_add_u32_e32 v180, s45, v143
	ds_read_b128 v[146:149], v158
	ds_read_b128 v[150:153], v158 offset:1024
	ds_read_b128 v[154:157], v158 offset:2048
	ds_read_b128 v[158:161], v158 offset:3072
	ds_read_b128 v[162:165], v180
	ds_read_b128 v[166:169], v180 offset:1024
	ds_read_b128 v[170:173], v180 offset:2048
	ds_read_b128 v[180:183], v180 offset:3072
	s_add_u32 s16, s16, 0x80000
	s_addc_u32 s17, s17, 0
	s_mov_b32 m0, s26
	v_lshl_add_u64 v[220:221], s[16:17], 0, v[130:131]
	ds_read_b128 v[184:187], v145 offset:32768
	ds_read_b128 v[188:191], v145 offset:33792
	ds_read_b128 v[192:195], v145 offset:34816
	ds_read_b128 v[196:199], v145 offset:35840
	ds_read_b128 v[200:203], v145 offset:36864
	ds_read_b128 v[204:207], v145 offset:37888
	ds_read_b128 v[208:211], v145 offset:38912
	ds_read_b128 v[212:215], v145 offset:39936
	global_load_lds_dwordx4 v[220:221], off
	v_lshl_add_u64 v[220:221], s[16:17], 0, v[132:133]
	s_mov_b32 m0, s27
	s_nop 0
	global_load_lds_dwordx4 v[220:221], off
	s_waitcnt vmcnt(8)
	s_waitcnt lgkmcnt(0)
	s_setprio 1
	s_barrier
	v_mfma_f32_16x16x32_bf16 v[126:129], v[146:149], v[184:187], v[126:129]
	v_mfma_f32_16x16x32_bf16 v[126:129], v[150:153], v[188:191], v[126:129]
	v_mfma_f32_16x16x32_bf16 v[122:125], v[154:157], v[184:187], v[122:125]
	v_mfma_f32_16x16x32_bf16 v[122:125], v[158:161], v[188:191], v[122:125]
	v_mfma_f32_16x16x32_bf16 v[114:117], v[146:149], v[192:195], v[114:117]
	v_mfma_f32_16x16x32_bf16 v[114:117], v[150:153], v[196:199], v[114:117]
	v_mfma_f32_16x16x32_bf16 v[106:109], v[154:157], v[192:195], v[106:109]
	v_mfma_f32_16x16x32_bf16 v[106:109], v[158:161], v[196:199], v[106:109]
	v_mfma_f32_16x16x32_bf16 v[98:101], v[146:149], v[200:203], v[98:101]
	v_mfma_f32_16x16x32_bf16 v[98:101], v[150:153], v[204:207], v[98:101]
	v_mfma_f32_16x16x32_bf16 v[90:93], v[154:157], v[200:203], v[90:93]
	v_mfma_f32_16x16x32_bf16 v[90:93], v[158:161], v[204:207], v[90:93]
	v_mfma_f32_16x16x32_bf16 v[82:85], v[146:149], v[208:211], v[82:85]
	v_mfma_f32_16x16x32_bf16 v[82:85], v[150:153], v[212:215], v[82:85]
	v_mfma_f32_16x16x32_bf16 v[74:77], v[154:157], v[208:211], v[74:77]
	v_mfma_f32_16x16x32_bf16 v[74:77], v[158:161], v[212:215], v[74:77]
	v_mfma_f32_16x16x32_bf16 v[118:121], v[162:165], v[184:187], v[118:121]
	v_mfma_f32_16x16x32_bf16 v[118:121], v[166:169], v[188:191], v[118:121]
	v_mfma_f32_16x16x32_bf16 v[110:113], v[170:173], v[184:187], v[110:113]
	v_mfma_f32_16x16x32_bf16 v[110:113], v[180:183], v[188:191], v[110:113]
	v_mfma_f32_16x16x32_bf16 v[102:105], v[162:165], v[192:195], v[102:105]
	v_mfma_f32_16x16x32_bf16 v[102:105], v[166:169], v[196:199], v[102:105]
	v_mfma_f32_16x16x32_bf16 v[94:97], v[170:173], v[192:195], v[94:97]
	v_mfma_f32_16x16x32_bf16 v[94:97], v[180:183], v[196:199], v[94:97]
	v_mfma_f32_16x16x32_bf16 v[86:89], v[162:165], v[200:203], v[86:89]
	v_mfma_f32_16x16x32_bf16 v[86:89], v[166:169], v[204:207], v[86:89]
	v_mfma_f32_16x16x32_bf16 v[78:81], v[170:173], v[200:203], v[78:81]
	v_mfma_f32_16x16x32_bf16 v[78:81], v[180:183], v[204:207], v[78:81]
	v_mfma_f32_16x16x32_bf16 v[70:73], v[162:165], v[208:211], v[70:73]
	v_mfma_f32_16x16x32_bf16 v[70:73], v[166:169], v[212:215], v[70:73]
	v_mfma_f32_16x16x32_bf16 v[66:69], v[170:173], v[208:211], v[66:69]
	v_mfma_f32_16x16x32_bf16 v[66:69], v[180:183], v[212:215], v[66:69]
	s_barrier
; #define PG8_STAGE(bufoff, gbase, voff) do { _Pragma("unroll") for (int _i = 0; _i < 2; ++_i) \
;         __builtin_amdgcn_global_load_lds((const unsigned*)((const char*)(gbase) + (voff)[_i]), (LAS unsigned*)(lds + (bufoff) + ldsw + _i * 8192), 16, 0, 0); } while (0)
; #define PG8_LDA(dst, b, h) do { _Pragma("unroll") for (int m = 0; m < 4; ++m) _Pragma("unroll") for (int k = 0; k < 2; ++k) dst[m][k] = *(const LAS bf16x8*)(lds + PG8_SA(b, h) + aoff + m * 2048 + k * 1024); } while (0)
; #define PG8_MMA(ai, bj, At, Bt) do { __builtin_amdgcn_s_setprio(1); _Pragma("unroll") for (int m = 0; m < 4; ++m) _Pragma("unroll") for (int n = 0; n < 2; ++n) _Pragma("unroll") for (int k = 0; k < 2; ++k) \
;         acc[ai][bj][m][n] = __builtin_amdgcn_mfma_f32_16x16x32_bf16(Bt[n][k], At[m][k], acc[ai][bj][m][n], 0, 0, 0); __builtin_amdgcn_s_setprio(0); } while (0)
; #define PG8_WAIT_V(n) asm volatile("s_waitcnt vmcnt(" #n ")" ::: "memory")
; #define PG8_WAIT_L(n) asm volatile("s_waitcnt lgkmcnt(" #n ")" ::: "memory")
; #define PG8_BAR __builtin_amdgcn_s_barrier()
; #define PG8_SCHED __builtin_amdgcn_sched_barrier(0)
; template <class Epi, class Sched, int LDA, int LDB, bool ALIGN_EPI = true>
; __device__ __forceinline__ void gemm_phase(LAS unsigned char* lds, const Gemm g, const Sched& S, const Epi& E, int wave) {
;     ...
;             PG8_LDA(At, 1, 1); PG8_STAGE(PG8_SB(1, 0), b3, voffB); PG8_STAGE(PG8_SB(1, 1), b3 + hstepB, voffB); PG8_STAGE(PG8_SA(1, 0), a3, voffA);
;             PG8_WAIT_V(8); PG8_WAIT_L(0); PG8_BAR; PG8_MMA(1, 0, At, B0); PG8_MMA(1, 1, At, B1); PG8_BAR; PG8_SCHED;
;         }
	s_setprio 0
	s_add_i32 s16, s44, s47
	v_lshl_add_u64 v[140:141], v[140:141], 0, s[72:73]
	s_mov_b32 m0, s16
	ds_read_b128 v[184:187], v145 offset:49152
	ds_read_b128 v[188:191], v145 offset:50176
	ds_read_b128 v[192:195], v145 offset:51200
	ds_read_b128 v[196:199], v145 offset:52224
	ds_read_b128 v[200:203], v145 offset:53248
	ds_read_b128 v[204:207], v145 offset:54272
	ds_read_b128 v[208:211], v145 offset:55296
	ds_read_b128 v[212:215], v145 offset:56320
	global_load_lds_dwordx4 v[140:141], off
	s_add_i32 m0, s16, 0x2000
	s_add_u32 s14, s14, 0x84080
	v_lshl_add_u64 v[140:141], v[174:175], 0, s[72:73]
	s_addc_u32 s15, s15, 0
	s_add_i32 s16, s45, s47
	global_load_lds_dwordx4 v[140:141], off
	v_lshl_add_u64 v[140:141], s[14:15], 0, v[0:1]
	s_mov_b32 m0, s16
	s_nop 0
	global_load_lds_dwordx4 v[140:141], off
	v_lshl_add_u64 v[140:141], s[14:15], 0, v[134:135]
	s_add_i32 m0, s16, 0x2000
	s_nop 0
	global_load_lds_dwordx4 v[140:141], off
	v_lshl_add_u64 v[140:141], v[216:217], 0, s[72:73]
	s_mov_b32 m0, s28
	s_nop 0
	global_load_lds_dwordx4 v[140:141], off
	v_lshl_add_u64 v[140:141], v[218:219], 0, s[72:73]
	s_mov_b32 m0, s29
	s_nop 0
	global_load_lds_dwordx4 v[140:141], off
	s_waitcnt vmcnt(8)
	s_waitcnt lgkmcnt(0)
	s_setprio 1
	s_barrier
	v_mfma_f32_16x16x32_bf16 v[62:65], v[146:149], v[184:187], v[62:65]
	v_mfma_f32_16x16x32_bf16 v[62:65], v[150:153], v[188:191], v[62:65]
	v_mfma_f32_16x16x32_bf16 v[58:61], v[154:157], v[184:187], v[58:61]
	v_mfma_f32_16x16x32_bf16 v[58:61], v[158:161], v[188:191], v[58:61]
	v_mfma_f32_16x16x32_bf16 v[50:53], v[146:149], v[192:195], v[50:53]
	v_mfma_f32_16x16x32_bf16 v[50:53], v[150:153], v[196:199], v[50:53]
	v_mfma_f32_16x16x32_bf16 v[42:45], v[154:157], v[192:195], v[42:45]
	v_mfma_f32_16x16x32_bf16 v[42:45], v[158:161], v[196:199], v[42:45]
	v_mfma_f32_16x16x32_bf16 v[34:37], v[146:149], v[200:203], v[34:37]
	v_mfma_f32_16x16x32_bf16 v[34:37], v[150:153], v[204:207], v[34:37]
	v_mfma_f32_16x16x32_bf16 v[26:29], v[154:157], v[200:203], v[26:29]
	v_mfma_f32_16x16x32_bf16 v[26:29], v[158:161], v[204:207], v[26:29]
	v_mfma_f32_16x16x32_bf16 v[18:21], v[146:149], v[208:211], v[18:21]
	v_mfma_f32_16x16x32_bf16 v[18:21], v[150:153], v[212:215], v[18:21]
	v_mfma_f32_16x16x32_bf16 v[10:13], v[154:157], v[208:211], v[10:13]
	v_mfma_f32_16x16x32_bf16 v[10:13], v[158:161], v[212:215], v[10:13]
	v_mfma_f32_16x16x32_bf16 v[54:57], v[162:165], v[184:187], v[54:57]
	v_mfma_f32_16x16x32_bf16 v[54:57], v[166:169], v[188:191], v[54:57]
	v_mfma_f32_16x16x32_bf16 v[46:49], v[170:173], v[184:187], v[46:49]
	v_mfma_f32_16x16x32_bf16 v[46:49], v[180:183], v[188:191], v[46:49]
	v_mfma_f32_16x16x32_bf16 v[38:41], v[162:165], v[192:195], v[38:41]
	v_mfma_f32_16x16x32_bf16 v[38:41], v[166:169], v[196:199], v[38:41]
	v_mfma_f32_16x16x32_bf16 v[30:33], v[170:173], v[192:195], v[30:33]
	v_mfma_f32_16x16x32_bf16 v[30:33], v[180:183], v[196:199], v[30:33]
	v_mfma_f32_16x16x32_bf16 v[22:25], v[162:165], v[200:203], v[22:25]
	v_mfma_f32_16x16x32_bf16 v[22:25], v[166:169], v[204:207], v[22:25]
	v_mfma_f32_16x16x32_bf16 v[14:17], v[170:173], v[200:203], v[14:17]
	v_mfma_f32_16x16x32_bf16 v[14:17], v[180:183], v[204:207], v[14:17]
	v_mfma_f32_16x16x32_bf16 v[6:9], v[162:165], v[208:211], v[6:9]
	v_mfma_f32_16x16x32_bf16 v[6:9], v[166:169], v[212:215], v[6:9]
	v_mfma_f32_16x16x32_bf16 v[2:5], v[170:173], v[208:211], v[2:5]
	v_mfma_f32_16x16x32_bf16 v[2:5], v[180:183], v[212:215], v[2:5]
	s_barrier
	s_setprio 0
	s_add_i32 s39, s39, 2
	s_add_u32 s12, s12, 0x100
	s_addc_u32 s13, s13, 0
	s_add_u32 s37, s37, 0x100
	s_addc_u32 s38, s38, 0
	s_cmp_gt_u32 s39, 29
	s_cbranch_scc0 .LBB0_2513
	v_readlane_b32 s12, v252, 14
	v_readlane_b32 s13, v252, 15
	s_and_b64 vcc, exec, s[12:13]
	s_cbranch_vccz .LBB0_2516
	s_barrier

; #define PG8_STAGE(bufoff, gbase, voff) do { _Pragma("unroll") for (int _i = 0; _i < 2; ++_i) \
;         __builtin_amdgcn_global_load_lds((const unsigned*)((const char*)(gbase) + (voff)[_i]), (LAS unsigned*)(lds + (bufoff) + ldsw + _i * 8192), 16, 0, 0); } while (0)
; #define PG8_LDA(dst, b, h) do { _Pragma("unroll") for (int m = 0; m < 4; ++m) _Pragma("unroll") for (int k = 0; k < 2; ++k) dst[m][k] = *(const LAS bf16x8*)(lds + PG8_SA(b, h) + aoff + m * 2048 + k * 1024); } while (0)
; #define PG8_LDB(dst, b, h) do { _Pragma("unroll") for (int n = 0; n < 2; ++n) _Pragma("unroll") for (int k = 0; k < 2; ++k) dst[n][k] = *(const LAS bf16x8*)(lds + PG8_SB(b, h) + boff + n * 2048 + k * 1024); } while (0)
; #define PG8_MMA(ai, bj, At, Bt) do { __builtin_amdgcn_s_setprio(1); _Pragma("unroll") for (int m = 0; m < 4; ++m) _Pragma("unroll") for (int n = 0; n < 2; ++n) _Pragma("unroll") for (int k = 0; k < 2; ++k) \
;         acc[ai][bj][m][n] = __builtin_amdgcn_mfma_f32_16x16x32_bf16(Bt[n][k], At[m][k], acc[ai][bj][m][n], 0, 0, 0); __builtin_amdgcn_s_setprio(0); } while (0)
; #define PG8_WAIT_V(n) asm volatile("s_waitcnt vmcnt(" #n ")" ::: "memory")
; template <class Epi, class Sched, int LDA, int LDB, bool ALIGN_EPI = true>
; __device__ __forceinline__ void gemm_phase(LAS unsigned char* lds, const Gemm g, const Sched& S, const Epi& E, int wave) {
;     ...
;         for (int t = 0; t < nt; t += 2) {
;             const bool last = (t == nt - 2);
;             const char* a1 = cA + (size_t)(t + 1) * kstep;
;             const char* a2 = last ? nA : cA + (size_t)(t + 2) * kstep; const char* b2 = last ? nB : cB + (size_t)(t + 2) * kstep;
;             const char* a3 = a2 + kstep; const char* b3 = b2 + kstep;
;             PG8_LDB(B0, 0, 0); PG8_LDB(B1, 0, 1); PG8_SCHED; PG8_LDA(At, 0, 0); PG8_STAGE(PG8_SA(1, 1), a1 + hstepA, voffA);
;             PG8_WAIT_V(8); PG8_WAIT_L(0); PG8_BAR; PG8_MMA(0, 0, At, B0); PG8_MMA(0, 1, At, B1); PG8_BAR; PG8_SCHED;
;             PG8_LDA(At, 0, 1); PG8_STAGE(PG8_SB(0, 0), b2, voffB); PG8_STAGE(PG8_SB(0, 1), b2 + hstepB, voffB); PG8_STAGE(PG8_SA(0, 0), a2, voffA);
;             PG8_WAIT_V(8); PG8_WAIT_L(0); PG8_BAR; PG8_MMA(1, 0, At, B0); PG8_MMA(1, 1, At, B1); PG8_BAR; PG8_SCHED;
;             PG8_LDB(B0, 1, 0); PG8_LDB(B1, 1, 1); PG8_SCHED; PG8_LDA(At, 1, 0); PG8_STAGE(PG8_SA(0, 1), a2 + hstepA, voffA);
.LBB0_2551:
	s_add_u32 s2, s0, 0x100
	s_addc_u32 s3, s1, 0
	s_add_i32 s50, 0, 0x10000
	s_cmp_eq_u32 s49, 8
	s_cselect_b32 s17, s11, s3
	s_cselect_b32 s16, s10, s2
	v_add_u32_e32 v0, s50, v154
	s_cselect_b32 s15, s13, s47
	s_cselect_b32 s14, s12, s46
	s_add_i32 s51, 0, 0x14000
	ds_read_b128 v[130:133], v0
	ds_read_b128 v[148:151], v0 offset:1024
	ds_read_b128 v[158:161], v0 offset:2048
	ds_read_b128 v[162:165], v0 offset:3072
	v_add_u32_e32 v0, s51, v154
	ds_read_b128 v[166:169], v0
	ds_read_b128 v[170:173], v0 offset:1024
	ds_read_b128 v[180:183], v0 offset:2048
	ds_read_b128 v[184:187], v0 offset:3072
	v_lshl_add_u64 v[152:153], s[0:1], 0, v[144:145]
	s_add_i32 m0, s28, 0xc000
	ds_read_b128 v[188:191], v156
	ds_read_b128 v[192:195], v156 offset:1024
	ds_read_b128 v[196:199], v156 offset:2048
	ds_read_b128 v[200:203], v156 offset:3072
	ds_read_b128 v[204:207], v156 offset:4096
	ds_read_b128 v[208:211], v156 offset:5120
	ds_read_b128 v[212:215], v156 offset:6144
	ds_read_b128 v[216:219], v156 offset:7168
	global_load_lds_dwordx4 v[152:153], off
	v_lshl_add_u64 v[152:153], s[0:1], 0, v[146:147]
	s_add_i32 m0, s28, 0xe000
	s_nop 0
	global_load_lds_dwordx4 v[152:153], off
	s_waitcnt vmcnt(8)
	s_waitcnt lgkmcnt(0)
	s_setprio 1
	s_barrier
	v_mfma_f32_16x16x32_bf16 v[126:129], v[130:133], v[188:191], v[126:129]
	v_mfma_f32_16x16x32_bf16 v[126:129], v[148:151], v[192:195], v[126:129]
	v_mfma_f32_16x16x32_bf16 v[122:125], v[158:161], v[188:191], v[122:125]
	v_mfma_f32_16x16x32_bf16 v[122:125], v[162:165], v[192:195], v[122:125]
	v_mfma_f32_16x16x32_bf16 v[118:121], v[130:133], v[196:199], v[118:121]
	v_mfma_f32_16x16x32_bf16 v[118:121], v[148:151], v[200:203], v[118:121]
	v_mfma_f32_16x16x32_bf16 v[114:117], v[158:161], v[196:199], v[114:117]
	v_mfma_f32_16x16x32_bf16 v[114:117], v[162:165], v[200:203], v[114:117]
	v_mfma_f32_16x16x32_bf16 v[110:113], v[130:133], v[204:207], v[110:113]
	v_mfma_f32_16x16x32_bf16 v[110:113], v[148:151], v[208:211], v[110:113]
	v_mfma_f32_16x16x32_bf16 v[106:109], v[158:161], v[204:207], v[106:109]
	v_mfma_f32_16x16x32_bf16 v[106:109], v[162:165], v[208:211], v[106:109]
	v_mfma_f32_16x16x32_bf16 v[102:105], v[130:133], v[212:215], v[102:105]
	v_mfma_f32_16x16x32_bf16 v[102:105], v[148:151], v[216:219], v[102:105]
	v_mfma_f32_16x16x32_bf16 v[98:101], v[158:161], v[212:215], v[98:101]
	v_mfma_f32_16x16x32_bf16 v[98:101], v[162:165], v[216:219], v[98:101]
	v_mfma_f32_16x16x32_bf16 v[62:65], v[166:169], v[188:191], v[62:65]
	v_mfma_f32_16x16x32_bf16 v[62:65], v[170:173], v[192:195], v[62:65]
	v_mfma_f32_16x16x32_bf16 v[58:61], v[180:183], v[188:191], v[58:61]
	v_mfma_f32_16x16x32_bf16 v[58:61], v[184:187], v[192:195], v[58:61]
	v_mfma_f32_16x16x32_bf16 v[54:57], v[166:169], v[196:199], v[54:57]
	v_mfma_f32_16x16x32_bf16 v[54:57], v[170:173], v[200:203], v[54:57]
	v_mfma_f32_16x16x32_bf16 v[50:53], v[180:183], v[196:199], v[50:53]
	v_mfma_f32_16x16x32_bf16 v[50:53], v[184:187], v[200:203], v[50:53]
	v_mfma_f32_16x16x32_bf16 v[46:49], v[166:169], v[204:207], v[46:49]
	v_mfma_f32_16x16x32_bf16 v[46:49], v[170:173], v[208:211], v[46:49]
	v_mfma_f32_16x16x32_bf16 v[42:45], v[180:183], v[204:207], v[42:45]
	v_mfma_f32_16x16x32_bf16 v[42:45], v[184:187], v[208:211], v[42:45]
	v_mfma_f32_16x16x32_bf16 v[38:41], v[166:169], v[212:215], v[38:41]
	v_mfma_f32_16x16x32_bf16 v[38:41], v[170:173], v[216:219], v[38:41]
	v_mfma_f32_16x16x32_bf16 v[34:37], v[180:183], v[212:215], v[34:37]
	v_mfma_f32_16x16x32_bf16 v[34:37], v[184:187], v[216:219], v[34:37]
	s_barrier
	s_setprio 0
	s_add_i32 s0, s50, s54
	v_lshl_add_u64 v[152:153], s[14:15], 0, v[136:137]
	s_mov_b32 m0, s0
	ds_read_b128 v[188:191], v156 offset:16384
	ds_read_b128 v[192:195], v156 offset:17408
	ds_read_b128 v[196:199], v156 offset:18432
	ds_read_b128 v[200:203], v156 offset:19456
	ds_read_b128 v[204:207], v156 offset:20480
	ds_read_b128 v[208:211], v156 offset:21504
	ds_read_b128 v[212:215], v156 offset:22528
	ds_read_b128 v[216:219], v156 offset:23552
	global_load_lds_dwordx4 v[152:153], off
	s_add_i32 m0, s0, 0x2000
	s_add_u32 s0, s14, 0x30000
	v_lshl_add_u64 v[174:175], s[14:15], 0, v[140:141]
	s_addc_u32 s1, s15, 0
	s_add_i32 s50, s51, s54
	global_load_lds_dwordx4 v[174:175], off
	v_lshl_add_u64 v[220:221], s[0:1], 0, v[136:137]
	s_mov_b32 m0, s50
	v_lshl_add_u64 v[222:223], s[16:17], 0, v[138:139]
	global_load_lds_dwordx4 v[220:221], off
	v_lshl_add_u64 v[220:221], s[0:1], 0, v[140:141]
	s_add_i32 m0, s50, 0x2000
	s_nop 0
	global_load_lds_dwordx4 v[220:221], off
	v_lshl_add_u64 v[220:221], s[16:17], 0, v[134:135]
	s_mov_b32 m0, s28
	s_nop 0
	global_load_lds_dwordx4 v[220:221], off
	s_mov_b32 m0, s29
	s_nop 0
	global_load_lds_dwordx4 v[222:223], off
	s_waitcnt vmcnt(8)
	s_waitcnt lgkmcnt(0)
	s_setprio 1
	s_barrier
; #define PG8_STAGE(bufoff, gbase, voff) do { _Pragma("unroll") for (int _i = 0; _i < 2; ++_i) \
;         __builtin_amdgcn_global_load_lds((const unsigned*)((const char*)(gbase) + (voff)[_i]), (LAS unsigned*)(lds + (bufoff) + ldsw + _i * 8192), 16, 0, 0); } while (0)
; #define PG8_LDA(dst, b, h) do { _Pragma("unroll") for (int m = 0; m < 4; ++m) _Pragma("unroll") for (int k = 0; k < 2; ++k) dst[m][k] = *(const LAS bf16x8*)(lds + PG8_SA(b, h) + aoff + m * 2048 + k * 1024); } while (0)
; #define PG8_LDB(dst, b, h) do { _Pragma("unroll") for (int n = 0; n < 2; ++n) _Pragma("unroll") for (int k = 0; k < 2; ++k) dst[n][k] = *(const LAS bf16x8*)(lds + PG8_SB(b, h) + boff + n * 2048 + k * 1024); } while (0)
; #define PG8_MMA(ai, bj, At, Bt) do { __builtin_amdgcn_s_setprio(1); _Pragma("unroll") for (int m = 0; m < 4; ++m) _Pragma("unroll") for (int n = 0; n < 2; ++n) _Pragma("unroll") for (int k = 0; k < 2; ++k) \
;         acc[ai][bj][m][n] = __builtin_amdgcn_mfma_f32_16x16x32_bf16(Bt[n][k], At[m][k], acc[ai][bj][m][n], 0, 0, 0); __builtin_amdgcn_s_setprio(0); } while (0)
; #define PG8_WAIT_V(n) asm volatile("s_waitcnt vmcnt(" #n ")" ::: "memory")
; #define PG8_WAIT_L(n) asm volatile("s_waitcnt lgkmcnt(" #n ")" ::: "memory")
; #define PG8_BAR __builtin_amdgcn_s_barrier()
; #define PG8_SCHED __builtin_amdgcn_sched_barrier(0)
; template <class Epi, class Sched, int LDA, int LDB, bool ALIGN_EPI = true>
; __device__ __forceinline__ void gemm_phase(LAS unsigned char* lds, const Gemm g, const Sched& S, const Epi& E, int wave) {
;     ...
;             PG8_WAIT_V(8); PG8_WAIT_L(0); PG8_BAR; PG8_MMA(1, 0, At, B0); PG8_MMA(1, 1, At, B1); PG8_BAR; PG8_SCHED;
;             PG8_LDB(B0, 1, 0); PG8_LDB(B1, 1, 1); PG8_SCHED; PG8_LDA(At, 1, 0); PG8_STAGE(PG8_SA(0, 1), a2 + hstepA, voffA);
;             PG8_WAIT_V(8); PG8_WAIT_L(0); PG8_BAR; PG8_MMA(0, 0, At, B0); PG8_MMA(0, 1, At, B1); PG8_BAR; PG8_SCHED;
	v_mfma_f32_16x16x32_bf16 v[94:97], v[130:133], v[188:191], v[94:97]
	v_mfma_f32_16x16x32_bf16 v[94:97], v[148:151], v[192:195], v[94:97]
	v_mfma_f32_16x16x32_bf16 v[90:93], v[158:161], v[188:191], v[90:93]
	v_mfma_f32_16x16x32_bf16 v[90:93], v[162:165], v[192:195], v[90:93]
	v_mfma_f32_16x16x32_bf16 v[86:89], v[130:133], v[196:199], v[86:89]
	v_mfma_f32_16x16x32_bf16 v[86:89], v[148:151], v[200:203], v[86:89]
	v_mfma_f32_16x16x32_bf16 v[82:85], v[158:161], v[196:199], v[82:85]
	v_mfma_f32_16x16x32_bf16 v[82:85], v[162:165], v[200:203], v[82:85]
	v_mfma_f32_16x16x32_bf16 v[78:81], v[130:133], v[204:207], v[78:81]
	v_mfma_f32_16x16x32_bf16 v[78:81], v[148:151], v[208:211], v[78:81]
	v_mfma_f32_16x16x32_bf16 v[74:77], v[158:161], v[204:207], v[74:77]
	v_mfma_f32_16x16x32_bf16 v[74:77], v[162:165], v[208:211], v[74:77]
	v_mfma_f32_16x16x32_bf16 v[70:73], v[130:133], v[212:215], v[70:73]
	v_mfma_f32_16x16x32_bf16 v[70:73], v[148:151], v[216:219], v[70:73]
	v_mfma_f32_16x16x32_bf16 v[66:69], v[158:161], v[212:215], v[66:69]
	v_mfma_f32_16x16x32_bf16 v[66:69], v[162:165], v[216:219], v[66:69]
	v_mfma_f32_16x16x32_bf16 v[30:33], v[166:169], v[188:191], v[30:33]
	v_mfma_f32_16x16x32_bf16 v[30:33], v[170:173], v[192:195], v[30:33]
	v_mfma_f32_16x16x32_bf16 v[26:29], v[180:183], v[188:191], v[26:29]
	v_mfma_f32_16x16x32_bf16 v[26:29], v[184:187], v[192:195], v[26:29]
	v_mfma_f32_16x16x32_bf16 v[22:25], v[166:169], v[196:199], v[22:25]
	v_mfma_f32_16x16x32_bf16 v[22:25], v[170:173], v[200:203], v[22:25]
	v_mfma_f32_16x16x32_bf16 v[18:21], v[180:183], v[196:199], v[18:21]
	v_mfma_f32_16x16x32_bf16 v[18:21], v[184:187], v[200:203], v[18:21]
	v_mfma_f32_16x16x32_bf16 v[14:17], v[166:169], v[204:207], v[14:17]
	v_mfma_f32_16x16x32_bf16 v[14:17], v[170:173], v[208:211], v[14:17]
	v_mfma_f32_16x16x32_bf16 v[10:13], v[180:183], v[204:207], v[10:13]
	v_mfma_f32_16x16x32_bf16 v[10:13], v[184:187], v[208:211], v[10:13]
	v_mfma_f32_16x16x32_bf16 v[6:9], v[166:169], v[212:215], v[6:9]
	v_mfma_f32_16x16x32_bf16 v[6:9], v[170:173], v[216:219], v[6:9]
	v_mfma_f32_16x16x32_bf16 v[2:5], v[180:183], v[212:215], v[2:5]
	v_mfma_f32_16x16x32_bf16 v[2:5], v[184:187], v[216:219], v[2:5]
	s_barrier
	s_setprio 0
	s_add_i32 s50, 0, 0x18000
	v_add_u32_e32 v0, s50, v154
	s_add_i32 s51, 0, 0x1c000
	ds_read_b128 v[130:133], v0
	ds_read_b128 v[148:151], v0 offset:1024
	ds_read_b128 v[158:161], v0 offset:2048
	ds_read_b128 v[162:165], v0 offset:3072
	v_add_u32_e32 v0, s51, v154
	ds_read_b128 v[166:169], v0
	ds_read_b128 v[170:173], v0 offset:1024
	ds_read_b128 v[180:183], v0 offset:2048
	ds_read_b128 v[184:187], v0 offset:3072
	s_add_u32 s0, s16, 0x30000
	s_addc_u32 s1, s17, 0
	s_mov_b32 m0, s34
	v_lshl_add_u64 v[224:225], s[0:1], 0, v[134:135]
	ds_read_b128 v[188:191], v156 offset:32768
	ds_read_b128 v[192:195], v156 offset:33792
	ds_read_b128 v[196:199], v156 offset:34816
	ds_read_b128 v[200:203], v156 offset:35840
	ds_read_b128 v[204:207], v156 offset:36864
	ds_read_b128 v[208:211], v156 offset:37888
	ds_read_b128 v[212:215], v156 offset:38912
	ds_read_b128 v[216:219], v156 offset:39936
	global_load_lds_dwordx4 v[224:225], off
	v_lshl_add_u64 v[224:225], s[0:1], 0, v[138:139]
	s_mov_b32 m0, s35
	s_nop 0
	global_load_lds_dwordx4 v[224:225], off
	s_waitcnt vmcnt(8)
	s_waitcnt lgkmcnt(0)
	s_setprio 1
	s_barrier
	v_mfma_f32_16x16x32_bf16 v[126:129], v[130:133], v[188:191], v[126:129]
	v_mfma_f32_16x16x32_bf16 v[126:129], v[148:151], v[192:195], v[126:129]
	v_mfma_f32_16x16x32_bf16 v[122:125], v[158:161], v[188:191], v[122:125]
	v_mfma_f32_16x16x32_bf16 v[122:125], v[162:165], v[192:195], v[122:125]
	v_mfma_f32_16x16x32_bf16 v[118:121], v[130:133], v[196:199], v[118:121]
	v_mfma_f32_16x16x32_bf16 v[118:121], v[148:151], v[200:203], v[118:121]
	v_mfma_f32_16x16x32_bf16 v[114:117], v[158:161], v[196:199], v[114:117]
	v_mfma_f32_16x16x32_bf16 v[114:117], v[162:165], v[200:203], v[114:117]
	v_mfma_f32_16x16x32_bf16 v[110:113], v[130:133], v[204:207], v[110:113]
	v_mfma_f32_16x16x32_bf16 v[110:113], v[148:151], v[208:211], v[110:113]
	v_mfma_f32_16x16x32_bf16 v[106:109], v[158:161], v[204:207], v[106:109]
	v_mfma_f32_16x16x32_bf16 v[106:109], v[162:165], v[208:211], v[106:109]
	v_mfma_f32_16x16x32_bf16 v[102:105], v[130:133], v[212:215], v[102:105]
	v_mfma_f32_16x16x32_bf16 v[102:105], v[148:151], v[216:219], v[102:105]
	v_mfma_f32_16x16x32_bf16 v[98:101], v[158:161], v[212:215], v[98:101]
	v_mfma_f32_16x16x32_bf16 v[98:101], v[162:165], v[216:219], v[98:101]
	v_mfma_f32_16x16x32_bf16 v[62:65], v[166:169], v[188:191], v[62:65]
	v_mfma_f32_16x16x32_bf16 v[62:65], v[170:173], v[192:195], v[62:65]
	v_mfma_f32_16x16x32_bf16 v[58:61], v[180:183], v[188:191], v[58:61]
	v_mfma_f32_16x16x32_bf16 v[58:61], v[184:187], v[192:195], v[58:61]
	v_mfma_f32_16x16x32_bf16 v[54:57], v[166:169], v[196:199], v[54:57]
	v_mfma_f32_16x16x32_bf16 v[54:57], v[170:173], v[200:203], v[54:57]
	v_mfma_f32_16x16x32_bf16 v[50:53], v[180:183], v[196:199], v[50:53]
	v_mfma_f32_16x16x32_bf16 v[50:53], v[184:187], v[200:203], v[50:53]
	v_mfma_f32_16x16x32_bf16 v[46:49], v[166:169], v[204:207], v[46:49]
	v_mfma_f32_16x16x32_bf16 v[46:49], v[170:173], v[208:211], v[46:49]
	v_mfma_f32_16x16x32_bf16 v[42:45], v[180:183], v[204:207], v[42:45]
	v_mfma_f32_16x16x32_bf16 v[42:45], v[184:187], v[208:211], v[42:45]
	v_mfma_f32_16x16x32_bf16 v[38:41], v[166:169], v[212:215], v[38:41]
	v_mfma_f32_16x16x32_bf16 v[38:41], v[170:173], v[216:219], v[38:41]
	v_mfma_f32_16x16x32_bf16 v[34:37], v[180:183], v[212:215], v[34:37]
	v_mfma_f32_16x16x32_bf16 v[34:37], v[184:187], v[216:219], v[34:37]
	s_barrier
; #define PG8_STAGE(bufoff, gbase, voff) do { _Pragma("unroll") for (int _i = 0; _i < 2; ++_i) \
;         __builtin_amdgcn_global_load_lds((const unsigned*)((const char*)(gbase) + (voff)[_i]), (LAS unsigned*)(lds + (bufoff) + ldsw + _i * 8192), 16, 0, 0); } while (0)
; #define PG8_LDA(dst, b, h) do { _Pragma("unroll") for (int m = 0; m < 4; ++m) _Pragma("unroll") for (int k = 0; k < 2; ++k) dst[m][k] = *(const LAS bf16x8*)(lds + PG8_SA(b, h) + aoff + m * 2048 + k * 1024); } while (0)
; #define PG8_MMA(ai, bj, At, Bt) do { __builtin_amdgcn_s_setprio(1); _Pragma("unroll") for (int m = 0; m < 4; ++m) _Pragma("unroll") for (int n = 0; n < 2; ++n) _Pragma("unroll") for (int k = 0; k < 2; ++k) \
;         acc[ai][bj][m][n] = __builtin_amdgcn_mfma_f32_16x16x32_bf16(Bt[n][k], At[m][k], acc[ai][bj][m][n], 0, 0, 0); __builtin_amdgcn_s_setprio(0); } while (0)
; #define PG8_WAIT_V(n) asm volatile("s_waitcnt vmcnt(" #n ")" ::: "memory")
; #define PG8_WAIT_L(n) asm volatile("s_waitcnt lgkmcnt(" #n ")" ::: "memory")
; #define PG8_BAR __builtin_amdgcn_s_barrier()
; #define PG8_SCHED __builtin_amdgcn_sched_barrier(0)
; template <class Epi, class Sched, int LDA, int LDB, bool ALIGN_EPI = true>
; __device__ __forceinline__ void gemm_phase(LAS unsigned char* lds, const Gemm g, const Sched& S, const Epi& E, int wave) {
;     ...
;             PG8_LDA(At, 1, 1); PG8_STAGE(PG8_SB(1, 0), b3, voffB); PG8_STAGE(PG8_SB(1, 1), b3 + hstepB, voffB); PG8_STAGE(PG8_SA(1, 0), a3, voffA);
;             PG8_WAIT_V(8); PG8_WAIT_L(0); PG8_BAR; PG8_MMA(1, 0, At, B0); PG8_MMA(1, 1, At, B1); PG8_BAR; PG8_SCHED;
;         }
	s_setprio 0
	s_add_i32 s0, s50, s54
	v_lshl_add_u64 v[152:153], v[152:153], 0, s[72:73]
	s_mov_b32 m0, s0
	ds_read_b128 v[188:191], v156 offset:49152
	ds_read_b128 v[192:195], v156 offset:50176
	ds_read_b128 v[196:199], v156 offset:51200
	ds_read_b128 v[200:203], v156 offset:52224
	ds_read_b128 v[204:207], v156 offset:53248
	ds_read_b128 v[208:211], v156 offset:54272
	ds_read_b128 v[212:215], v156 offset:55296
	ds_read_b128 v[216:219], v156 offset:56320
	global_load_lds_dwordx4 v[152:153], off
	s_add_i32 m0, s0, 0x2000
	s_add_u32 s0, s14, 0x30080
	v_lshl_add_u64 v[152:153], v[174:175], 0, s[72:73]
	s_addc_u32 s1, s15, 0
	s_add_i32 s14, s51, s54
	global_load_lds_dwordx4 v[152:153], off
	v_lshl_add_u64 v[152:153], s[0:1], 0, v[136:137]
	s_mov_b32 m0, s14
	s_nop 0
	global_load_lds_dwordx4 v[152:153], off
	v_lshl_add_u64 v[152:153], s[0:1], 0, v[140:141]
	s_add_i32 m0, s14, 0x2000
	s_nop 0
	global_load_lds_dwordx4 v[152:153], off
	v_lshl_add_u64 v[152:153], v[220:221], 0, s[72:73]
	s_mov_b32 m0, s36
	s_nop 0
	global_load_lds_dwordx4 v[152:153], off
	v_lshl_add_u64 v[152:153], v[222:223], 0, s[72:73]
	s_mov_b32 m0, s37
	s_nop 0
	global_load_lds_dwordx4 v[152:153], off
	s_waitcnt vmcnt(8)
	s_waitcnt lgkmcnt(0)
	s_setprio 1
	s_barrier
	v_mfma_f32_16x16x32_bf16 v[94:97], v[130:133], v[188:191], v[94:97]
	v_mfma_f32_16x16x32_bf16 v[94:97], v[148:151], v[192:195], v[94:97]
	v_mfma_f32_16x16x32_bf16 v[90:93], v[158:161], v[188:191], v[90:93]
	v_mfma_f32_16x16x32_bf16 v[90:93], v[162:165], v[192:195], v[90:93]
	v_mfma_f32_16x16x32_bf16 v[86:89], v[130:133], v[196:199], v[86:89]
	v_mfma_f32_16x16x32_bf16 v[86:89], v[148:151], v[200:203], v[86:89]
	v_mfma_f32_16x16x32_bf16 v[82:85], v[158:161], v[196:199], v[82:85]
	v_mfma_f32_16x16x32_bf16 v[82:85], v[162:165], v[200:203], v[82:85]
	v_mfma_f32_16x16x32_bf16 v[78:81], v[130:133], v[204:207], v[78:81]
	v_mfma_f32_16x16x32_bf16 v[78:81], v[148:151], v[208:211], v[78:81]
	v_mfma_f32_16x16x32_bf16 v[74:77], v[158:161], v[204:207], v[74:77]
	v_mfma_f32_16x16x32_bf16 v[74:77], v[162:165], v[208:211], v[74:77]
	v_mfma_f32_16x16x32_bf16 v[70:73], v[130:133], v[212:215], v[70:73]
	v_mfma_f32_16x16x32_bf16 v[70:73], v[148:151], v[216:219], v[70:73]
	v_mfma_f32_16x16x32_bf16 v[66:69], v[158:161], v[212:215], v[66:69]
	v_mfma_f32_16x16x32_bf16 v[66:69], v[162:165], v[216:219], v[66:69]
	v_mfma_f32_16x16x32_bf16 v[30:33], v[166:169], v[188:191], v[30:33]
	v_mfma_f32_16x16x32_bf16 v[30:33], v[170:173], v[192:195], v[30:33]
	v_mfma_f32_16x16x32_bf16 v[26:29], v[180:183], v[188:191], v[26:29]
	v_mfma_f32_16x16x32_bf16 v[26:29], v[184:187], v[192:195], v[26:29]
	v_mfma_f32_16x16x32_bf16 v[22:25], v[166:169], v[196:199], v[22:25]
	v_mfma_f32_16x16x32_bf16 v[22:25], v[170:173], v[200:203], v[22:25]
	v_mfma_f32_16x16x32_bf16 v[18:21], v[180:183], v[196:199], v[18:21]
	v_mfma_f32_16x16x32_bf16 v[18:21], v[184:187], v[200:203], v[18:21]
	v_mfma_f32_16x16x32_bf16 v[14:17], v[166:169], v[204:207], v[14:17]
	v_mfma_f32_16x16x32_bf16 v[14:17], v[170:173], v[208:211], v[14:17]
	v_mfma_f32_16x16x32_bf16 v[10:13], v[180:183], v[204:207], v[10:13]
	v_mfma_f32_16x16x32_bf16 v[10:13], v[184:187], v[208:211], v[10:13]
	v_mfma_f32_16x16x32_bf16 v[6:9], v[166:169], v[212:215], v[6:9]
	v_mfma_f32_16x16x32_bf16 v[6:9], v[170:173], v[216:219], v[6:9]
	v_mfma_f32_16x16x32_bf16 v[2:5], v[180:183], v[212:215], v[2:5]
	v_mfma_f32_16x16x32_bf16 v[2:5], v[184:187], v[216:219], v[2:5]
	s_barrier
	s_setprio 0
	s_add_i32 s49, s49, 2
	s_add_u32 s46, s46, 0x100
	s_addc_u32 s47, s47, 0
	s_cmp_gt_u32 s49, 9
	s_mov_b64 s[0:1], s[2:3]
	s_cbranch_scc0 .LBB0_2551
	v_readlane_b32 s0, v252, 14
	v_readlane_b32 s1, v252, 15
	s_and_b64 vcc, exec, s[0:1]
	s_cbranch_vccz .LBB0_2554
	s_barrier

; #define PG8_STAGE(bufoff, gbase, voff) do { _Pragma("unroll") for (int _i = 0; _i < 2; ++_i) \
;         __builtin_amdgcn_global_load_lds((const unsigned*)((const char*)(gbase) + (voff)[_i]), (LAS unsigned*)(lds + (bufoff) + ldsw + _i * 8192), 16, 0, 0); } while (0)
; #define PG8_LDA(dst, b, h) do { _Pragma("unroll") for (int m = 0; m < 4; ++m) _Pragma("unroll") for (int k = 0; k < 2; ++k) dst[m][k] = *(const LAS bf16x8*)(lds + PG8_SA(b, h) + aoff + m * 2048 + k * 1024); } while (0)
; #define PG8_LDB(dst, b, h) do { _Pragma("unroll") for (int n = 0; n < 2; ++n) _Pragma("unroll") for (int k = 0; k < 2; ++k) dst[n][k] = *(const LAS bf16x8*)(lds + PG8_SB(b, h) + boff + n * 2048 + k * 1024); } while (0)
; #define PG8_MMA(ai, bj, At, Bt) do { __builtin_amdgcn_s_setprio(1); _Pragma("unroll") for (int m = 0; m < 4; ++m) _Pragma("unroll") for (int n = 0; n < 2; ++n) _Pragma("unroll") for (int k = 0; k < 2; ++k) \
;         acc[ai][bj][m][n] = __builtin_amdgcn_mfma_f32_16x16x32_bf16(Bt[n][k], At[m][k], acc[ai][bj][m][n], 0, 0, 0); __builtin_amdgcn_s_setprio(0); } while (0)
; #define PG8_WAIT_V(n) asm volatile("s_waitcnt vmcnt(" #n ")" ::: "memory")
; template <class Epi, class Sched, int LDA, int LDB, bool ALIGN_EPI = true>
; __device__ __forceinline__ void gemm_phase(LAS unsigned char* lds, const Gemm g, const Sched& S, const Epi& E, int wave) {
;     ...
;         for (int t = 0; t < nt; t += 2) {
;             const bool last = (t == nt - 2);
;             const char* a1 = cA + (size_t)(t + 1) * kstep;
;             const char* a2 = last ? nA : cA + (size_t)(t + 2) * kstep; const char* b2 = last ? nB : cB + (size_t)(t + 2) * kstep;
;             const char* a3 = a2 + kstep; const char* b3 = b2 + kstep;
;             PG8_LDB(B0, 0, 0); PG8_LDB(B1, 0, 1); PG8_SCHED; PG8_LDA(At, 0, 0); PG8_STAGE(PG8_SA(1, 1), a1 + hstepA, voffA);
;             PG8_WAIT_V(8); PG8_WAIT_L(0); PG8_BAR; PG8_MMA(0, 0, At, B0); PG8_MMA(0, 1, At, B1); PG8_BAR; PG8_SCHED;
;             PG8_LDA(At, 0, 1); PG8_STAGE(PG8_SB(0, 0), b2, voffB); PG8_STAGE(PG8_SB(0, 1), b2 + hstepB, voffB); PG8_STAGE(PG8_SA(0, 0), a2, voffA);
;             PG8_WAIT_V(8); PG8_WAIT_L(0); PG8_BAR; PG8_MMA(1, 0, At, B0); PG8_MMA(1, 1, At, B1); PG8_BAR; PG8_SCHED;
;             PG8_LDB(B0, 1, 0); PG8_LDB(B1, 1, 1); PG8_SCHED; PG8_LDA(At, 1, 0); PG8_STAGE(PG8_SA(0, 1), a2 + hstepA, voffA);
.LBB0_2619:
	s_add_u32 s16, s14, 0xfffe0080
	s_addc_u32 s17, s15, -1
	s_add_i32 s53, 0, 0x10000
	s_cmp_eq_u32 s52, 4
	s_cselect_b32 s19, s7, s17
	s_cselect_b32 s18, s13, s16
	v_add_u32_e32 v0, s53, v150
	s_cselect_b32 s17, s3, s51
	s_cselect_b32 s16, s44, s45
	s_add_i32 s58, 0, 0x14000
	ds_read_b128 v[144:147], v0
	ds_read_b128 v[152:155], v0 offset:1024
	ds_read_b128 v[156:159], v0 offset:2048
	ds_read_b128 v[160:163], v0 offset:3072
	v_add_u32_e32 v0, s58, v150
	ds_read_b128 v[164:167], v0
	ds_read_b128 v[168:171], v0 offset:1024
	ds_read_b128 v[172:175], v0 offset:2048
	ds_read_b128 v[180:183], v0 offset:3072
	v_lshl_add_u64 v[148:149], s[14:15], 0, v[140:141]
	s_add_i32 m0, s36, 0xc000
	ds_read_b128 v[184:187], v151
	ds_read_b128 v[188:191], v151 offset:1024
	ds_read_b128 v[192:195], v151 offset:2048
	ds_read_b128 v[196:199], v151 offset:3072
	ds_read_b128 v[200:203], v151 offset:4096
	ds_read_b128 v[204:207], v151 offset:5120
	ds_read_b128 v[208:211], v151 offset:6144
	ds_read_b128 v[212:215], v151 offset:7168
	global_load_lds_dwordx4 v[148:149], off
	v_lshl_add_u64 v[148:149], s[14:15], 0, v[142:143]
	s_add_i32 m0, s36, 0xe000
	s_nop 0
	global_load_lds_dwordx4 v[148:149], off
	s_waitcnt vmcnt(8)
	s_waitcnt lgkmcnt(0)
	s_setprio 1
	s_barrier
	v_mfma_f32_16x16x32_bf16 v[126:129], v[144:147], v[184:187], v[126:129]
	v_mfma_f32_16x16x32_bf16 v[126:129], v[152:155], v[188:191], v[126:129]
	v_mfma_f32_16x16x32_bf16 v[122:125], v[156:159], v[184:187], v[122:125]
	v_mfma_f32_16x16x32_bf16 v[122:125], v[160:163], v[188:191], v[122:125]
	v_mfma_f32_16x16x32_bf16 v[118:121], v[144:147], v[192:195], v[118:121]
	v_mfma_f32_16x16x32_bf16 v[118:121], v[152:155], v[196:199], v[118:121]
	v_mfma_f32_16x16x32_bf16 v[114:117], v[156:159], v[192:195], v[114:117]
	v_mfma_f32_16x16x32_bf16 v[114:117], v[160:163], v[196:199], v[114:117]
	v_mfma_f32_16x16x32_bf16 v[110:113], v[144:147], v[200:203], v[110:113]
	v_mfma_f32_16x16x32_bf16 v[110:113], v[152:155], v[204:207], v[110:113]
	v_mfma_f32_16x16x32_bf16 v[106:109], v[156:159], v[200:203], v[106:109]
	v_mfma_f32_16x16x32_bf16 v[106:109], v[160:163], v[204:207], v[106:109]
	v_mfma_f32_16x16x32_bf16 v[102:105], v[144:147], v[208:211], v[102:105]
	v_mfma_f32_16x16x32_bf16 v[102:105], v[152:155], v[212:215], v[102:105]
	v_mfma_f32_16x16x32_bf16 v[98:101], v[156:159], v[208:211], v[98:101]
	v_mfma_f32_16x16x32_bf16 v[98:101], v[160:163], v[212:215], v[98:101]
	v_mfma_f32_16x16x32_bf16 v[62:65], v[164:167], v[184:187], v[62:65]
	v_mfma_f32_16x16x32_bf16 v[62:65], v[168:171], v[188:191], v[62:65]
	v_mfma_f32_16x16x32_bf16 v[58:61], v[172:175], v[184:187], v[58:61]
	v_mfma_f32_16x16x32_bf16 v[58:61], v[180:183], v[188:191], v[58:61]
	v_mfma_f32_16x16x32_bf16 v[54:57], v[164:167], v[192:195], v[54:57]
	v_mfma_f32_16x16x32_bf16 v[54:57], v[168:171], v[196:199], v[54:57]
	v_mfma_f32_16x16x32_bf16 v[50:53], v[172:175], v[192:195], v[50:53]
	v_mfma_f32_16x16x32_bf16 v[50:53], v[180:183], v[196:199], v[50:53]
	v_mfma_f32_16x16x32_bf16 v[46:49], v[164:167], v[200:203], v[46:49]
	v_mfma_f32_16x16x32_bf16 v[46:49], v[168:171], v[204:207], v[46:49]
	v_mfma_f32_16x16x32_bf16 v[42:45], v[172:175], v[200:203], v[42:45]
	v_mfma_f32_16x16x32_bf16 v[42:45], v[180:183], v[204:207], v[42:45]
	v_mfma_f32_16x16x32_bf16 v[38:41], v[164:167], v[208:211], v[38:41]
	v_mfma_f32_16x16x32_bf16 v[38:41], v[168:171], v[212:215], v[38:41]
	v_mfma_f32_16x16x32_bf16 v[34:37], v[172:175], v[208:211], v[34:37]
	v_mfma_f32_16x16x32_bf16 v[34:37], v[180:183], v[212:215], v[34:37]
	s_barrier
	s_setprio 0
	s_add_i32 s53, s53, s59
	v_lshl_add_u64 v[148:149], s[16:17], 0, v[132:133]
	s_mov_b32 m0, s53
	ds_read_b128 v[184:187], v151 offset:16384
	ds_read_b128 v[188:191], v151 offset:17408
	ds_read_b128 v[192:195], v151 offset:18432
	ds_read_b128 v[196:199], v151 offset:19456
	ds_read_b128 v[200:203], v151 offset:20480
	ds_read_b128 v[204:207], v151 offset:21504
	ds_read_b128 v[208:211], v151 offset:22528
	ds_read_b128 v[212:215], v151 offset:23552
	global_load_lds_dwordx4 v[148:149], off
	s_add_i32 m0, s53, 0x2000
	s_add_u32 s54, s16, 0x20000
	v_lshl_add_u64 v[216:217], s[16:17], 0, v[136:137]
	s_addc_u32 s55, s17, 0
	s_add_i32 s53, s58, s59
	global_load_lds_dwordx4 v[216:217], off
	v_lshl_add_u64 v[218:219], s[54:55], 0, v[132:133]
	s_mov_b32 m0, s53
	v_lshl_add_u64 v[220:221], s[18:19], 0, v[134:135]
	global_load_lds_dwordx4 v[218:219], off
	v_lshl_add_u64 v[218:219], s[54:55], 0, v[136:137]
	s_add_i32 m0, s53, 0x2000
	s_nop 0
	global_load_lds_dwordx4 v[218:219], off
	v_lshl_add_u64 v[218:219], s[18:19], 0, v[130:131]
	s_mov_b32 m0, s36
	s_nop 0
	global_load_lds_dwordx4 v[218:219], off
	s_mov_b32 m0, s37
	s_nop 0
	global_load_lds_dwordx4 v[220:221], off
	s_waitcnt vmcnt(8)
	s_waitcnt lgkmcnt(0)
	s_setprio 1
	s_barrier
; #define PG8_STAGE(bufoff, gbase, voff) do { _Pragma("unroll") for (int _i = 0; _i < 2; ++_i) \
;         __builtin_amdgcn_global_load_lds((const unsigned*)((const char*)(gbase) + (voff)[_i]), (LAS unsigned*)(lds + (bufoff) + ldsw + _i * 8192), 16, 0, 0); } while (0)
; #define PG8_LDA(dst, b, h) do { _Pragma("unroll") for (int m = 0; m < 4; ++m) _Pragma("unroll") for (int k = 0; k < 2; ++k) dst[m][k] = *(const LAS bf16x8*)(lds + PG8_SA(b, h) + aoff + m * 2048 + k * 1024); } while (0)
; #define PG8_LDB(dst, b, h) do { _Pragma("unroll") for (int n = 0; n < 2; ++n) _Pragma("unroll") for (int k = 0; k < 2; ++k) dst[n][k] = *(const LAS bf16x8*)(lds + PG8_SB(b, h) + boff + n * 2048 + k * 1024); } while (0)
; #define PG8_MMA(ai, bj, At, Bt) do { __builtin_amdgcn_s_setprio(1); _Pragma("unroll") for (int m = 0; m < 4; ++m) _Pragma("unroll") for (int n = 0; n < 2; ++n) _Pragma("unroll") for (int k = 0; k < 2; ++k) \
;         acc[ai][bj][m][n] = __builtin_amdgcn_mfma_f32_16x16x32_bf16(Bt[n][k], At[m][k], acc[ai][bj][m][n], 0, 0, 0); __builtin_amdgcn_s_setprio(0); } while (0)
; #define PG8_WAIT_V(n) asm volatile("s_waitcnt vmcnt(" #n ")" ::: "memory")
; #define PG8_WAIT_L(n) asm volatile("s_waitcnt lgkmcnt(" #n ")" ::: "memory")
; #define PG8_BAR __builtin_amdgcn_s_barrier()
; #define PG8_SCHED __builtin_amdgcn_sched_barrier(0)
; template <class Epi, class Sched, int LDA, int LDB, bool ALIGN_EPI = true>
; __device__ __forceinline__ void gemm_phase(LAS unsigned char* lds, const Gemm g, const Sched& S, const Epi& E, int wave) {
;     ...
;             PG8_WAIT_V(8); PG8_WAIT_L(0); PG8_BAR; PG8_MMA(1, 0, At, B0); PG8_MMA(1, 1, At, B1); PG8_BAR; PG8_SCHED;
;             PG8_LDB(B0, 1, 0); PG8_LDB(B1, 1, 1); PG8_SCHED; PG8_LDA(At, 1, 0); PG8_STAGE(PG8_SA(0, 1), a2 + hstepA, voffA);
;             PG8_WAIT_V(8); PG8_WAIT_L(0); PG8_BAR; PG8_MMA(0, 0, At, B0); PG8_MMA(0, 1, At, B1); PG8_BAR; PG8_SCHED;
	v_mfma_f32_16x16x32_bf16 v[94:97], v[144:147], v[184:187], v[94:97]
	v_mfma_f32_16x16x32_bf16 v[94:97], v[152:155], v[188:191], v[94:97]
	v_mfma_f32_16x16x32_bf16 v[90:93], v[156:159], v[184:187], v[90:93]
	v_mfma_f32_16x16x32_bf16 v[90:93], v[160:163], v[188:191], v[90:93]
	v_mfma_f32_16x16x32_bf16 v[86:89], v[144:147], v[192:195], v[86:89]
	v_mfma_f32_16x16x32_bf16 v[86:89], v[152:155], v[196:199], v[86:89]
	v_mfma_f32_16x16x32_bf16 v[82:85], v[156:159], v[192:195], v[82:85]
	v_mfma_f32_16x16x32_bf16 v[82:85], v[160:163], v[196:199], v[82:85]
	v_mfma_f32_16x16x32_bf16 v[78:81], v[144:147], v[200:203], v[78:81]
	v_mfma_f32_16x16x32_bf16 v[78:81], v[152:155], v[204:207], v[78:81]
	v_mfma_f32_16x16x32_bf16 v[74:77], v[156:159], v[200:203], v[74:77]
	v_mfma_f32_16x16x32_bf16 v[74:77], v[160:163], v[204:207], v[74:77]
	v_mfma_f32_16x16x32_bf16 v[70:73], v[144:147], v[208:211], v[70:73]
	v_mfma_f32_16x16x32_bf16 v[70:73], v[152:155], v[212:215], v[70:73]
	v_mfma_f32_16x16x32_bf16 v[66:69], v[156:159], v[208:211], v[66:69]
	v_mfma_f32_16x16x32_bf16 v[66:69], v[160:163], v[212:215], v[66:69]
	v_mfma_f32_16x16x32_bf16 v[30:33], v[164:167], v[184:187], v[30:33]
	v_mfma_f32_16x16x32_bf16 v[30:33], v[168:171], v[188:191], v[30:33]
	v_mfma_f32_16x16x32_bf16 v[26:29], v[172:175], v[184:187], v[26:29]
	v_mfma_f32_16x16x32_bf16 v[26:29], v[180:183], v[188:191], v[26:29]
	v_mfma_f32_16x16x32_bf16 v[22:25], v[164:167], v[192:195], v[22:25]
	v_mfma_f32_16x16x32_bf16 v[22:25], v[168:171], v[196:199], v[22:25]
	v_mfma_f32_16x16x32_bf16 v[18:21], v[172:175], v[192:195], v[18:21]
	v_mfma_f32_16x16x32_bf16 v[18:21], v[180:183], v[196:199], v[18:21]
	v_mfma_f32_16x16x32_bf16 v[14:17], v[164:167], v[200:203], v[14:17]
	v_mfma_f32_16x16x32_bf16 v[14:17], v[168:171], v[204:207], v[14:17]
	v_mfma_f32_16x16x32_bf16 v[10:13], v[172:175], v[200:203], v[10:13]
	v_mfma_f32_16x16x32_bf16 v[10:13], v[180:183], v[204:207], v[10:13]
	v_mfma_f32_16x16x32_bf16 v[6:9], v[164:167], v[208:211], v[6:9]
	v_mfma_f32_16x16x32_bf16 v[6:9], v[168:171], v[212:215], v[6:9]
	v_mfma_f32_16x16x32_bf16 v[2:5], v[172:175], v[208:211], v[2:5]
	v_mfma_f32_16x16x32_bf16 v[2:5], v[180:183], v[212:215], v[2:5]
	s_barrier
	s_setprio 0
	s_add_i32 s53, 0, 0x18000
	v_add_u32_e32 v0, s53, v150
	s_add_i32 s54, 0, 0x1c000
	ds_read_b128 v[144:147], v0
	ds_read_b128 v[152:155], v0 offset:1024
	ds_read_b128 v[156:159], v0 offset:2048
	ds_read_b128 v[160:163], v0 offset:3072
	v_add_u32_e32 v0, s54, v150
	ds_read_b128 v[164:167], v0
	ds_read_b128 v[168:171], v0 offset:1024
	ds_read_b128 v[172:175], v0 offset:2048
	ds_read_b128 v[180:183], v0 offset:3072
	s_add_u32 s18, s18, 0x20000
	s_addc_u32 s19, s19, 0
	s_mov_b32 m0, s38
	v_lshl_add_u64 v[222:223], s[18:19], 0, v[130:131]
	ds_read_b128 v[184:187], v151 offset:32768
	ds_read_b128 v[188:191], v151 offset:33792
	ds_read_b128 v[192:195], v151 offset:34816
	ds_read_b128 v[196:199], v151 offset:35840
	ds_read_b128 v[200:203], v151 offset:36864
	ds_read_b128 v[204:207], v151 offset:37888
	ds_read_b128 v[208:211], v151 offset:38912
	ds_read_b128 v[212:215], v151 offset:39936
	global_load_lds_dwordx4 v[222:223], off
	v_lshl_add_u64 v[222:223], s[18:19], 0, v[134:135]
	s_mov_b32 m0, s39
	s_nop 0
	global_load_lds_dwordx4 v[222:223], off
	s_waitcnt vmcnt(8)
	s_waitcnt lgkmcnt(0)
	s_setprio 1
	s_barrier
	v_mfma_f32_16x16x32_bf16 v[126:129], v[144:147], v[184:187], v[126:129]
	v_mfma_f32_16x16x32_bf16 v[126:129], v[152:155], v[188:191], v[126:129]
	v_mfma_f32_16x16x32_bf16 v[122:125], v[156:159], v[184:187], v[122:125]
	v_mfma_f32_16x16x32_bf16 v[122:125], v[160:163], v[188:191], v[122:125]
	v_mfma_f32_16x16x32_bf16 v[118:121], v[144:147], v[192:195], v[118:121]
	v_mfma_f32_16x16x32_bf16 v[118:121], v[152:155], v[196:199], v[118:121]
	v_mfma_f32_16x16x32_bf16 v[114:117], v[156:159], v[192:195], v[114:117]
	v_mfma_f32_16x16x32_bf16 v[114:117], v[160:163], v[196:199], v[114:117]
	v_mfma_f32_16x16x32_bf16 v[110:113], v[144:147], v[200:203], v[110:113]
	v_mfma_f32_16x16x32_bf16 v[110:113], v[152:155], v[204:207], v[110:113]
	v_mfma_f32_16x16x32_bf16 v[106:109], v[156:159], v[200:203], v[106:109]
	v_mfma_f32_16x16x32_bf16 v[106:109], v[160:163], v[204:207], v[106:109]
	v_mfma_f32_16x16x32_bf16 v[102:105], v[144:147], v[208:211], v[102:105]
	v_mfma_f32_16x16x32_bf16 v[102:105], v[152:155], v[212:215], v[102:105]
	v_mfma_f32_16x16x32_bf16 v[98:101], v[156:159], v[208:211], v[98:101]
	v_mfma_f32_16x16x32_bf16 v[98:101], v[160:163], v[212:215], v[98:101]
	v_mfma_f32_16x16x32_bf16 v[62:65], v[164:167], v[184:187], v[62:65]
	v_mfma_f32_16x16x32_bf16 v[62:65], v[168:171], v[188:191], v[62:65]
	v_mfma_f32_16x16x32_bf16 v[58:61], v[172:175], v[184:187], v[58:61]
	v_mfma_f32_16x16x32_bf16 v[58:61], v[180:183], v[188:191], v[58:61]
	v_mfma_f32_16x16x32_bf16 v[54:57], v[164:167], v[192:195], v[54:57]
	v_mfma_f32_16x16x32_bf16 v[54:57], v[168:171], v[196:199], v[54:57]
	v_mfma_f32_16x16x32_bf16 v[50:53], v[172:175], v[192:195], v[50:53]
	v_mfma_f32_16x16x32_bf16 v[50:53], v[180:183], v[196:199], v[50:53]
	v_mfma_f32_16x16x32_bf16 v[46:49], v[164:167], v[200:203], v[46:49]
	v_mfma_f32_16x16x32_bf16 v[46:49], v[168:171], v[204:207], v[46:49]
	v_mfma_f32_16x16x32_bf16 v[42:45], v[172:175], v[200:203], v[42:45]
	v_mfma_f32_16x16x32_bf16 v[42:45], v[180:183], v[204:207], v[42:45]
	v_mfma_f32_16x16x32_bf16 v[38:41], v[164:167], v[208:211], v[38:41]
	v_mfma_f32_16x16x32_bf16 v[38:41], v[168:171], v[212:215], v[38:41]
	v_mfma_f32_16x16x32_bf16 v[34:37], v[172:175], v[208:211], v[34:37]
	v_mfma_f32_16x16x32_bf16 v[34:37], v[180:183], v[212:215], v[34:37]
	s_barrier
; #define PG8_STAGE(bufoff, gbase, voff) do { _Pragma("unroll") for (int _i = 0; _i < 2; ++_i) \
;         __builtin_amdgcn_global_load_lds((const unsigned*)((const char*)(gbase) + (voff)[_i]), (LAS unsigned*)(lds + (bufoff) + ldsw + _i * 8192), 16, 0, 0); } while (0)
; #define PG8_LDA(dst, b, h) do { _Pragma("unroll") for (int m = 0; m < 4; ++m) _Pragma("unroll") for (int k = 0; k < 2; ++k) dst[m][k] = *(const LAS bf16x8*)(lds + PG8_SA(b, h) + aoff + m * 2048 + k * 1024); } while (0)
; #define PG8_MMA(ai, bj, At, Bt) do { __builtin_amdgcn_s_setprio(1); _Pragma("unroll") for (int m = 0; m < 4; ++m) _Pragma("unroll") for (int n = 0; n < 2; ++n) _Pragma("unroll") for (int k = 0; k < 2; ++k) \
;         acc[ai][bj][m][n] = __builtin_amdgcn_mfma_f32_16x16x32_bf16(Bt[n][k], At[m][k], acc[ai][bj][m][n], 0, 0, 0); __builtin_amdgcn_s_setprio(0); } while (0)
; #define PG8_WAIT_V(n) asm volatile("s_waitcnt vmcnt(" #n ")" ::: "memory")
; #define PG8_WAIT_L(n) asm volatile("s_waitcnt lgkmcnt(" #n ")" ::: "memory")
; #define PG8_BAR __builtin_amdgcn_s_barrier()
; #define PG8_SCHED __builtin_amdgcn_sched_barrier(0)
; template <class Epi, class Sched, int LDA, int LDB, bool ALIGN_EPI = true>
; __device__ __forceinline__ void gemm_phase(LAS unsigned char* lds, const Gemm g, const Sched& S, const Epi& E, int wave) {
;     ...
;             PG8_LDA(At, 1, 1); PG8_STAGE(PG8_SB(1, 0), b3, voffB); PG8_STAGE(PG8_SB(1, 1), b3 + hstepB, voffB); PG8_STAGE(PG8_SA(1, 0), a3, voffA);
;             PG8_WAIT_V(8); PG8_WAIT_L(0); PG8_BAR; PG8_MMA(1, 0, At, B0); PG8_MMA(1, 1, At, B1); PG8_BAR; PG8_SCHED;
;         }
	s_setprio 0
	s_add_i32 s18, s53, s59
	v_lshl_add_u64 v[148:149], v[148:149], 0, s[70:71]
	s_mov_b32 m0, s18
	ds_read_b128 v[184:187], v151 offset:49152
	ds_read_b128 v[188:191], v151 offset:50176
	ds_read_b128 v[192:195], v151 offset:51200
	ds_read_b128 v[196:199], v151 offset:52224
	ds_read_b128 v[200:203], v151 offset:53248
	ds_read_b128 v[204:207], v151 offset:54272
	ds_read_b128 v[208:211], v151 offset:55296
	ds_read_b128 v[212:215], v151 offset:56320
	global_load_lds_dwordx4 v[148:149], off
	s_add_i32 m0, s18, 0x2000
	s_add_u32 s16, s16, 0x20080
	v_lshl_add_u64 v[148:149], v[216:217], 0, s[70:71]
	s_addc_u32 s17, s17, 0
	s_add_i32 s18, s54, s59
	global_load_lds_dwordx4 v[148:149], off
	v_lshl_add_u64 v[148:149], s[16:17], 0, v[132:133]
	s_mov_b32 m0, s18
	s_nop 0
	global_load_lds_dwordx4 v[148:149], off
	v_lshl_add_u64 v[148:149], s[16:17], 0, v[136:137]
	s_add_i32 m0, s18, 0x2000
	s_nop 0
	global_load_lds_dwordx4 v[148:149], off
	v_lshl_add_u64 v[148:149], v[218:219], 0, s[70:71]
	s_mov_b32 m0, s46
	s_nop 0
	global_load_lds_dwordx4 v[148:149], off
	v_lshl_add_u64 v[148:149], v[220:221], 0, s[70:71]
	s_mov_b32 m0, s47
	s_nop 0
	global_load_lds_dwordx4 v[148:149], off
	s_waitcnt vmcnt(8)
	s_waitcnt lgkmcnt(0)
	s_setprio 1
	s_barrier
	v_mfma_f32_16x16x32_bf16 v[94:97], v[144:147], v[184:187], v[94:97]
	v_mfma_f32_16x16x32_bf16 v[94:97], v[152:155], v[188:191], v[94:97]
	v_mfma_f32_16x16x32_bf16 v[90:93], v[156:159], v[184:187], v[90:93]
	v_mfma_f32_16x16x32_bf16 v[90:93], v[160:163], v[188:191], v[90:93]
	v_mfma_f32_16x16x32_bf16 v[86:89], v[144:147], v[192:195], v[86:89]
	v_mfma_f32_16x16x32_bf16 v[86:89], v[152:155], v[196:199], v[86:89]
	v_mfma_f32_16x16x32_bf16 v[82:85], v[156:159], v[192:195], v[82:85]
	v_mfma_f32_16x16x32_bf16 v[82:85], v[160:163], v[196:199], v[82:85]
	v_mfma_f32_16x16x32_bf16 v[78:81], v[144:147], v[200:203], v[78:81]
	v_mfma_f32_16x16x32_bf16 v[78:81], v[152:155], v[204:207], v[78:81]
	v_mfma_f32_16x16x32_bf16 v[74:77], v[156:159], v[200:203], v[74:77]
	v_mfma_f32_16x16x32_bf16 v[74:77], v[160:163], v[204:207], v[74:77]
	v_mfma_f32_16x16x32_bf16 v[70:73], v[144:147], v[208:211], v[70:73]
	v_mfma_f32_16x16x32_bf16 v[70:73], v[152:155], v[212:215], v[70:73]
	v_mfma_f32_16x16x32_bf16 v[66:69], v[156:159], v[208:211], v[66:69]
	v_mfma_f32_16x16x32_bf16 v[66:69], v[160:163], v[212:215], v[66:69]
	v_mfma_f32_16x16x32_bf16 v[30:33], v[164:167], v[184:187], v[30:33]
	v_mfma_f32_16x16x32_bf16 v[30:33], v[168:171], v[188:191], v[30:33]
	v_mfma_f32_16x16x32_bf16 v[26:29], v[172:175], v[184:187], v[26:29]
	v_mfma_f32_16x16x32_bf16 v[26:29], v[180:183], v[188:191], v[26:29]
	v_mfma_f32_16x16x32_bf16 v[22:25], v[164:167], v[192:195], v[22:25]
	v_mfma_f32_16x16x32_bf16 v[22:25], v[168:171], v[196:199], v[22:25]
	v_mfma_f32_16x16x32_bf16 v[18:21], v[172:175], v[192:195], v[18:21]
	v_mfma_f32_16x16x32_bf16 v[18:21], v[180:183], v[196:199], v[18:21]
	v_mfma_f32_16x16x32_bf16 v[14:17], v[164:167], v[200:203], v[14:17]
	v_mfma_f32_16x16x32_bf16 v[14:17], v[168:171], v[204:207], v[14:17]
	v_mfma_f32_16x16x32_bf16 v[10:13], v[172:175], v[200:203], v[10:13]
	v_mfma_f32_16x16x32_bf16 v[10:13], v[180:183], v[204:207], v[10:13]
	v_mfma_f32_16x16x32_bf16 v[6:9], v[164:167], v[208:211], v[6:9]
	v_mfma_f32_16x16x32_bf16 v[6:9], v[168:171], v[212:215], v[6:9]
	v_mfma_f32_16x16x32_bf16 v[2:5], v[172:175], v[208:211], v[2:5]
	v_mfma_f32_16x16x32_bf16 v[2:5], v[180:183], v[212:215], v[2:5]
	s_barrier
	s_setprio 0
	s_add_i32 s52, s52, 2
	s_add_u32 s14, s14, 0x100
	s_addc_u32 s15, s15, 0
	s_add_u32 s45, s45, 0x100
	s_addc_u32 s51, s51, 0
	s_cmp_gt_u32 s52, 5
	s_cbranch_scc0 .LBB0_2619
	v_readlane_b32 s14, v252, 14
	v_readlane_b32 s15, v252, 15
	s_and_b64 vcc, exec, s[14:15]
	s_cbranch_vccz .LBB0_2622
	s_barrier

; #define PG8_STAGE(bufoff, gbase, voff) do { _Pragma("unroll") for (int _i = 0; _i < 2; ++_i) \
;         __builtin_amdgcn_global_load_lds((const unsigned*)((const char*)(gbase) + (voff)[_i]), (LAS unsigned*)(lds + (bufoff) + ldsw + _i * 8192), 16, 0, 0); } while (0)
; #define PG8_LDA(dst, b, h) do { _Pragma("unroll") for (int m = 0; m < 4; ++m) _Pragma("unroll") for (int k = 0; k < 2; ++k) dst[m][k] = *(const LAS bf16x8*)(lds + PG8_SA(b, h) + aoff + m * 2048 + k * 1024); } while (0)
; #define PG8_LDB(dst, b, h) do { _Pragma("unroll") for (int n = 0; n < 2; ++n) _Pragma("unroll") for (int k = 0; k < 2; ++k) dst[n][k] = *(const LAS bf16x8*)(lds + PG8_SB(b, h) + boff + n * 2048 + k * 1024); } while (0)
; #define PG8_MMA(ai, bj, At, Bt) do { __builtin_amdgcn_s_setprio(1); _Pragma("unroll") for (int m = 0; m < 4; ++m) _Pragma("unroll") for (int n = 0; n < 2; ++n) _Pragma("unroll") for (int k = 0; k < 2; ++k) \
;         acc[ai][bj][m][n] = __builtin_amdgcn_mfma_f32_16x16x32_bf16(Bt[n][k], At[m][k], acc[ai][bj][m][n], 0, 0, 0); __builtin_amdgcn_s_setprio(0); } while (0)
; #define PG8_WAIT_V(n) asm volatile("s_waitcnt vmcnt(" #n ")" ::: "memory")
; template <class Epi, class Sched, int LDA, int LDB, bool ALIGN_EPI = true>
; __device__ __forceinline__ void gemm_phase(LAS unsigned char* lds, const Gemm g, const Sched& S, const Epi& E, int wave) {
;     ...
;         for (int t = 0; t < nt; t += 2) {
;             const bool last = (t == nt - 2);
;             const char* a1 = cA + (size_t)(t + 1) * kstep;
;             const char* a2 = last ? nA : cA + (size_t)(t + 2) * kstep; const char* b2 = last ? nB : cB + (size_t)(t + 2) * kstep;
;             const char* a3 = a2 + kstep; const char* b3 = b2 + kstep;
;             PG8_LDB(B0, 0, 0); PG8_LDB(B1, 0, 1); PG8_SCHED; PG8_LDA(At, 0, 0); PG8_STAGE(PG8_SA(1, 1), a1 + hstepA, voffA);
;             PG8_WAIT_V(8); PG8_WAIT_L(0); PG8_BAR; PG8_MMA(0, 0, At, B0); PG8_MMA(0, 1, At, B1); PG8_BAR; PG8_SCHED;
;             PG8_LDA(At, 0, 1); PG8_STAGE(PG8_SB(0, 0), b2, voffB); PG8_STAGE(PG8_SB(0, 1), b2 + hstepB, voffB); PG8_STAGE(PG8_SA(0, 0), a2, voffA);
;             PG8_WAIT_V(8); PG8_WAIT_L(0); PG8_BAR; PG8_MMA(1, 0, At, B0); PG8_MMA(1, 1, At, B1); PG8_BAR; PG8_SCHED;
;             PG8_LDB(B0, 1, 0); PG8_LDB(B1, 1, 1); PG8_SCHED; PG8_LDA(At, 1, 0); PG8_STAGE(PG8_SA(0, 1), a2 + hstepA, voffA);
.LBB0_2649:
	s_add_u32 s18, s16, 0xfffe0080
	s_addc_u32 s19, s17, -1
	s_add_i32 s48, 0, 0x10000
	s_cmp_eq_u32 s47, 4
	s_cselect_b32 s25, s7, s19
	s_cselect_b32 s24, s13, s18
	s_cselect_b32 s19, s3, s46
	s_cselect_b32 s18, s44, s45
	s_add_i32 s50, 0, 0x14000
	v_add_u32_e32 v152, s48, v161
	v_add_u32_e32 v172, s50, v161
	ds_read_b128 v[130:133], v152
	ds_read_b128 v[134:137], v152 offset:1024
	ds_read_b128 v[148:151], v152 offset:2048
	ds_read_b128 v[152:155], v152 offset:3072
	ds_read_b128 v[156:159], v172
	ds_read_b128 v[164:167], v172 offset:1024
	ds_read_b128 v[168:171], v172 offset:2048
	ds_read_b128 v[172:175], v172 offset:3072
	v_lshl_add_u64 v[212:213], s[16:17], 0, v[144:145]
	s_add_i32 m0, s15, 0xc000
	ds_read_b128 v[180:183], v163
	ds_read_b128 v[184:187], v163 offset:1024
	ds_read_b128 v[188:191], v163 offset:2048
	ds_read_b128 v[192:195], v163 offset:3072
	ds_read_b128 v[196:199], v163 offset:4096
	ds_read_b128 v[200:203], v163 offset:5120
	ds_read_b128 v[204:207], v163 offset:6144
	ds_read_b128 v[208:211], v163 offset:7168
	global_load_lds_dwordx4 v[212:213], off
	v_lshl_add_u64 v[212:213], s[16:17], 0, v[146:147]
	s_add_i32 m0, s15, 0xe000
	s_nop 0
	global_load_lds_dwordx4 v[212:213], off
	s_waitcnt vmcnt(8)
	s_waitcnt lgkmcnt(0)
	s_setprio 1
	s_barrier
	v_mfma_f32_16x16x32_bf16 v[126:129], v[130:133], v[180:183], v[126:129]
	v_mfma_f32_16x16x32_bf16 v[126:129], v[134:137], v[184:187], v[126:129]
	v_mfma_f32_16x16x32_bf16 v[122:125], v[148:151], v[180:183], v[122:125]
	v_mfma_f32_16x16x32_bf16 v[122:125], v[152:155], v[184:187], v[122:125]
	v_mfma_f32_16x16x32_bf16 v[110:113], v[130:133], v[188:191], v[110:113]
	v_mfma_f32_16x16x32_bf16 v[110:113], v[134:137], v[192:195], v[110:113]
	v_mfma_f32_16x16x32_bf16 v[106:109], v[148:151], v[188:191], v[106:109]
	v_mfma_f32_16x16x32_bf16 v[106:109], v[152:155], v[192:195], v[106:109]
	v_mfma_f32_16x16x32_bf16 v[94:97], v[130:133], v[196:199], v[94:97]
	v_mfma_f32_16x16x32_bf16 v[94:97], v[134:137], v[200:203], v[94:97]
	v_mfma_f32_16x16x32_bf16 v[90:93], v[148:151], v[196:199], v[90:93]
	v_mfma_f32_16x16x32_bf16 v[90:93], v[152:155], v[200:203], v[90:93]
	v_mfma_f32_16x16x32_bf16 v[78:81], v[130:133], v[204:207], v[78:81]
	v_mfma_f32_16x16x32_bf16 v[78:81], v[134:137], v[208:211], v[78:81]
	v_mfma_f32_16x16x32_bf16 v[74:77], v[148:151], v[204:207], v[74:77]
	v_mfma_f32_16x16x32_bf16 v[74:77], v[152:155], v[208:211], v[74:77]
	v_mfma_f32_16x16x32_bf16 v[118:121], v[156:159], v[180:183], v[118:121]
	v_mfma_f32_16x16x32_bf16 v[118:121], v[164:167], v[184:187], v[118:121]
	v_mfma_f32_16x16x32_bf16 v[114:117], v[168:171], v[180:183], v[114:117]
	v_mfma_f32_16x16x32_bf16 v[114:117], v[172:175], v[184:187], v[114:117]
	v_mfma_f32_16x16x32_bf16 v[102:105], v[156:159], v[188:191], v[102:105]
	v_mfma_f32_16x16x32_bf16 v[102:105], v[164:167], v[192:195], v[102:105]
	v_mfma_f32_16x16x32_bf16 v[98:101], v[168:171], v[188:191], v[98:101]
	v_mfma_f32_16x16x32_bf16 v[98:101], v[172:175], v[192:195], v[98:101]
	v_mfma_f32_16x16x32_bf16 v[86:89], v[156:159], v[196:199], v[86:89]
	v_mfma_f32_16x16x32_bf16 v[86:89], v[164:167], v[200:203], v[86:89]
	v_mfma_f32_16x16x32_bf16 v[82:85], v[168:171], v[196:199], v[82:85]
	v_mfma_f32_16x16x32_bf16 v[82:85], v[172:175], v[200:203], v[82:85]
	v_mfma_f32_16x16x32_bf16 v[70:73], v[156:159], v[204:207], v[70:73]
	v_mfma_f32_16x16x32_bf16 v[70:73], v[164:167], v[208:211], v[70:73]
	v_mfma_f32_16x16x32_bf16 v[66:69], v[168:171], v[204:207], v[66:69]
	v_mfma_f32_16x16x32_bf16 v[66:69], v[172:175], v[208:211], v[66:69]
	s_barrier
	s_setprio 0
	s_add_i32 s48, s48, s51
	v_lshl_add_u64 v[212:213], s[18:19], 0, v[0:1]
	s_mov_b32 m0, s48
	ds_read_b128 v[180:183], v163 offset:16384
	ds_read_b128 v[184:187], v163 offset:17408
	ds_read_b128 v[188:191], v163 offset:18432
	ds_read_b128 v[192:195], v163 offset:19456
	ds_read_b128 v[196:199], v163 offset:20480
	ds_read_b128 v[200:203], v163 offset:21504
	ds_read_b128 v[204:207], v163 offset:22528
	ds_read_b128 v[208:211], v163 offset:23552
	global_load_lds_dwordx4 v[212:213], off
	s_add_i32 m0, s48, 0x2000
	s_add_u32 s48, s18, 0x20000
	v_lshl_add_u64 v[214:215], s[18:19], 0, v[142:143]
	s_addc_u32 s49, s19, 0
	s_add_i32 s50, s50, s51
	global_load_lds_dwordx4 v[214:215], off
	v_lshl_add_u64 v[216:217], s[48:49], 0, v[0:1]
	s_mov_b32 m0, s50
	v_lshl_add_u64 v[218:219], s[24:25], 0, v[140:141]
	global_load_lds_dwordx4 v[216:217], off
	v_lshl_add_u64 v[216:217], s[48:49], 0, v[142:143]
	s_add_i32 m0, s50, 0x2000
	s_nop 0
	global_load_lds_dwordx4 v[216:217], off
	v_lshl_add_u64 v[216:217], s[24:25], 0, v[138:139]
	s_mov_b32 m0, s15
	s_nop 0
	global_load_lds_dwordx4 v[216:217], off
	s_mov_b32 m0, s28
	s_nop 0
	global_load_lds_dwordx4 v[218:219], off
	s_waitcnt vmcnt(8)
	s_waitcnt lgkmcnt(0)
	s_setprio 1
	s_barrier
; #define PG8_STAGE(bufoff, gbase, voff) do { _Pragma("unroll") for (int _i = 0; _i < 2; ++_i) \
;         __builtin_amdgcn_global_load_lds((const unsigned*)((const char*)(gbase) + (voff)[_i]), (LAS unsigned*)(lds + (bufoff) + ldsw + _i * 8192), 16, 0, 0); } while (0)
; #define PG8_LDA(dst, b, h) do { _Pragma("unroll") for (int m = 0; m < 4; ++m) _Pragma("unroll") for (int k = 0; k < 2; ++k) dst[m][k] = *(const LAS bf16x8*)(lds + PG8_SA(b, h) + aoff + m * 2048 + k * 1024); } while (0)
; #define PG8_LDB(dst, b, h) do { _Pragma("unroll") for (int n = 0; n < 2; ++n) _Pragma("unroll") for (int k = 0; k < 2; ++k) dst[n][k] = *(const LAS bf16x8*)(lds + PG8_SB(b, h) + boff + n * 2048 + k * 1024); } while (0)
; #define PG8_MMA(ai, bj, At, Bt) do { __builtin_amdgcn_s_setprio(1); _Pragma("unroll") for (int m = 0; m < 4; ++m) _Pragma("unroll") for (int n = 0; n < 2; ++n) _Pragma("unroll") for (int k = 0; k < 2; ++k) \
;         acc[ai][bj][m][n] = __builtin_amdgcn_mfma_f32_16x16x32_bf16(Bt[n][k], At[m][k], acc[ai][bj][m][n], 0, 0, 0); __builtin_amdgcn_s_setprio(0); } while (0)
; #define PG8_WAIT_V(n) asm volatile("s_waitcnt vmcnt(" #n ")" ::: "memory")
; #define PG8_WAIT_L(n) asm volatile("s_waitcnt lgkmcnt(" #n ")" ::: "memory")
; #define PG8_BAR __builtin_amdgcn_s_barrier()
; #define PG8_SCHED __builtin_amdgcn_sched_barrier(0)
; template <class Epi, class Sched, int LDA, int LDB, bool ALIGN_EPI = true>
; __device__ __forceinline__ void gemm_phase(LAS unsigned char* lds, const Gemm g, const Sched& S, const Epi& E, int wave) {
;     ...
;             PG8_WAIT_V(8); PG8_WAIT_L(0); PG8_BAR; PG8_MMA(1, 0, At, B0); PG8_MMA(1, 1, At, B1); PG8_BAR; PG8_SCHED;
;             PG8_LDB(B0, 1, 0); PG8_LDB(B1, 1, 1); PG8_SCHED; PG8_LDA(At, 1, 0); PG8_STAGE(PG8_SA(0, 1), a2 + hstepA, voffA);
;             PG8_WAIT_V(8); PG8_WAIT_L(0); PG8_BAR; PG8_MMA(0, 0, At, B0); PG8_MMA(0, 1, At, B1); PG8_BAR; PG8_SCHED;
	v_mfma_f32_16x16x32_bf16 v[62:65], v[130:133], v[180:183], v[62:65]
	v_mfma_f32_16x16x32_bf16 v[62:65], v[134:137], v[184:187], v[62:65]
	v_mfma_f32_16x16x32_bf16 v[58:61], v[148:151], v[180:183], v[58:61]
	v_mfma_f32_16x16x32_bf16 v[58:61], v[152:155], v[184:187], v[58:61]
	v_mfma_f32_16x16x32_bf16 v[46:49], v[130:133], v[188:191], v[46:49]
	v_mfma_f32_16x16x32_bf16 v[46:49], v[134:137], v[192:195], v[46:49]
	v_mfma_f32_16x16x32_bf16 v[42:45], v[148:151], v[188:191], v[42:45]
	v_mfma_f32_16x16x32_bf16 v[42:45], v[152:155], v[192:195], v[42:45]
	v_mfma_f32_16x16x32_bf16 v[30:33], v[130:133], v[196:199], v[30:33]
	v_mfma_f32_16x16x32_bf16 v[30:33], v[134:137], v[200:203], v[30:33]
	v_mfma_f32_16x16x32_bf16 v[26:29], v[148:151], v[196:199], v[26:29]
	v_mfma_f32_16x16x32_bf16 v[26:29], v[152:155], v[200:203], v[26:29]
	v_mfma_f32_16x16x32_bf16 v[14:17], v[130:133], v[204:207], v[14:17]
	v_mfma_f32_16x16x32_bf16 v[14:17], v[134:137], v[208:211], v[14:17]
	v_mfma_f32_16x16x32_bf16 v[10:13], v[148:151], v[204:207], v[10:13]
	v_mfma_f32_16x16x32_bf16 v[10:13], v[152:155], v[208:211], v[10:13]
	v_mfma_f32_16x16x32_bf16 v[54:57], v[156:159], v[180:183], v[54:57]
	v_mfma_f32_16x16x32_bf16 v[54:57], v[164:167], v[184:187], v[54:57]
	v_mfma_f32_16x16x32_bf16 v[50:53], v[168:171], v[180:183], v[50:53]
	v_mfma_f32_16x16x32_bf16 v[50:53], v[172:175], v[184:187], v[50:53]
	v_mfma_f32_16x16x32_bf16 v[38:41], v[156:159], v[188:191], v[38:41]
	v_mfma_f32_16x16x32_bf16 v[38:41], v[164:167], v[192:195], v[38:41]
	v_mfma_f32_16x16x32_bf16 v[34:37], v[168:171], v[188:191], v[34:37]
	v_mfma_f32_16x16x32_bf16 v[34:37], v[172:175], v[192:195], v[34:37]
	v_mfma_f32_16x16x32_bf16 v[22:25], v[156:159], v[196:199], v[22:25]
	v_mfma_f32_16x16x32_bf16 v[22:25], v[164:167], v[200:203], v[22:25]
	v_mfma_f32_16x16x32_bf16 v[18:21], v[168:171], v[196:199], v[18:21]
	v_mfma_f32_16x16x32_bf16 v[18:21], v[172:175], v[200:203], v[18:21]
	v_mfma_f32_16x16x32_bf16 v[6:9], v[156:159], v[204:207], v[6:9]
	v_mfma_f32_16x16x32_bf16 v[6:9], v[164:167], v[208:211], v[6:9]
	v_mfma_f32_16x16x32_bf16 v[2:5], v[168:171], v[204:207], v[2:5]
	v_mfma_f32_16x16x32_bf16 v[2:5], v[172:175], v[208:211], v[2:5]
	s_barrier
	s_setprio 0
	s_add_i32 s48, 0, 0x18000
	s_add_i32 s49, 0, 0x1c000
	v_add_u32_e32 v152, s48, v161
	v_add_u32_e32 v172, s49, v161
	ds_read_b128 v[130:133], v152
	ds_read_b128 v[134:137], v152 offset:1024
	ds_read_b128 v[148:151], v152 offset:2048
	ds_read_b128 v[152:155], v152 offset:3072
	ds_read_b128 v[156:159], v172
	ds_read_b128 v[164:167], v172 offset:1024
	ds_read_b128 v[168:171], v172 offset:2048
	ds_read_b128 v[172:175], v172 offset:3072
	s_add_u32 s24, s24, 0x20000
	s_addc_u32 s25, s25, 0
	s_mov_b32 m0, s29
	v_lshl_add_u64 v[220:221], s[24:25], 0, v[138:139]
	ds_read_b128 v[180:183], v163 offset:32768
	ds_read_b128 v[184:187], v163 offset:33792
	ds_read_b128 v[188:191], v163 offset:34816
	ds_read_b128 v[192:195], v163 offset:35840
	ds_read_b128 v[196:199], v163 offset:36864
	ds_read_b128 v[200:203], v163 offset:37888
	ds_read_b128 v[204:207], v163 offset:38912
	ds_read_b128 v[208:211], v163 offset:39936
	global_load_lds_dwordx4 v[220:221], off
	v_lshl_add_u64 v[220:221], s[24:25], 0, v[140:141]
	s_mov_b32 m0, s34
	s_nop 0
	global_load_lds_dwordx4 v[220:221], off
	s_waitcnt vmcnt(8)
	s_waitcnt lgkmcnt(0)
	s_setprio 1
	s_barrier
	v_mfma_f32_16x16x32_bf16 v[126:129], v[130:133], v[180:183], v[126:129]
	v_mfma_f32_16x16x32_bf16 v[126:129], v[134:137], v[184:187], v[126:129]
	v_mfma_f32_16x16x32_bf16 v[122:125], v[148:151], v[180:183], v[122:125]
	v_mfma_f32_16x16x32_bf16 v[122:125], v[152:155], v[184:187], v[122:125]
	v_mfma_f32_16x16x32_bf16 v[110:113], v[130:133], v[188:191], v[110:113]
	v_mfma_f32_16x16x32_bf16 v[110:113], v[134:137], v[192:195], v[110:113]
	v_mfma_f32_16x16x32_bf16 v[106:109], v[148:151], v[188:191], v[106:109]
	v_mfma_f32_16x16x32_bf16 v[106:109], v[152:155], v[192:195], v[106:109]
	v_mfma_f32_16x16x32_bf16 v[94:97], v[130:133], v[196:199], v[94:97]
	v_mfma_f32_16x16x32_bf16 v[94:97], v[134:137], v[200:203], v[94:97]
	v_mfma_f32_16x16x32_bf16 v[90:93], v[148:151], v[196:199], v[90:93]
	v_mfma_f32_16x16x32_bf16 v[90:93], v[152:155], v[200:203], v[90:93]
	v_mfma_f32_16x16x32_bf16 v[78:81], v[130:133], v[204:207], v[78:81]
	v_mfma_f32_16x16x32_bf16 v[78:81], v[134:137], v[208:211], v[78:81]
	v_mfma_f32_16x16x32_bf16 v[74:77], v[148:151], v[204:207], v[74:77]
	v_mfma_f32_16x16x32_bf16 v[74:77], v[152:155], v[208:211], v[74:77]
	v_mfma_f32_16x16x32_bf16 v[118:121], v[156:159], v[180:183], v[118:121]
	v_mfma_f32_16x16x32_bf16 v[118:121], v[164:167], v[184:187], v[118:121]
	v_mfma_f32_16x16x32_bf16 v[114:117], v[168:171], v[180:183], v[114:117]
	v_mfma_f32_16x16x32_bf16 v[114:117], v[172:175], v[184:187], v[114:117]
	v_mfma_f32_16x16x32_bf16 v[102:105], v[156:159], v[188:191], v[102:105]
	v_mfma_f32_16x16x32_bf16 v[102:105], v[164:167], v[192:195], v[102:105]
	v_mfma_f32_16x16x32_bf16 v[98:101], v[168:171], v[188:191], v[98:101]
	v_mfma_f32_16x16x32_bf16 v[98:101], v[172:175], v[192:195], v[98:101]
	v_mfma_f32_16x16x32_bf16 v[86:89], v[156:159], v[196:199], v[86:89]
	v_mfma_f32_16x16x32_bf16 v[86:89], v[164:167], v[200:203], v[86:89]
	v_mfma_f32_16x16x32_bf16 v[82:85], v[168:171], v[196:199], v[82:85]
	v_mfma_f32_16x16x32_bf16 v[82:85], v[172:175], v[200:203], v[82:85]
	v_mfma_f32_16x16x32_bf16 v[70:73], v[156:159], v[204:207], v[70:73]
	v_mfma_f32_16x16x32_bf16 v[70:73], v[164:167], v[208:211], v[70:73]
	v_mfma_f32_16x16x32_bf16 v[66:69], v[168:171], v[204:207], v[66:69]
	v_mfma_f32_16x16x32_bf16 v[66:69], v[172:175], v[208:211], v[66:69]
	s_barrier
; #define PG8_STAGE(bufoff, gbase, voff) do { _Pragma("unroll") for (int _i = 0; _i < 2; ++_i) \
;         __builtin_amdgcn_global_load_lds((const unsigned*)((const char*)(gbase) + (voff)[_i]), (LAS unsigned*)(lds + (bufoff) + ldsw + _i * 8192), 16, 0, 0); } while (0)
; #define PG8_LDA(dst, b, h) do { _Pragma("unroll") for (int m = 0; m < 4; ++m) _Pragma("unroll") for (int k = 0; k < 2; ++k) dst[m][k] = *(const LAS bf16x8*)(lds + PG8_SA(b, h) + aoff + m * 2048 + k * 1024); } while (0)
; #define PG8_MMA(ai, bj, At, Bt) do { __builtin_amdgcn_s_setprio(1); _Pragma("unroll") for (int m = 0; m < 4; ++m) _Pragma("unroll") for (int n = 0; n < 2; ++n) _Pragma("unroll") for (int k = 0; k < 2; ++k) \
;         acc[ai][bj][m][n] = __builtin_amdgcn_mfma_f32_16x16x32_bf16(Bt[n][k], At[m][k], acc[ai][bj][m][n], 0, 0, 0); __builtin_amdgcn_s_setprio(0); } while (0)
; #define PG8_WAIT_V(n) asm volatile("s_waitcnt vmcnt(" #n ")" ::: "memory")
; #define PG8_WAIT_L(n) asm volatile("s_waitcnt lgkmcnt(" #n ")" ::: "memory")
; #define PG8_BAR __builtin_amdgcn_s_barrier()
; #define PG8_SCHED __builtin_amdgcn_sched_barrier(0)
; template <class Epi, class Sched, int LDA, int LDB, bool ALIGN_EPI = true>
; __device__ __forceinline__ void gemm_phase(LAS unsigned char* lds, const Gemm g, const Sched& S, const Epi& E, int wave) {
;     ...
;             PG8_LDA(At, 1, 1); PG8_STAGE(PG8_SB(1, 0), b3, voffB); PG8_STAGE(PG8_SB(1, 1), b3 + hstepB, voffB); PG8_STAGE(PG8_SA(1, 0), a3, voffA);
;             PG8_WAIT_V(8); PG8_WAIT_L(0); PG8_BAR; PG8_MMA(1, 0, At, B0); PG8_MMA(1, 1, At, B1); PG8_BAR; PG8_SCHED;
;         }
	s_setprio 0
	s_add_i32 s24, s48, s51
	v_lshl_add_u64 v[212:213], v[212:213], 0, s[52:53]
	s_mov_b32 m0, s24
	ds_read_b128 v[180:183], v163 offset:49152
	ds_read_b128 v[184:187], v163 offset:50176
	ds_read_b128 v[188:191], v163 offset:51200
	ds_read_b128 v[192:195], v163 offset:52224
	ds_read_b128 v[196:199], v163 offset:53248
	ds_read_b128 v[200:203], v163 offset:54272
	ds_read_b128 v[204:207], v163 offset:55296
	ds_read_b128 v[208:211], v163 offset:56320
	global_load_lds_dwordx4 v[212:213], off
	s_add_i32 m0, s24, 0x2000
	s_add_u32 s18, s18, 0x20080
	v_lshl_add_u64 v[212:213], v[214:215], 0, s[52:53]
	s_addc_u32 s19, s19, 0
	s_add_i32 s24, s49, s51
	global_load_lds_dwordx4 v[212:213], off
	v_lshl_add_u64 v[212:213], s[18:19], 0, v[0:1]
	s_mov_b32 m0, s24
	s_nop 0
	global_load_lds_dwordx4 v[212:213], off
	v_lshl_add_u64 v[212:213], s[18:19], 0, v[142:143]
	s_add_i32 m0, s24, 0x2000
	s_nop 0
	global_load_lds_dwordx4 v[212:213], off
	v_lshl_add_u64 v[212:213], v[216:217], 0, s[52:53]
	s_mov_b32 m0, s35
	s_nop 0
	global_load_lds_dwordx4 v[212:213], off
	v_lshl_add_u64 v[212:213], v[218:219], 0, s[52:53]
	s_mov_b32 m0, s36
	s_nop 0
	global_load_lds_dwordx4 v[212:213], off
	s_waitcnt vmcnt(8)
	s_waitcnt lgkmcnt(0)
	s_setprio 1
	s_barrier
	v_mfma_f32_16x16x32_bf16 v[62:65], v[130:133], v[180:183], v[62:65]
	v_mfma_f32_16x16x32_bf16 v[62:65], v[134:137], v[184:187], v[62:65]
	v_mfma_f32_16x16x32_bf16 v[58:61], v[148:151], v[180:183], v[58:61]
	v_mfma_f32_16x16x32_bf16 v[58:61], v[152:155], v[184:187], v[58:61]
	v_mfma_f32_16x16x32_bf16 v[46:49], v[130:133], v[188:191], v[46:49]
	v_mfma_f32_16x16x32_bf16 v[46:49], v[134:137], v[192:195], v[46:49]
	v_mfma_f32_16x16x32_bf16 v[42:45], v[148:151], v[188:191], v[42:45]
	v_mfma_f32_16x16x32_bf16 v[42:45], v[152:155], v[192:195], v[42:45]
	v_mfma_f32_16x16x32_bf16 v[30:33], v[130:133], v[196:199], v[30:33]
	v_mfma_f32_16x16x32_bf16 v[30:33], v[134:137], v[200:203], v[30:33]
	v_mfma_f32_16x16x32_bf16 v[26:29], v[148:151], v[196:199], v[26:29]
	v_mfma_f32_16x16x32_bf16 v[26:29], v[152:155], v[200:203], v[26:29]
	v_mfma_f32_16x16x32_bf16 v[14:17], v[130:133], v[204:207], v[14:17]
	v_mfma_f32_16x16x32_bf16 v[14:17], v[134:137], v[208:211], v[14:17]
	v_mfma_f32_16x16x32_bf16 v[10:13], v[148:151], v[204:207], v[10:13]
	v_mfma_f32_16x16x32_bf16 v[10:13], v[152:155], v[208:211], v[10:13]
	v_mfma_f32_16x16x32_bf16 v[54:57], v[156:159], v[180:183], v[54:57]
	v_mfma_f32_16x16x32_bf16 v[54:57], v[164:167], v[184:187], v[54:57]
	v_mfma_f32_16x16x32_bf16 v[50:53], v[168:171], v[180:183], v[50:53]
	v_mfma_f32_16x16x32_bf16 v[50:53], v[172:175], v[184:187], v[50:53]
	v_mfma_f32_16x16x32_bf16 v[38:41], v[156:159], v[188:191], v[38:41]
	v_mfma_f32_16x16x32_bf16 v[38:41], v[164:167], v[192:195], v[38:41]
	v_mfma_f32_16x16x32_bf16 v[34:37], v[168:171], v[188:191], v[34:37]
	v_mfma_f32_16x16x32_bf16 v[34:37], v[172:175], v[192:195], v[34:37]
	v_mfma_f32_16x16x32_bf16 v[22:25], v[156:159], v[196:199], v[22:25]
	v_mfma_f32_16x16x32_bf16 v[22:25], v[164:167], v[200:203], v[22:25]
	v_mfma_f32_16x16x32_bf16 v[18:21], v[168:171], v[196:199], v[18:21]
	v_mfma_f32_16x16x32_bf16 v[18:21], v[172:175], v[200:203], v[18:21]
	v_mfma_f32_16x16x32_bf16 v[6:9], v[156:159], v[204:207], v[6:9]
	v_mfma_f32_16x16x32_bf16 v[6:9], v[164:167], v[208:211], v[6:9]
	v_mfma_f32_16x16x32_bf16 v[2:5], v[168:171], v[204:207], v[2:5]
	v_mfma_f32_16x16x32_bf16 v[2:5], v[172:175], v[208:211], v[2:5]
	s_barrier
	s_setprio 0
	s_add_i32 s47, s47, 2
	s_add_u32 s16, s16, 0x100
	s_addc_u32 s17, s17, 0
	s_add_u32 s45, s45, 0x100
	s_addc_u32 s46, s46, 0
	s_cmp_gt_u32 s47, 5
	s_cbranch_scc0 .LBB0_2649
	v_readlane_b32 s16, v252, 14
	v_readlane_b32 s17, v252, 15
	s_and_b64 vcc, exec, s[16:17]
	s_cbranch_vccz .LBB0_2652
	s_barrier

; #define PG8_STAGE(bufoff, gbase, voff) do { _Pragma("unroll") for (int _i = 0; _i < 2; ++_i) \
;         __builtin_amdgcn_global_load_lds((const unsigned*)((const char*)(gbase) + (voff)[_i]), (LAS unsigned*)(lds + (bufoff) + ldsw + _i * 8192), 16, 0, 0); } while (0)
; #define PG8_LDA(dst, b, h) do { _Pragma("unroll") for (int m = 0; m < 4; ++m) _Pragma("unroll") for (int k = 0; k < 2; ++k) dst[m][k] = *(const LAS bf16x8*)(lds + PG8_SA(b, h) + aoff + m * 2048 + k * 1024); } while (0)
; #define PG8_LDB(dst, b, h) do { _Pragma("unroll") for (int n = 0; n < 2; ++n) _Pragma("unroll") for (int k = 0; k < 2; ++k) dst[n][k] = *(const LAS bf16x8*)(lds + PG8_SB(b, h) + boff + n * 2048 + k * 1024); } while (0)
; #define PG8_MMA(ai, bj, At, Bt) do { __builtin_amdgcn_s_setprio(1); _Pragma("unroll") for (int m = 0; m < 4; ++m) _Pragma("unroll") for (int n = 0; n < 2; ++n) _Pragma("unroll") for (int k = 0; k < 2; ++k) \
;         acc[ai][bj][m][n] = __builtin_amdgcn_mfma_f32_16x16x32_bf16(Bt[n][k], At[m][k], acc[ai][bj][m][n], 0, 0, 0); __builtin_amdgcn_s_setprio(0); } while (0)
; #define PG8_WAIT_V(n) asm volatile("s_waitcnt vmcnt(" #n ")" ::: "memory")
; template <class Epi, class Sched, int LDA, int LDB, bool ALIGN_EPI = true>
; __device__ __forceinline__ void gemm_phase(LAS unsigned char* lds, const Gemm g, const Sched& S, const Epi& E, int wave) {
;     ...
;         for (int t = 0; t < nt; t += 2) {
;             const bool last = (t == nt - 2);
;             const char* a1 = cA + (size_t)(t + 1) * kstep;
;             const char* a2 = last ? nA : cA + (size_t)(t + 2) * kstep; const char* b2 = last ? nB : cB + (size_t)(t + 2) * kstep;
;             const char* a3 = a2 + kstep; const char* b3 = b2 + kstep;
;             PG8_LDB(B0, 0, 0); PG8_LDB(B1, 0, 1); PG8_SCHED; PG8_LDA(At, 0, 0); PG8_STAGE(PG8_SA(1, 1), a1 + hstepA, voffA);
;             PG8_WAIT_V(8); PG8_WAIT_L(0); PG8_BAR; PG8_MMA(0, 0, At, B0); PG8_MMA(0, 1, At, B1); PG8_BAR; PG8_SCHED;
;             PG8_LDA(At, 0, 1); PG8_STAGE(PG8_SB(0, 0), b2, voffB); PG8_STAGE(PG8_SB(0, 1), b2 + hstepB, voffB); PG8_STAGE(PG8_SA(0, 0), a2, voffA);
;             PG8_WAIT_V(8); PG8_WAIT_L(0); PG8_BAR; PG8_MMA(1, 0, At, B0); PG8_MMA(1, 1, At, B1); PG8_BAR; PG8_SCHED;
;             PG8_LDB(B0, 1, 0); PG8_LDB(B1, 1, 1); PG8_SCHED; PG8_LDA(At, 1, 0); PG8_STAGE(PG8_SA(0, 1), a2 + hstepA, voffA);
.LBB0_4715:
	s_add_i32 s49, s24, 2
	s_add_u32 s25, s18, 0xfff80080
	s_addc_u32 s28, s19, -1
	s_add_i32 s50, 0, 0x10000
	s_cmp_eq_u32 s17, s24
	s_cselect_b32 s29, s1, s28
	s_cselect_b32 s28, s7, s25
	v_add_u32_e32 v0, s50, v153
	s_cselect_b32 s25, s3, s45
	s_cselect_b32 s24, s15, s44
	s_add_i32 s52, 0, 0x14000
	ds_read_b128 v[144:147], v0
	ds_read_b128 v[148:151], v0 offset:1024
	ds_read_b128 v[156:159], v0 offset:2048
	ds_read_b128 v[160:163], v0 offset:3072
	v_add_u32_e32 v0, s52, v153
	ds_read_b128 v[164:167], v0
	ds_read_b128 v[168:171], v0 offset:1024
	ds_read_b128 v[172:175], v0 offset:2048
	ds_read_b128 v[180:183], v0 offset:3072
	v_lshl_add_u64 v[216:217], s[18:19], 0, v[140:141]
	s_add_i32 m0, s27, 0xc000
	ds_read_b128 v[184:187], v155
	ds_read_b128 v[188:191], v155 offset:1024
	ds_read_b128 v[192:195], v155 offset:2048
	ds_read_b128 v[196:199], v155 offset:3072
	ds_read_b128 v[200:203], v155 offset:4096
	ds_read_b128 v[204:207], v155 offset:5120
	ds_read_b128 v[208:211], v155 offset:6144
	ds_read_b128 v[212:215], v155 offset:7168
	global_load_lds_dwordx4 v[216:217], off
	v_lshl_add_u64 v[216:217], s[18:19], 0, v[142:143]
	s_add_i32 m0, s27, 0xe000
	s_nop 0
	global_load_lds_dwordx4 v[216:217], off
	s_waitcnt vmcnt(8)
	s_waitcnt lgkmcnt(0)
	s_setprio 1
	s_barrier
	v_mfma_f32_16x16x32_bf16 v[126:129], v[144:147], v[184:187], v[126:129]
	v_mfma_f32_16x16x32_bf16 v[126:129], v[148:151], v[188:191], v[126:129]
	v_mfma_f32_16x16x32_bf16 v[122:125], v[156:159], v[184:187], v[122:125]
	v_mfma_f32_16x16x32_bf16 v[122:125], v[160:163], v[188:191], v[122:125]
	v_mfma_f32_16x16x32_bf16 v[110:113], v[144:147], v[192:195], v[110:113]
	v_mfma_f32_16x16x32_bf16 v[110:113], v[148:151], v[196:199], v[110:113]
	v_mfma_f32_16x16x32_bf16 v[106:109], v[156:159], v[192:195], v[106:109]
	v_mfma_f32_16x16x32_bf16 v[106:109], v[160:163], v[196:199], v[106:109]
	v_mfma_f32_16x16x32_bf16 v[94:97], v[144:147], v[200:203], v[94:97]
	v_mfma_f32_16x16x32_bf16 v[94:97], v[148:151], v[204:207], v[94:97]
	v_mfma_f32_16x16x32_bf16 v[90:93], v[156:159], v[200:203], v[90:93]
	v_mfma_f32_16x16x32_bf16 v[90:93], v[160:163], v[204:207], v[90:93]
	v_mfma_f32_16x16x32_bf16 v[78:81], v[144:147], v[208:211], v[78:81]
	v_mfma_f32_16x16x32_bf16 v[78:81], v[148:151], v[212:215], v[78:81]
	v_mfma_f32_16x16x32_bf16 v[74:77], v[156:159], v[208:211], v[74:77]
	v_mfma_f32_16x16x32_bf16 v[74:77], v[160:163], v[212:215], v[74:77]
	v_mfma_f32_16x16x32_bf16 v[118:121], v[164:167], v[184:187], v[118:121]
	v_mfma_f32_16x16x32_bf16 v[118:121], v[168:171], v[188:191], v[118:121]
	v_mfma_f32_16x16x32_bf16 v[114:117], v[172:175], v[184:187], v[114:117]
	v_mfma_f32_16x16x32_bf16 v[114:117], v[180:183], v[188:191], v[114:117]
	v_mfma_f32_16x16x32_bf16 v[102:105], v[164:167], v[192:195], v[102:105]
	v_mfma_f32_16x16x32_bf16 v[102:105], v[168:171], v[196:199], v[102:105]
	v_mfma_f32_16x16x32_bf16 v[98:101], v[172:175], v[192:195], v[98:101]
	v_mfma_f32_16x16x32_bf16 v[98:101], v[180:183], v[196:199], v[98:101]
	v_mfma_f32_16x16x32_bf16 v[86:89], v[164:167], v[200:203], v[86:89]
	v_mfma_f32_16x16x32_bf16 v[86:89], v[168:171], v[204:207], v[86:89]
	v_mfma_f32_16x16x32_bf16 v[82:85], v[172:175], v[200:203], v[82:85]
	v_mfma_f32_16x16x32_bf16 v[82:85], v[180:183], v[204:207], v[82:85]
	v_mfma_f32_16x16x32_bf16 v[70:73], v[164:167], v[208:211], v[70:73]
	v_mfma_f32_16x16x32_bf16 v[70:73], v[168:171], v[212:215], v[70:73]
	v_mfma_f32_16x16x32_bf16 v[66:69], v[172:175], v[208:211], v[66:69]
	v_mfma_f32_16x16x32_bf16 v[66:69], v[180:183], v[212:215], v[66:69]
	s_barrier
	s_setprio 0
	s_add_i32 s50, s50, s53
	v_lshl_add_u64 v[216:217], s[24:25], 0, v[132:133]
	s_mov_b32 m0, s50
	ds_read_b128 v[184:187], v155 offset:16384
	ds_read_b128 v[188:191], v155 offset:17408
	ds_read_b128 v[192:195], v155 offset:18432
	ds_read_b128 v[196:199], v155 offset:19456
	ds_read_b128 v[200:203], v155 offset:20480
	ds_read_b128 v[204:207], v155 offset:21504
	ds_read_b128 v[208:211], v155 offset:22528
	ds_read_b128 v[212:215], v155 offset:23552
	global_load_lds_dwordx4 v[216:217], off
	s_add_i32 m0, s50, 0x2000
	s_add_u32 s50, s24, 0x80000
	v_lshl_add_u64 v[218:219], s[24:25], 0, v[136:137]
	s_addc_u32 s51, s25, 0
	s_add_i32 s52, s52, s53
	global_load_lds_dwordx4 v[218:219], off
	v_lshl_add_u64 v[220:221], s[50:51], 0, v[132:133]
	s_mov_b32 m0, s52
	v_lshl_add_u64 v[222:223], s[28:29], 0, v[134:135]
	global_load_lds_dwordx4 v[220:221], off
	v_lshl_add_u64 v[220:221], s[50:51], 0, v[136:137]
	s_add_i32 m0, s52, 0x2000
	s_nop 0
	global_load_lds_dwordx4 v[220:221], off
	v_lshl_add_u64 v[220:221], s[28:29], 0, v[130:131]
	s_mov_b32 m0, s27
	s_nop 0
	global_load_lds_dwordx4 v[220:221], off
	s_mov_b32 m0, s34
	s_nop 0
	global_load_lds_dwordx4 v[222:223], off
	s_waitcnt vmcnt(8)
	s_waitcnt lgkmcnt(0)
	s_setprio 1
	s_barrier
; #define PG8_STAGE(bufoff, gbase, voff) do { _Pragma("unroll") for (int _i = 0; _i < 2; ++_i) \
;         __builtin_amdgcn_global_load_lds((const unsigned*)((const char*)(gbase) + (voff)[_i]), (LAS unsigned*)(lds + (bufoff) + ldsw + _i * 8192), 16, 0, 0); } while (0)
; #define PG8_LDA(dst, b, h) do { _Pragma("unroll") for (int m = 0; m < 4; ++m) _Pragma("unroll") for (int k = 0; k < 2; ++k) dst[m][k] = *(const LAS bf16x8*)(lds + PG8_SA(b, h) + aoff + m * 2048 + k * 1024); } while (0)
; #define PG8_LDB(dst, b, h) do { _Pragma("unroll") for (int n = 0; n < 2; ++n) _Pragma("unroll") for (int k = 0; k < 2; ++k) dst[n][k] = *(const LAS bf16x8*)(lds + PG8_SB(b, h) + boff + n * 2048 + k * 1024); } while (0)
; #define PG8_MMA(ai, bj, At, Bt) do { __builtin_amdgcn_s_setprio(1); _Pragma("unroll") for (int m = 0; m < 4; ++m) _Pragma("unroll") for (int n = 0; n < 2; ++n) _Pragma("unroll") for (int k = 0; k < 2; ++k) \
;         acc[ai][bj][m][n] = __builtin_amdgcn_mfma_f32_16x16x32_bf16(Bt[n][k], At[m][k], acc[ai][bj][m][n], 0, 0, 0); __builtin_amdgcn_s_setprio(0); } while (0)
; #define PG8_WAIT_V(n) asm volatile("s_waitcnt vmcnt(" #n ")" ::: "memory")
; #define PG8_WAIT_L(n) asm volatile("s_waitcnt lgkmcnt(" #n ")" ::: "memory")
; #define PG8_BAR __builtin_amdgcn_s_barrier()
; #define PG8_SCHED __builtin_amdgcn_sched_barrier(0)
; template <class Epi, class Sched, int LDA, int LDB, bool ALIGN_EPI = true>
; __device__ __forceinline__ void gemm_phase(LAS unsigned char* lds, const Gemm g, const Sched& S, const Epi& E, int wave) {
;     ...
;             PG8_WAIT_V(8); PG8_WAIT_L(0); PG8_BAR; PG8_MMA(1, 0, At, B0); PG8_MMA(1, 1, At, B1); PG8_BAR; PG8_SCHED;
;             PG8_LDB(B0, 1, 0); PG8_LDB(B1, 1, 1); PG8_SCHED; PG8_LDA(At, 1, 0); PG8_STAGE(PG8_SA(0, 1), a2 + hstepA, voffA);
;             PG8_WAIT_V(8); PG8_WAIT_L(0); PG8_BAR; PG8_MMA(0, 0, At, B0); PG8_MMA(0, 1, At, B1); PG8_BAR; PG8_SCHED;
	v_mfma_f32_16x16x32_bf16 v[62:65], v[144:147], v[184:187], v[62:65]
	v_mfma_f32_16x16x32_bf16 v[62:65], v[148:151], v[188:191], v[62:65]
	v_mfma_f32_16x16x32_bf16 v[58:61], v[156:159], v[184:187], v[58:61]
	v_mfma_f32_16x16x32_bf16 v[58:61], v[160:163], v[188:191], v[58:61]
	v_mfma_f32_16x16x32_bf16 v[46:49], v[144:147], v[192:195], v[46:49]
	v_mfma_f32_16x16x32_bf16 v[46:49], v[148:151], v[196:199], v[46:49]
	v_mfma_f32_16x16x32_bf16 v[42:45], v[156:159], v[192:195], v[42:45]
	v_mfma_f32_16x16x32_bf16 v[42:45], v[160:163], v[196:199], v[42:45]
	v_mfma_f32_16x16x32_bf16 v[30:33], v[144:147], v[200:203], v[30:33]
	v_mfma_f32_16x16x32_bf16 v[30:33], v[148:151], v[204:207], v[30:33]
	v_mfma_f32_16x16x32_bf16 v[26:29], v[156:159], v[200:203], v[26:29]
	v_mfma_f32_16x16x32_bf16 v[26:29], v[160:163], v[204:207], v[26:29]
	v_mfma_f32_16x16x32_bf16 v[14:17], v[144:147], v[208:211], v[14:17]
	v_mfma_f32_16x16x32_bf16 v[14:17], v[148:151], v[212:215], v[14:17]
	v_mfma_f32_16x16x32_bf16 v[10:13], v[156:159], v[208:211], v[10:13]
	v_mfma_f32_16x16x32_bf16 v[10:13], v[160:163], v[212:215], v[10:13]
	v_mfma_f32_16x16x32_bf16 v[54:57], v[164:167], v[184:187], v[54:57]
	v_mfma_f32_16x16x32_bf16 v[54:57], v[168:171], v[188:191], v[54:57]
	v_mfma_f32_16x16x32_bf16 v[50:53], v[172:175], v[184:187], v[50:53]
	v_mfma_f32_16x16x32_bf16 v[50:53], v[180:183], v[188:191], v[50:53]
	v_mfma_f32_16x16x32_bf16 v[38:41], v[164:167], v[192:195], v[38:41]
	v_mfma_f32_16x16x32_bf16 v[38:41], v[168:171], v[196:199], v[38:41]
	v_mfma_f32_16x16x32_bf16 v[34:37], v[172:175], v[192:195], v[34:37]
	v_mfma_f32_16x16x32_bf16 v[34:37], v[180:183], v[196:199], v[34:37]
	v_mfma_f32_16x16x32_bf16 v[22:25], v[164:167], v[200:203], v[22:25]
	v_mfma_f32_16x16x32_bf16 v[22:25], v[168:171], v[204:207], v[22:25]
	v_mfma_f32_16x16x32_bf16 v[18:21], v[172:175], v[200:203], v[18:21]
	v_mfma_f32_16x16x32_bf16 v[18:21], v[180:183], v[204:207], v[18:21]
	v_mfma_f32_16x16x32_bf16 v[6:9], v[164:167], v[208:211], v[6:9]
	v_mfma_f32_16x16x32_bf16 v[6:9], v[168:171], v[212:215], v[6:9]
	v_mfma_f32_16x16x32_bf16 v[2:5], v[172:175], v[208:211], v[2:5]
	v_mfma_f32_16x16x32_bf16 v[2:5], v[180:183], v[212:215], v[2:5]
	s_barrier
	s_setprio 0
	s_add_i32 s50, 0, 0x18000
	v_add_u32_e32 v0, s50, v153
	s_add_i32 s51, 0, 0x1c000
	ds_read_b128 v[144:147], v0
	ds_read_b128 v[148:151], v0 offset:1024
	ds_read_b128 v[156:159], v0 offset:2048
	ds_read_b128 v[160:163], v0 offset:3072
	v_add_u32_e32 v0, s51, v153
	ds_read_b128 v[164:167], v0
	ds_read_b128 v[168:171], v0 offset:1024
	ds_read_b128 v[172:175], v0 offset:2048
	ds_read_b128 v[180:183], v0 offset:3072
	s_add_u32 s28, s28, 0x80000
	s_addc_u32 s29, s29, 0
	s_mov_b32 m0, s35
	v_lshl_add_u64 v[224:225], s[28:29], 0, v[130:131]
	ds_read_b128 v[184:187], v155 offset:32768
	ds_read_b128 v[188:191], v155 offset:33792
	ds_read_b128 v[192:195], v155 offset:34816
	ds_read_b128 v[196:199], v155 offset:35840
	ds_read_b128 v[200:203], v155 offset:36864
	ds_read_b128 v[204:207], v155 offset:37888
	ds_read_b128 v[208:211], v155 offset:38912
	ds_read_b128 v[212:215], v155 offset:39936
	global_load_lds_dwordx4 v[224:225], off
	v_lshl_add_u64 v[224:225], s[28:29], 0, v[134:135]
	s_mov_b32 m0, s36
	s_nop 0
	global_load_lds_dwordx4 v[224:225], off
	s_waitcnt vmcnt(8)
	s_waitcnt lgkmcnt(0)
	s_setprio 1
	s_barrier
	v_mfma_f32_16x16x32_bf16 v[126:129], v[144:147], v[184:187], v[126:129]
	v_mfma_f32_16x16x32_bf16 v[126:129], v[148:151], v[188:191], v[126:129]
	v_mfma_f32_16x16x32_bf16 v[122:125], v[156:159], v[184:187], v[122:125]
	v_mfma_f32_16x16x32_bf16 v[122:125], v[160:163], v[188:191], v[122:125]
	v_mfma_f32_16x16x32_bf16 v[110:113], v[144:147], v[192:195], v[110:113]
	v_mfma_f32_16x16x32_bf16 v[110:113], v[148:151], v[196:199], v[110:113]
	v_mfma_f32_16x16x32_bf16 v[106:109], v[156:159], v[192:195], v[106:109]
	v_mfma_f32_16x16x32_bf16 v[106:109], v[160:163], v[196:199], v[106:109]
	v_mfma_f32_16x16x32_bf16 v[94:97], v[144:147], v[200:203], v[94:97]
	v_mfma_f32_16x16x32_bf16 v[94:97], v[148:151], v[204:207], v[94:97]
	v_mfma_f32_16x16x32_bf16 v[90:93], v[156:159], v[200:203], v[90:93]
	v_mfma_f32_16x16x32_bf16 v[90:93], v[160:163], v[204:207], v[90:93]
	v_mfma_f32_16x16x32_bf16 v[78:81], v[144:147], v[208:211], v[78:81]
	v_mfma_f32_16x16x32_bf16 v[78:81], v[148:151], v[212:215], v[78:81]
	v_mfma_f32_16x16x32_bf16 v[74:77], v[156:159], v[208:211], v[74:77]
	v_mfma_f32_16x16x32_bf16 v[74:77], v[160:163], v[212:215], v[74:77]
	v_mfma_f32_16x16x32_bf16 v[118:121], v[164:167], v[184:187], v[118:121]
	v_mfma_f32_16x16x32_bf16 v[118:121], v[168:171], v[188:191], v[118:121]
	v_mfma_f32_16x16x32_bf16 v[114:117], v[172:175], v[184:187], v[114:117]
	v_mfma_f32_16x16x32_bf16 v[114:117], v[180:183], v[188:191], v[114:117]
	v_mfma_f32_16x16x32_bf16 v[102:105], v[164:167], v[192:195], v[102:105]
	v_mfma_f32_16x16x32_bf16 v[102:105], v[168:171], v[196:199], v[102:105]
	v_mfma_f32_16x16x32_bf16 v[98:101], v[172:175], v[192:195], v[98:101]
	v_mfma_f32_16x16x32_bf16 v[98:101], v[180:183], v[196:199], v[98:101]
	v_mfma_f32_16x16x32_bf16 v[86:89], v[164:167], v[200:203], v[86:89]
	v_mfma_f32_16x16x32_bf16 v[86:89], v[168:171], v[204:207], v[86:89]
	v_mfma_f32_16x16x32_bf16 v[82:85], v[172:175], v[200:203], v[82:85]
	v_mfma_f32_16x16x32_bf16 v[82:85], v[180:183], v[204:207], v[82:85]
	v_mfma_f32_16x16x32_bf16 v[70:73], v[164:167], v[208:211], v[70:73]
	v_mfma_f32_16x16x32_bf16 v[70:73], v[168:171], v[212:215], v[70:73]
	v_mfma_f32_16x16x32_bf16 v[66:69], v[172:175], v[208:211], v[66:69]
	v_mfma_f32_16x16x32_bf16 v[66:69], v[180:183], v[212:215], v[66:69]
	s_barrier
; #define PG8_STAGE(bufoff, gbase, voff) do { _Pragma("unroll") for (int _i = 0; _i < 2; ++_i) \
;         __builtin_amdgcn_global_load_lds((const unsigned*)((const char*)(gbase) + (voff)[_i]), (LAS unsigned*)(lds + (bufoff) + ldsw + _i * 8192), 16, 0, 0); } while (0)
; #define PG8_LDA(dst, b, h) do { _Pragma("unroll") for (int m = 0; m < 4; ++m) _Pragma("unroll") for (int k = 0; k < 2; ++k) dst[m][k] = *(const LAS bf16x8*)(lds + PG8_SA(b, h) + aoff + m * 2048 + k * 1024); } while (0)
; #define PG8_MMA(ai, bj, At, Bt) do { __builtin_amdgcn_s_setprio(1); _Pragma("unroll") for (int m = 0; m < 4; ++m) _Pragma("unroll") for (int n = 0; n < 2; ++n) _Pragma("unroll") for (int k = 0; k < 2; ++k) \
;         acc[ai][bj][m][n] = __builtin_amdgcn_mfma_f32_16x16x32_bf16(Bt[n][k], At[m][k], acc[ai][bj][m][n], 0, 0, 0); __builtin_amdgcn_s_setprio(0); } while (0)
; #define PG8_WAIT_V(n) asm volatile("s_waitcnt vmcnt(" #n ")" ::: "memory")
; #define PG8_WAIT_L(n) asm volatile("s_waitcnt lgkmcnt(" #n ")" ::: "memory")
; #define PG8_BAR __builtin_amdgcn_s_barrier()
; #define PG8_SCHED __builtin_amdgcn_sched_barrier(0)
; template <class Epi, class Sched, int LDA, int LDB, bool ALIGN_EPI = true>
; __device__ __forceinline__ void gemm_phase(LAS unsigned char* lds, const Gemm g, const Sched& S, const Epi& E, int wave) {
;     ...
;             PG8_LDA(At, 1, 1); PG8_STAGE(PG8_SB(1, 0), b3, voffB); PG8_STAGE(PG8_SB(1, 1), b3 + hstepB, voffB); PG8_STAGE(PG8_SA(1, 0), a3, voffA);
;             PG8_WAIT_V(8); PG8_WAIT_L(0); PG8_BAR; PG8_MMA(1, 0, At, B0); PG8_MMA(1, 1, At, B1); PG8_BAR; PG8_SCHED;
;         }
;         if constexpr (ALIGN_EPI) { if (wr == 0) PG8_BAR; }
	s_setprio 0
	s_add_i32 s28, s50, s53
	v_lshl_add_u64 v[216:217], v[216:217], 0, s[54:55]
	s_mov_b32 m0, s28
	ds_read_b128 v[184:187], v155 offset:49152
	ds_read_b128 v[188:191], v155 offset:50176
	ds_read_b128 v[192:195], v155 offset:51200
	ds_read_b128 v[196:199], v155 offset:52224
	ds_read_b128 v[200:203], v155 offset:53248
	ds_read_b128 v[204:207], v155 offset:54272
	ds_read_b128 v[208:211], v155 offset:55296
	ds_read_b128 v[212:215], v155 offset:56320
	global_load_lds_dwordx4 v[216:217], off
	s_add_i32 m0, s28, 0x2000
	s_add_u32 s24, s24, 0x80080
	v_lshl_add_u64 v[216:217], v[218:219], 0, s[54:55]
	s_addc_u32 s25, s25, 0
	s_add_i32 s28, s51, s53
	global_load_lds_dwordx4 v[216:217], off
	v_lshl_add_u64 v[216:217], s[24:25], 0, v[132:133]
	s_mov_b32 m0, s28
	s_nop 0
	global_load_lds_dwordx4 v[216:217], off
	v_lshl_add_u64 v[216:217], s[24:25], 0, v[136:137]
	s_add_i32 m0, s28, 0x2000
	s_nop 0
	global_load_lds_dwordx4 v[216:217], off
	v_lshl_add_u64 v[216:217], v[220:221], 0, s[54:55]
	s_mov_b32 m0, s37
	s_nop 0
	global_load_lds_dwordx4 v[216:217], off
	v_lshl_add_u64 v[216:217], v[222:223], 0, s[54:55]
	s_mov_b32 m0, s38
	s_nop 0
	global_load_lds_dwordx4 v[216:217], off
	s_waitcnt vmcnt(8)
	s_waitcnt lgkmcnt(0)
	s_setprio 1
	s_barrier
	v_mfma_f32_16x16x32_bf16 v[62:65], v[144:147], v[184:187], v[62:65]
	v_mfma_f32_16x16x32_bf16 v[62:65], v[148:151], v[188:191], v[62:65]
	v_mfma_f32_16x16x32_bf16 v[58:61], v[156:159], v[184:187], v[58:61]
	v_mfma_f32_16x16x32_bf16 v[58:61], v[160:163], v[188:191], v[58:61]
	v_mfma_f32_16x16x32_bf16 v[46:49], v[144:147], v[192:195], v[46:49]
	v_mfma_f32_16x16x32_bf16 v[46:49], v[148:151], v[196:199], v[46:49]
	v_mfma_f32_16x16x32_bf16 v[42:45], v[156:159], v[192:195], v[42:45]
	v_mfma_f32_16x16x32_bf16 v[42:45], v[160:163], v[196:199], v[42:45]
	v_mfma_f32_16x16x32_bf16 v[30:33], v[144:147], v[200:203], v[30:33]
	v_mfma_f32_16x16x32_bf16 v[30:33], v[148:151], v[204:207], v[30:33]
	v_mfma_f32_16x16x32_bf16 v[26:29], v[156:159], v[200:203], v[26:29]
	v_mfma_f32_16x16x32_bf16 v[26:29], v[160:163], v[204:207], v[26:29]
	v_mfma_f32_16x16x32_bf16 v[14:17], v[144:147], v[208:211], v[14:17]
	v_mfma_f32_16x16x32_bf16 v[14:17], v[148:151], v[212:215], v[14:17]
	v_mfma_f32_16x16x32_bf16 v[10:13], v[156:159], v[208:211], v[10:13]
	v_mfma_f32_16x16x32_bf16 v[10:13], v[160:163], v[212:215], v[10:13]
	v_mfma_f32_16x16x32_bf16 v[54:57], v[164:167], v[184:187], v[54:57]
	v_mfma_f32_16x16x32_bf16 v[54:57], v[168:171], v[188:191], v[54:57]
	v_mfma_f32_16x16x32_bf16 v[50:53], v[172:175], v[184:187], v[50:53]
	v_mfma_f32_16x16x32_bf16 v[50:53], v[180:183], v[188:191], v[50:53]
	v_mfma_f32_16x16x32_bf16 v[38:41], v[164:167], v[192:195], v[38:41]
	v_mfma_f32_16x16x32_bf16 v[38:41], v[168:171], v[196:199], v[38:41]
	v_mfma_f32_16x16x32_bf16 v[34:37], v[172:175], v[192:195], v[34:37]
	v_mfma_f32_16x16x32_bf16 v[34:37], v[180:183], v[196:199], v[34:37]
	v_mfma_f32_16x16x32_bf16 v[22:25], v[164:167], v[200:203], v[22:25]
	v_mfma_f32_16x16x32_bf16 v[22:25], v[168:171], v[204:207], v[22:25]
	v_mfma_f32_16x16x32_bf16 v[18:21], v[172:175], v[200:203], v[18:21]
	v_mfma_f32_16x16x32_bf16 v[18:21], v[180:183], v[204:207], v[18:21]
	v_mfma_f32_16x16x32_bf16 v[6:9], v[164:167], v[208:211], v[6:9]
	v_mfma_f32_16x16x32_bf16 v[6:9], v[168:171], v[212:215], v[6:9]
	v_mfma_f32_16x16x32_bf16 v[2:5], v[172:175], v[208:211], v[2:5]
	v_mfma_f32_16x16x32_bf16 v[2:5], v[180:183], v[212:215], v[2:5]
	s_barrier
	s_setprio 0
	s_add_u32 s18, s18, 0x100
	s_addc_u32 s19, s19, 0
	s_add_u32 s44, s44, 0x100
	s_addc_u32 s45, s45, 0
	s_cmp_ge_i32 s49, s43
	s_mov_b32 s24, s49
	s_cbranch_scc0 .LBB0_4715
	v_readlane_b32 s18, v252, 14
	v_readlane_b32 s19, v252, 15
	s_and_b64 vcc, exec, s[18:19]
	s_cbranch_vccz .LBB0_4718
	s_barrier

; #define PG8_STAGE(bufoff, gbase, voff) do { _Pragma("unroll") for (int _i = 0; _i < 2; ++_i) \
;         __builtin_amdgcn_global_load_lds((const unsigned*)((const char*)(gbase) + (voff)[_i]), (LAS unsigned*)(lds + (bufoff) + ldsw + _i * 8192), 16, 0, 0); } while (0)
; #define PG8_LDA(dst, b, h) do { _Pragma("unroll") for (int m = 0; m < 4; ++m) _Pragma("unroll") for (int k = 0; k < 2; ++k) dst[m][k] = *(const LAS bf16x8*)(lds + PG8_SA(b, h) + aoff + m * 2048 + k * 1024); } while (0)
; #define PG8_LDB(dst, b, h) do { _Pragma("unroll") for (int n = 0; n < 2; ++n) _Pragma("unroll") for (int k = 0; k < 2; ++k) dst[n][k] = *(const LAS bf16x8*)(lds + PG8_SB(b, h) + boff + n * 2048 + k * 1024); } while (0)
; #define PG8_MMA(ai, bj, At, Bt) do { __builtin_amdgcn_s_setprio(1); _Pragma("unroll") for (int m = 0; m < 4; ++m) _Pragma("unroll") for (int n = 0; n < 2; ++n) _Pragma("unroll") for (int k = 0; k < 2; ++k) \
;         acc[ai][bj][m][n] = __builtin_amdgcn_mfma_f32_16x16x32_bf16(Bt[n][k], At[m][k], acc[ai][bj][m][n], 0, 0, 0); __builtin_amdgcn_s_setprio(0); } while (0)
; #define PG8_WAIT_V(n) asm volatile("s_waitcnt vmcnt(" #n ")" ::: "memory")
; #define PG8_WAIT_L(n) asm volatile("s_waitcnt lgkmcnt(" #n ")" ::: "memory")
; #define PG8_BAR __builtin_amdgcn_s_barrier()
; #define PG8_SCHED __builtin_amdgcn_sched_barrier(0)
; template <class Epi, class Sched, int LDA, int LDB, bool ALIGN_EPI = true>
; __device__ __forceinline__ void gemm_phase(LAS unsigned char* lds, const Gemm g, const Sched& S, const Epi& E, int wave) {
;     ...
;             PG8_LDB(B0, 0, 0); PG8_LDB(B1, 0, 1); PG8_SCHED; PG8_LDA(At, 0, 0); PG8_STAGE(PG8_SA(1, 1), a1 + hstepA, voffA);
;             PG8_WAIT_V(8); PG8_WAIT_L(0); PG8_BAR; PG8_MMA(0, 0, At, B0); PG8_MMA(0, 1, At, B1); PG8_BAR; PG8_SCHED;
;             PG8_LDA(At, 0, 1); PG8_STAGE(PG8_SB(0, 0), b2, voffB); PG8_STAGE(PG8_SB(0, 1), b2 + hstepB, voffB); PG8_STAGE(PG8_SA(0, 0), a2, voffA);
;             PG8_WAIT_V(8); PG8_WAIT_L(0); PG8_BAR; PG8_MMA(1, 0, At, B0); PG8_MMA(1, 1, At, B1); PG8_BAR; PG8_SCHED;
.LBB0_4901:
	s_add_i32 s65, s36, 2
	s_add_u32 s37, s34, 0xfff80080
	s_addc_u32 s38, s35, -1
	s_add_i32 s66, 0, 0x10000
	s_cmp_eq_u32 s29, s36
	s_cselect_b32 s39, s9, s38
	s_cselect_b32 s38, s13, s37
	s_cselect_b32 s37, s11, s64
	s_cselect_b32 s36, s25, s59
	s_add_i32 s72, 0, 0x14000
	v_add_u32_e32 v70, s66, v213
	v_add_u32_e32 v168, s72, v213
	ds_read_b128 v[50:53], v70
	ds_read_b128 v[54:57], v70 offset:1024
	ds_read_b128 v[66:69], v70 offset:2048
	ds_read_b128 v[70:73], v70 offset:3072
	ds_read_b128 v[156:159], v168
	ds_read_b128 v[160:163], v168 offset:1024
	ds_read_b128 v[164:167], v168 offset:2048
	ds_read_b128 v[168:171], v168 offset:3072
	v_lshl_add_u64 v[208:209], s[34:35], 0, v[152:153]
	s_add_i32 m0, s27, 0xc000
	ds_read_b128 v[172:175], v215
	ds_read_b128 v[180:183], v215 offset:1024
	ds_read_b128 v[184:187], v215 offset:2048
	ds_read_b128 v[188:191], v215 offset:3072
	ds_read_b128 v[192:195], v215 offset:4096
	ds_read_b128 v[196:199], v215 offset:5120
	ds_read_b128 v[200:203], v215 offset:6144
	ds_read_b128 v[204:207], v215 offset:7168
	global_load_lds_dwordx4 v[208:209], off
	v_lshl_add_u64 v[208:209], s[34:35], 0, v[154:155]
	s_add_i32 m0, s27, 0xe000
	s_nop 0
	global_load_lds_dwordx4 v[208:209], off
	s_waitcnt vmcnt(8)
	s_waitcnt lgkmcnt(0)
	s_setprio 1
	s_barrier
	v_mfma_f32_16x16x32_bf16 v[142:145], v[50:53], v[172:175], v[142:145]
	v_mfma_f32_16x16x32_bf16 v[142:145], v[54:57], v[180:183], v[142:145]
	v_mfma_f32_16x16x32_bf16 v[138:141], v[66:69], v[172:175], v[138:141]
	v_mfma_f32_16x16x32_bf16 v[138:141], v[70:73], v[180:183], v[138:141]
	v_mfma_f32_16x16x32_bf16 v[126:129], v[50:53], v[184:187], v[126:129]
	v_mfma_f32_16x16x32_bf16 v[126:129], v[54:57], v[188:191], v[126:129]
	v_mfma_f32_16x16x32_bf16 v[122:125], v[66:69], v[184:187], v[122:125]
	v_mfma_f32_16x16x32_bf16 v[122:125], v[70:73], v[188:191], v[122:125]
	v_mfma_f32_16x16x32_bf16 v[110:113], v[50:53], v[192:195], v[110:113]
	v_mfma_f32_16x16x32_bf16 v[110:113], v[54:57], v[196:199], v[110:113]
	v_mfma_f32_16x16x32_bf16 v[106:109], v[66:69], v[192:195], v[106:109]
	v_mfma_f32_16x16x32_bf16 v[106:109], v[70:73], v[196:199], v[106:109]
	v_mfma_f32_16x16x32_bf16 v[94:97], v[50:53], v[200:203], v[94:97]
	v_mfma_f32_16x16x32_bf16 v[94:97], v[54:57], v[204:207], v[94:97]
	v_mfma_f32_16x16x32_bf16 v[90:93], v[66:69], v[200:203], v[90:93]
	v_mfma_f32_16x16x32_bf16 v[90:93], v[70:73], v[204:207], v[90:93]
	v_mfma_f32_16x16x32_bf16 v[134:137], v[156:159], v[172:175], v[134:137]
	v_mfma_f32_16x16x32_bf16 v[134:137], v[160:163], v[180:183], v[134:137]
	v_mfma_f32_16x16x32_bf16 v[130:133], v[164:167], v[172:175], v[130:133]
	v_mfma_f32_16x16x32_bf16 v[130:133], v[168:171], v[180:183], v[130:133]
	v_mfma_f32_16x16x32_bf16 v[118:121], v[156:159], v[184:187], v[118:121]
	v_mfma_f32_16x16x32_bf16 v[118:121], v[160:163], v[188:191], v[118:121]
	v_mfma_f32_16x16x32_bf16 v[114:117], v[164:167], v[184:187], v[114:117]
	v_mfma_f32_16x16x32_bf16 v[114:117], v[168:171], v[188:191], v[114:117]
	v_mfma_f32_16x16x32_bf16 v[102:105], v[156:159], v[192:195], v[102:105]
	v_mfma_f32_16x16x32_bf16 v[102:105], v[160:163], v[196:199], v[102:105]
	v_mfma_f32_16x16x32_bf16 v[98:101], v[164:167], v[192:195], v[98:101]
	v_mfma_f32_16x16x32_bf16 v[98:101], v[168:171], v[196:199], v[98:101]
	v_mfma_f32_16x16x32_bf16 v[86:89], v[156:159], v[200:203], v[86:89]
	v_mfma_f32_16x16x32_bf16 v[86:89], v[160:163], v[204:207], v[86:89]
	v_mfma_f32_16x16x32_bf16 v[82:85], v[164:167], v[200:203], v[82:85]
	v_mfma_f32_16x16x32_bf16 v[82:85], v[168:171], v[204:207], v[82:85]
	s_barrier
	s_setprio 0
	s_add_i32 s66, s66, s60
	v_lshl_add_u64 v[208:209], s[36:37], 0, v[0:1]
	s_mov_b32 m0, s66
	ds_read_b128 v[172:175], v215 offset:16384
	ds_read_b128 v[180:183], v215 offset:17408
	ds_read_b128 v[184:187], v215 offset:18432
	ds_read_b128 v[188:191], v215 offset:19456
	ds_read_b128 v[192:195], v215 offset:20480
	ds_read_b128 v[196:199], v215 offset:21504
	ds_read_b128 v[200:203], v215 offset:22528
	ds_read_b128 v[204:207], v215 offset:23552
	global_load_lds_dwordx4 v[208:209], off
	s_add_i32 m0, s66, 0x2000
	s_add_u32 s66, s36, 0x80000
	v_lshl_add_u64 v[210:211], s[36:37], 0, v[150:151]
	s_addc_u32 s67, s37, 0
	s_add_i32 s72, s72, s60
	global_load_lds_dwordx4 v[210:211], off
	v_lshl_add_u64 v[216:217], s[66:67], 0, v[0:1]
	s_mov_b32 m0, s72
	v_lshl_add_u64 v[218:219], s[38:39], 0, v[148:149]
	global_load_lds_dwordx4 v[216:217], off
	v_lshl_add_u64 v[216:217], s[66:67], 0, v[150:151]
	s_add_i32 m0, s72, 0x2000
	s_nop 0
	global_load_lds_dwordx4 v[216:217], off
	v_lshl_add_u64 v[216:217], s[38:39], 0, v[146:147]
	s_mov_b32 m0, s27
	s_nop 0
	global_load_lds_dwordx4 v[216:217], off
	s_mov_b32 m0, s44
	s_nop 0
	global_load_lds_dwordx4 v[218:219], off
	s_waitcnt vmcnt(8)
	s_waitcnt lgkmcnt(0)
	s_setprio 1
	s_barrier
; #define PG8_STAGE(bufoff, gbase, voff) do { _Pragma("unroll") for (int _i = 0; _i < 2; ++_i) \
;         __builtin_amdgcn_global_load_lds((const unsigned*)((const char*)(gbase) + (voff)[_i]), (LAS unsigned*)(lds + (bufoff) + ldsw + _i * 8192), 16, 0, 0); } while (0)
; #define PG8_LDA(dst, b, h) do { _Pragma("unroll") for (int m = 0; m < 4; ++m) _Pragma("unroll") for (int k = 0; k < 2; ++k) dst[m][k] = *(const LAS bf16x8*)(lds + PG8_SA(b, h) + aoff + m * 2048 + k * 1024); } while (0)
; #define PG8_LDB(dst, b, h) do { _Pragma("unroll") for (int n = 0; n < 2; ++n) _Pragma("unroll") for (int k = 0; k < 2; ++k) dst[n][k] = *(const LAS bf16x8*)(lds + PG8_SB(b, h) + boff + n * 2048 + k * 1024); } while (0)
; #define PG8_MMA(ai, bj, At, Bt) do { __builtin_amdgcn_s_setprio(1); _Pragma("unroll") for (int m = 0; m < 4; ++m) _Pragma("unroll") for (int n = 0; n < 2; ++n) _Pragma("unroll") for (int k = 0; k < 2; ++k) \
;         acc[ai][bj][m][n] = __builtin_amdgcn_mfma_f32_16x16x32_bf16(Bt[n][k], At[m][k], acc[ai][bj][m][n], 0, 0, 0); __builtin_amdgcn_s_setprio(0); } while (0)
; #define PG8_WAIT_V(n) asm volatile("s_waitcnt vmcnt(" #n ")" ::: "memory")
; #define PG8_WAIT_L(n) asm volatile("s_waitcnt lgkmcnt(" #n ")" ::: "memory")
; #define PG8_BAR __builtin_amdgcn_s_barrier()
; #define PG8_SCHED __builtin_amdgcn_sched_barrier(0)
; template <class Epi, class Sched, int LDA, int LDB, bool ALIGN_EPI = true>
; __device__ __forceinline__ void gemm_phase(LAS unsigned char* lds, const Gemm g, const Sched& S, const Epi& E, int wave) {
;     ...
;             PG8_WAIT_V(8); PG8_WAIT_L(0); PG8_BAR; PG8_MMA(1, 0, At, B0); PG8_MMA(1, 1, At, B1); PG8_BAR; PG8_SCHED;
;             PG8_LDB(B0, 1, 0); PG8_LDB(B1, 1, 1); PG8_SCHED; PG8_LDA(At, 1, 0); PG8_STAGE(PG8_SA(0, 1), a2 + hstepA, voffA);
;             PG8_WAIT_V(8); PG8_WAIT_L(0); PG8_BAR; PG8_MMA(0, 0, At, B0); PG8_MMA(0, 1, At, B1); PG8_BAR; PG8_SCHED;
	v_mfma_f32_16x16x32_bf16 v[78:81], v[50:53], v[172:175], v[78:81]
	v_mfma_f32_16x16x32_bf16 v[74:77], v[66:69], v[172:175], v[74:77]
	v_mfma_f32_16x16x32_bf16 v[46:49], v[50:53], v[184:187], v[46:49]
	v_mfma_f32_16x16x32_bf16 v[42:45], v[66:69], v[184:187], v[42:45]
	v_mfma_f32_16x16x32_bf16 v[30:33], v[50:53], v[192:195], v[30:33]
	v_mfma_f32_16x16x32_bf16 v[26:29], v[66:69], v[192:195], v[26:29]
	v_mfma_f32_16x16x32_bf16 v[14:17], v[50:53], v[200:203], v[14:17]
	v_mfma_f32_16x16x32_bf16 v[10:13], v[66:69], v[200:203], v[10:13]
	v_mfma_f32_16x16x32_bf16 v[78:81], v[54:57], v[180:183], v[78:81]
	v_mfma_f32_16x16x32_bf16 v[74:77], v[70:73], v[180:183], v[74:77]
	v_mfma_f32_16x16x32_bf16 v[46:49], v[54:57], v[188:191], v[46:49]
	v_mfma_f32_16x16x32_bf16 v[42:45], v[70:73], v[188:191], v[42:45]
	v_mfma_f32_16x16x32_bf16 v[30:33], v[54:57], v[196:199], v[30:33]
	v_mfma_f32_16x16x32_bf16 v[26:29], v[70:73], v[196:199], v[26:29]
	v_mfma_f32_16x16x32_bf16 v[14:17], v[54:57], v[204:207], v[14:17]
	v_mfma_f32_16x16x32_bf16 v[10:13], v[70:73], v[204:207], v[10:13]
	v_mfma_f32_16x16x32_bf16 v[38:41], v[156:159], v[184:187], v[38:41]
	v_mfma_f32_16x16x32_bf16 v[34:37], v[164:167], v[184:187], v[34:37]
	v_mfma_f32_16x16x32_bf16 v[22:25], v[156:159], v[192:195], v[22:25]
	v_mfma_f32_16x16x32_bf16 v[18:21], v[164:167], v[192:195], v[18:21]
	v_mfma_f32_16x16x32_bf16 v[6:9], v[156:159], v[200:203], v[6:9]
	v_mfma_f32_16x16x32_bf16 v[2:5], v[164:167], v[200:203], v[2:5]
	v_mfma_f32_16x16x32_bf16 v[50:53], v[156:159], v[172:175], v[62:65]
	v_mfma_f32_16x16x32_bf16 v[54:57], v[164:167], v[172:175], v[58:61]
	v_mfma_f32_16x16x32_bf16 v[38:41], v[160:163], v[188:191], v[38:41]
	v_mfma_f32_16x16x32_bf16 v[34:37], v[168:171], v[188:191], v[34:37]
	v_mfma_f32_16x16x32_bf16 v[22:25], v[160:163], v[196:199], v[22:25]
	v_mfma_f32_16x16x32_bf16 v[18:21], v[168:171], v[196:199], v[18:21]
	v_mfma_f32_16x16x32_bf16 v[6:9], v[160:163], v[204:207], v[6:9]
	v_mfma_f32_16x16x32_bf16 v[2:5], v[168:171], v[204:207], v[2:5]
	v_mfma_f32_16x16x32_bf16 v[50:53], v[160:163], v[180:183], v[50:53]
	v_mfma_f32_16x16x32_bf16 v[54:57], v[168:171], v[180:183], v[54:57]
	s_barrier
	s_setprio 0
	s_add_i32 s66, 0, 0x18000
	s_add_i32 s67, 0, 0x1c000
	v_add_u32_e32 v70, s66, v213
	v_add_u32_e32 v168, s67, v213
	ds_read_b128 v[58:61], v70
	ds_read_b128 v[62:65], v70 offset:1024
	ds_read_b128 v[66:69], v70 offset:2048
	ds_read_b128 v[70:73], v70 offset:3072
	ds_read_b128 v[156:159], v168
	ds_read_b128 v[160:163], v168 offset:1024
	ds_read_b128 v[164:167], v168 offset:2048
	ds_read_b128 v[168:171], v168 offset:3072
	s_add_u32 s38, s38, 0x80000
	s_addc_u32 s39, s39, 0
	s_mov_b32 m0, s45
	v_lshl_add_u64 v[220:221], s[38:39], 0, v[146:147]
	ds_read_b128 v[172:175], v215 offset:32768
	ds_read_b128 v[180:183], v215 offset:33792
	ds_read_b128 v[184:187], v215 offset:34816
	ds_read_b128 v[188:191], v215 offset:35840
	ds_read_b128 v[192:195], v215 offset:36864
	ds_read_b128 v[196:199], v215 offset:37888
	ds_read_b128 v[200:203], v215 offset:38912
	ds_read_b128 v[204:207], v215 offset:39936
	global_load_lds_dwordx4 v[220:221], off
	v_lshl_add_u64 v[220:221], s[38:39], 0, v[148:149]
	s_mov_b32 m0, s46
	s_nop 0
	global_load_lds_dwordx4 v[220:221], off
	s_waitcnt vmcnt(8)
	s_waitcnt lgkmcnt(0)
	s_setprio 1
	s_barrier
	v_mfma_f32_16x16x32_bf16 v[142:145], v[58:61], v[172:175], v[142:145]
	v_mfma_f32_16x16x32_bf16 v[142:145], v[62:65], v[180:183], v[142:145]
	v_mfma_f32_16x16x32_bf16 v[138:141], v[66:69], v[172:175], v[138:141]
	v_mfma_f32_16x16x32_bf16 v[138:141], v[70:73], v[180:183], v[138:141]
	v_mfma_f32_16x16x32_bf16 v[126:129], v[58:61], v[184:187], v[126:129]
	v_mfma_f32_16x16x32_bf16 v[126:129], v[62:65], v[188:191], v[126:129]
	v_mfma_f32_16x16x32_bf16 v[122:125], v[66:69], v[184:187], v[122:125]
	v_mfma_f32_16x16x32_bf16 v[122:125], v[70:73], v[188:191], v[122:125]
	v_mfma_f32_16x16x32_bf16 v[110:113], v[58:61], v[192:195], v[110:113]
	v_mfma_f32_16x16x32_bf16 v[110:113], v[62:65], v[196:199], v[110:113]
	v_mfma_f32_16x16x32_bf16 v[106:109], v[66:69], v[192:195], v[106:109]
	v_mfma_f32_16x16x32_bf16 v[106:109], v[70:73], v[196:199], v[106:109]
	v_mfma_f32_16x16x32_bf16 v[94:97], v[58:61], v[200:203], v[94:97]
	v_mfma_f32_16x16x32_bf16 v[94:97], v[62:65], v[204:207], v[94:97]
	v_mfma_f32_16x16x32_bf16 v[90:93], v[66:69], v[200:203], v[90:93]
	v_mfma_f32_16x16x32_bf16 v[90:93], v[70:73], v[204:207], v[90:93]
	v_mfma_f32_16x16x32_bf16 v[134:137], v[156:159], v[172:175], v[134:137]
	v_mfma_f32_16x16x32_bf16 v[134:137], v[160:163], v[180:183], v[134:137]
	v_mfma_f32_16x16x32_bf16 v[130:133], v[164:167], v[172:175], v[130:133]
	v_mfma_f32_16x16x32_bf16 v[130:133], v[168:171], v[180:183], v[130:133]
	v_mfma_f32_16x16x32_bf16 v[118:121], v[156:159], v[184:187], v[118:121]
	v_mfma_f32_16x16x32_bf16 v[118:121], v[160:163], v[188:191], v[118:121]
	v_mfma_f32_16x16x32_bf16 v[114:117], v[164:167], v[184:187], v[114:117]
	v_mfma_f32_16x16x32_bf16 v[114:117], v[168:171], v[188:191], v[114:117]
	v_mfma_f32_16x16x32_bf16 v[102:105], v[156:159], v[192:195], v[102:105]
	v_mfma_f32_16x16x32_bf16 v[102:105], v[160:163], v[196:199], v[102:105]
	v_mfma_f32_16x16x32_bf16 v[98:101], v[164:167], v[192:195], v[98:101]
	v_mfma_f32_16x16x32_bf16 v[98:101], v[168:171], v[196:199], v[98:101]
	v_mfma_f32_16x16x32_bf16 v[86:89], v[156:159], v[200:203], v[86:89]
	v_mfma_f32_16x16x32_bf16 v[86:89], v[160:163], v[204:207], v[86:89]
	v_mfma_f32_16x16x32_bf16 v[82:85], v[164:167], v[200:203], v[82:85]
	v_mfma_f32_16x16x32_bf16 v[82:85], v[168:171], v[204:207], v[82:85]
	s_barrier
; #define PG8_STAGE(bufoff, gbase, voff) do { _Pragma("unroll") for (int _i = 0; _i < 2; ++_i) \
;         __builtin_amdgcn_global_load_lds((const unsigned*)((const char*)(gbase) + (voff)[_i]), (LAS unsigned*)(lds + (bufoff) + ldsw + _i * 8192), 16, 0, 0); } while (0)
; #define PG8_LDA(dst, b, h) do { _Pragma("unroll") for (int m = 0; m < 4; ++m) _Pragma("unroll") for (int k = 0; k < 2; ++k) dst[m][k] = *(const LAS bf16x8*)(lds + PG8_SA(b, h) + aoff + m * 2048 + k * 1024); } while (0)
; #define PG8_MMA(ai, bj, At, Bt) do { __builtin_amdgcn_s_setprio(1); _Pragma("unroll") for (int m = 0; m < 4; ++m) _Pragma("unroll") for (int n = 0; n < 2; ++n) _Pragma("unroll") for (int k = 0; k < 2; ++k) \
;         acc[ai][bj][m][n] = __builtin_amdgcn_mfma_f32_16x16x32_bf16(Bt[n][k], At[m][k], acc[ai][bj][m][n], 0, 0, 0); __builtin_amdgcn_s_setprio(0); } while (0)
; #define PG8_WAIT_V(n) asm volatile("s_waitcnt vmcnt(" #n ")" ::: "memory")
; #define PG8_WAIT_L(n) asm volatile("s_waitcnt lgkmcnt(" #n ")" ::: "memory")
; #define PG8_BAR __builtin_amdgcn_s_barrier()
; #define PG8_SCHED __builtin_amdgcn_sched_barrier(0)
; template <class Epi, class Sched, int LDA, int LDB, bool ALIGN_EPI = true>
; __device__ __forceinline__ void gemm_phase(LAS unsigned char* lds, const Gemm g, const Sched& S, const Epi& E, int wave) {
;     ...
;             PG8_LDA(At, 1, 1); PG8_STAGE(PG8_SB(1, 0), b3, voffB); PG8_STAGE(PG8_SB(1, 1), b3 + hstepB, voffB); PG8_STAGE(PG8_SA(1, 0), a3, voffA);
;             PG8_WAIT_V(8); PG8_WAIT_L(0); PG8_BAR; PG8_MMA(1, 0, At, B0); PG8_MMA(1, 1, At, B1); PG8_BAR; PG8_SCHED;
;         }
;         if constexpr (ALIGN_EPI) { if (wr == 0) PG8_BAR; }
	s_setprio 0
	s_add_i32 s38, s66, s60
	v_lshl_add_u64 v[208:209], v[208:209], 0, s[70:71]
	s_mov_b32 m0, s38
	ds_read_b128 v[172:175], v215 offset:49152
	ds_read_b128 v[180:183], v215 offset:50176
	ds_read_b128 v[184:187], v215 offset:51200
	ds_read_b128 v[188:191], v215 offset:52224
	ds_read_b128 v[192:195], v215 offset:53248
	ds_read_b128 v[196:199], v215 offset:54272
	ds_read_b128 v[200:203], v215 offset:55296
	ds_read_b128 v[204:207], v215 offset:56320
	global_load_lds_dwordx4 v[208:209], off
	s_add_i32 m0, s38, 0x2000
	s_add_u32 s36, s36, 0x80080
	v_lshl_add_u64 v[208:209], v[210:211], 0, s[70:71]
	s_addc_u32 s37, s37, 0
	s_add_i32 s38, s67, s60
	global_load_lds_dwordx4 v[208:209], off
	v_lshl_add_u64 v[208:209], s[36:37], 0, v[0:1]
	s_mov_b32 m0, s38
	s_nop 0
	global_load_lds_dwordx4 v[208:209], off
	v_lshl_add_u64 v[208:209], s[36:37], 0, v[150:151]
	s_add_i32 m0, s38, 0x2000
	s_nop 0
	global_load_lds_dwordx4 v[208:209], off
	v_lshl_add_u64 v[208:209], v[216:217], 0, s[70:71]
	s_mov_b32 m0, s51
	s_nop 0
	global_load_lds_dwordx4 v[208:209], off
	v_lshl_add_u64 v[208:209], v[218:219], 0, s[70:71]
	s_mov_b32 m0, s52
	s_nop 0
	global_load_lds_dwordx4 v[208:209], off
	s_waitcnt vmcnt(8)
	s_waitcnt lgkmcnt(0)
	s_setprio 1
	s_barrier
	v_mfma_f32_16x16x32_bf16 v[78:81], v[58:61], v[172:175], v[78:81]
	v_mfma_f32_16x16x32_bf16 v[74:77], v[66:69], v[172:175], v[74:77]
	v_mfma_f32_16x16x32_bf16 v[46:49], v[58:61], v[184:187], v[46:49]
	v_mfma_f32_16x16x32_bf16 v[42:45], v[66:69], v[184:187], v[42:45]
	v_mfma_f32_16x16x32_bf16 v[30:33], v[58:61], v[192:195], v[30:33]
	v_mfma_f32_16x16x32_bf16 v[26:29], v[66:69], v[192:195], v[26:29]
	v_mfma_f32_16x16x32_bf16 v[14:17], v[58:61], v[200:203], v[14:17]
	v_mfma_f32_16x16x32_bf16 v[10:13], v[66:69], v[200:203], v[10:13]
	v_mfma_f32_16x16x32_bf16 v[78:81], v[62:65], v[180:183], v[78:81]
	v_mfma_f32_16x16x32_bf16 v[74:77], v[70:73], v[180:183], v[74:77]
	v_mfma_f32_16x16x32_bf16 v[46:49], v[62:65], v[188:191], v[46:49]
	v_mfma_f32_16x16x32_bf16 v[42:45], v[70:73], v[188:191], v[42:45]
	v_mfma_f32_16x16x32_bf16 v[30:33], v[62:65], v[196:199], v[30:33]
	v_mfma_f32_16x16x32_bf16 v[26:29], v[70:73], v[196:199], v[26:29]
	v_mfma_f32_16x16x32_bf16 v[14:17], v[62:65], v[204:207], v[14:17]
	v_mfma_f32_16x16x32_bf16 v[10:13], v[70:73], v[204:207], v[10:13]
	v_mfma_f32_16x16x32_bf16 v[50:53], v[156:159], v[172:175], v[50:53]
	v_mfma_f32_16x16x32_bf16 v[62:65], v[160:163], v[180:183], v[50:53]
	v_mfma_f32_16x16x32_bf16 v[50:53], v[164:167], v[172:175], v[54:57]
	v_mfma_f32_16x16x32_bf16 v[38:41], v[156:159], v[184:187], v[38:41]
	v_mfma_f32_16x16x32_bf16 v[34:37], v[164:167], v[184:187], v[34:37]
	v_mfma_f32_16x16x32_bf16 v[22:25], v[156:159], v[192:195], v[22:25]
	v_mfma_f32_16x16x32_bf16 v[18:21], v[164:167], v[192:195], v[18:21]
	v_mfma_f32_16x16x32_bf16 v[6:9], v[156:159], v[200:203], v[6:9]
	v_mfma_f32_16x16x32_bf16 v[2:5], v[164:167], v[200:203], v[2:5]
	v_mfma_f32_16x16x32_bf16 v[58:61], v[168:171], v[180:183], v[50:53]
	v_mfma_f32_16x16x32_bf16 v[38:41], v[160:163], v[188:191], v[38:41]
	v_mfma_f32_16x16x32_bf16 v[34:37], v[168:171], v[188:191], v[34:37]
	v_mfma_f32_16x16x32_bf16 v[22:25], v[160:163], v[196:199], v[22:25]
	v_mfma_f32_16x16x32_bf16 v[18:21], v[168:171], v[196:199], v[18:21]
	v_mfma_f32_16x16x32_bf16 v[6:9], v[160:163], v[204:207], v[6:9]
	v_mfma_f32_16x16x32_bf16 v[2:5], v[168:171], v[204:207], v[2:5]
	s_barrier
	s_setprio 0
	s_add_u32 s34, s34, 0x100
	s_addc_u32 s35, s35, 0
	s_add_u32 s59, s59, 0x100
	s_addc_u32 s64, s64, 0
	s_cmp_ge_i32 s65, s43
	s_mov_b32 s36, s65
	s_cbranch_scc0 .LBB0_4901
	v_readlane_b32 s34, v252, 14
	v_readlane_b32 s35, v252, 15
	s_and_b64 vcc, exec, s[34:35]
	s_cbranch_vccz .LBB0_4904
	s_barrier
